# GEMM loops: merged vmcnt+lgkmcnt waits; G_up: fragment reads from one invariant LDS base register, LDS-DMA sequences reordered so address adds / loop bookkeeping fill the M0 wait state instead of s_no
# baseline (speedup 1.0000x reference)
; #define G_STAGE_A(bufoff, p0, p1, koff) do { \
;         __builtin_amdgcn_global_load_lds((const unsigned*)(gbase + (size_t)(unsigned)((p0) + (koff) + voffA[0])), (LAS unsigned*)(lds + (bufoff) + ldsw), 16, 0, 0); \
;         __builtin_amdgcn_global_load_lds((const unsigned*)(gbase + (size_t)(unsigned)((p1) + (koff) + voffA[1])), (LAS unsigned*)(lds + (bufoff) + ldsw + 8192), 16, 0, 0); } while (0)
; #define G_STAGE_B(bufoff, p, koff) do { \
;         __builtin_amdgcn_global_load_lds((const unsigned*)(gbase + (size_t)(unsigned)((p) + (koff) + voffB[0])), (LAS unsigned*)(lds + (bufoff) + ldsw), 16, 0, 0); \
;         __builtin_amdgcn_global_load_lds((const unsigned*)(gbase + (size_t)(unsigned)((p) + (koff) + voffB[1])), (LAS unsigned*)(lds + (bufoff) + ldsw + 8192), 16, 0, 0); } while (0)
; #define G_LDA(dst, b, h) do { _Pragma("unroll") for (int m = 0; m < 4; ++m) _Pragma("unroll") for (int k = 0; k < 2; ++k) dst[m][k] = *(const LAS bf16x8*)(lds + G_SA(b, h) + aoff + m * 2048 + k * 1024); } while (0)
; #define G_LDB(dst, b, h) do { _Pragma("unroll") for (int n = 0; n < 2; ++n) _Pragma("unroll") for (int k = 0; k < 2; ++k) dst[n][k] = *(const LAS bf16x8*)(lds + G_SB(b, h) + boff + n * 2048 + k * 1024); } while (0)
; #define G_BAR __builtin_amdgcn_s_barrier()
; template <class Epi>
; DI void gemm_phase(LAS unsigned char* lds, const Sched& S, const Epi& E, const int K) {
;     ...
;         for (int t = 0; t < nt; t += 2) {
;             const bool last = (t == nt - 2);
;             const unsigned k1 = (unsigned)(t + 1) * kstepA;
;             const unsigned k2 = last ? 0u : (unsigned)(t + 2) * kstepA, k3 = k2 + kstepA;
;             const unsigned kb2 = last ? 0u : (unsigned)(t + 2) * kstepB, kb3 = kb2 + kstepB;
;             const unsigned x0 = last ? n0 : cur.a0, x1 = last ? n1 : cur.a1, x2 = last ? n2 : cur.a2, x3 = last ? n3 : cur.a3;
;             const unsigned xb = last ? nB : cur.b;
;     ...
;             G_LDB(B0, 0, 0); G_LDB(B1, 0, 1); G_SCHED; G_LDA(At, 0, 0); G_STAGE_A(G_SA(1, 1), cur.a2, cur.a3, k1);
;             G_WAIT_V(8); G_WAIT_L(0); G_BAR; G_MMA(0, 0, At, B0); G_MMA(0, 1, At, B1); G_BAR; G_SCHED;
;             G_LDA(At, 0, 1); G_STAGE_B(G_SB(0, 0), xb, kb2); G_STAGE_B(G_SB(0, 1), xb + hstepB, kb2); G_STAGE_A(G_SA(0, 0), x0, x1, k2);
;             G_WAIT_V(8); G_WAIT_L(0); G_BAR; G_MMA(1, 0, At, B0); G_MMA(1, 1, At, B1); G_BAR; G_SCHED;
.LBB0_109:
	v_lshrrev_b32_e32 v183, 6, v187
	v_readlane_b32 s46, v255, 2
	v_readlane_b32 s47, v255, 3
	v_readfirstlane_b32 s0, v183
	v_readlane_b32 s62, v255, 4
	v_readlane_b32 s63, v255, 5
	v_readlane_b32 s40, v254, 52
	v_readlane_b32 s88, v255, 1
	v_and_b32_e32 v183, 31, v231
	v_lshlrev_b32_e32 v183, 4, v183
	s_nop 3
	s_cmp_eq_u32 s0, 1
	s_cselect_b64 s[46:47], s[80:81], s[46:47]
	s_cmp_eq_u32 s0, 2
	s_cselect_b64 s[46:47], s[70:71], s[46:47]
	s_cmp_eq_u32 s0, 3
	s_cselect_b64 s[46:47], s[62:63], s[46:47]
	s_cmp_eq_u32 s0, 4
	s_cselect_b64 s[46:47], s[24:25], s[46:47]
	s_cmp_eq_u32 s0, 5
	s_cselect_b64 s[46:47], s[72:73], s[46:47]
	s_cmp_eq_u32 s0, 6
	s_cselect_b64 s[46:47], s[66:67], s[46:47]
	s_cmp_eq_u32 s0, 7
	s_cselect_b64 s[46:47], s[68:69], s[46:47]
	s_lshl_b32 s40, s40, 9
	s_add_u32 s46, s46, s40
	s_addc_u32 s47, s47, 0
	s_and_b32 s88, s88, 1
	s_lshl_b32 s88, s88, 12
	s_lshl_b32 s91, s0, 9
	s_add_i32 s88, s88, s91
	s_add_i32 m0, s88, 0x20100
	s_mov_b32 exec_lo, -1
	s_mov_b32 exec_hi, 0
	global_load_lds_dwordx4 v183, s[46:47]
	s_mov_b64 exec, -1
	v_add_u32_e32 v128, s61, v212
	v_add_u32_e32 v129, s27, v213
	s_mov_b32 s90, 0
	s_mov_b32 s44, -2
	v_add_u32_e32 v252, 0x10000, v207
.LBB0_110:
	s_add_i32 s91, s90, 0x100
	s_cmp_eq_u32 s44, 28
	s_cselect_b32 s40, 0, s91
	s_cselect_b32 s46, s54, s41
	s_cselect_b32 s47, s56, s61
	s_cselect_b32 s88, s55, s27
	s_cselect_b32 s62, s45, s58
	s_cselect_b32 vcc_hi, s57, s60
	s_add_i32 s63, 0, 0x10000
	s_add_i32 s0, 0, 0x14000
	ds_read_b128 v[130:133], v252
	ds_read_b128 v[134:137], v252 offset:1024
	ds_read_b128 v[138:141], v252 offset:2048
	ds_read_b128 v[142:145], v252 offset:3072
	ds_read_b128 v[146:149], v252 offset:16384
	ds_read_b128 v[150:153], v252 offset:17408
	ds_read_b128 v[154:157], v252 offset:18432
	ds_read_b128 v[162:165], v252 offset:19456
	v_add_u32_e32 v158, s90, v129
	s_add_i32 m0, s78, 0xc000
	v_add_u32_e32 v183, s90, v128
	ds_read_b128 v[166:169], v214
	ds_read_b128 v[170:173], v214 offset:1024
	ds_read_b128 v[174:177], v214 offset:2048
	ds_read_b128 v[178:181], v214 offset:3072
	ds_read_b128 v[194:197], v214 offset:4096
	ds_read_b128 v[198:201], v214 offset:5120
	ds_read_b128 v[216:219], v214 offset:6144
	ds_read_b128 v[220:223], v214 offset:7168
	global_load_lds_dwordx4 v158, s[82:83]
	s_add_i32 m0, s78, 0xe000
	s_or_b32 vcc_lo, s40, 0x80
	global_load_lds_dwordx4 v183, s[82:83]
	s_waitcnt vmcnt(8) lgkmcnt(0)
	s_barrier
	s_setprio 1
	v_mfma_f32_16x16x32_bf16 v[124:127], v[130:133], v[166:169], v[124:127]
	v_mfma_f32_16x16x32_bf16 v[120:123], v[138:141], v[166:169], v[120:123]
	v_mfma_f32_16x16x32_bf16 v[116:119], v[130:133], v[174:177], v[116:119]
	v_mfma_f32_16x16x32_bf16 v[112:115], v[138:141], v[174:177], v[112:115]
	v_mfma_f32_16x16x32_bf16 v[108:111], v[130:133], v[194:197], v[108:111]
	v_mfma_f32_16x16x32_bf16 v[104:107], v[138:141], v[194:197], v[104:107]
	v_mfma_f32_16x16x32_bf16 v[100:103], v[130:133], v[216:219], v[100:103]
	v_mfma_f32_16x16x32_bf16 v[96:99], v[138:141], v[216:219], v[96:99]
	v_mfma_f32_16x16x32_bf16 v[124:127], v[134:137], v[170:173], v[124:127]
	v_mfma_f32_16x16x32_bf16 v[120:123], v[142:145], v[170:173], v[120:123]
	v_mfma_f32_16x16x32_bf16 v[116:119], v[134:137], v[178:181], v[116:119]
	v_mfma_f32_16x16x32_bf16 v[112:115], v[142:145], v[178:181], v[112:115]
	v_mfma_f32_16x16x32_bf16 v[108:111], v[134:137], v[198:201], v[108:111]
	v_mfma_f32_16x16x32_bf16 v[104:107], v[142:145], v[198:201], v[104:107]
	v_mfma_f32_16x16x32_bf16 v[100:103], v[134:137], v[220:223], v[100:103]
	v_mfma_f32_16x16x32_bf16 v[96:99], v[142:145], v[220:223], v[96:99]
	v_mfma_f32_16x16x32_bf16 v[92:95], v[146:149], v[166:169], v[92:95]
	v_mfma_f32_16x16x32_bf16 v[88:91], v[154:157], v[166:169], v[88:91]
	v_mfma_f32_16x16x32_bf16 v[84:87], v[146:149], v[174:177], v[84:87]
	v_mfma_f32_16x16x32_bf16 v[80:83], v[154:157], v[174:177], v[80:83]
	v_mfma_f32_16x16x32_bf16 v[76:79], v[146:149], v[194:197], v[76:79]
	v_mfma_f32_16x16x32_bf16 v[72:75], v[154:157], v[194:197], v[72:75]
	v_mfma_f32_16x16x32_bf16 v[68:71], v[146:149], v[216:219], v[68:71]
	v_mfma_f32_16x16x32_bf16 v[64:67], v[154:157], v[216:219], v[64:67]
	v_mfma_f32_16x16x32_bf16 v[92:95], v[150:153], v[170:173], v[92:95]
	v_mfma_f32_16x16x32_bf16 v[88:91], v[162:165], v[170:173], v[88:91]
	v_mfma_f32_16x16x32_bf16 v[84:87], v[150:153], v[178:181], v[84:87]
	v_mfma_f32_16x16x32_bf16 v[80:83], v[162:165], v[178:181], v[80:83]
	v_mfma_f32_16x16x32_bf16 v[76:79], v[150:153], v[198:201], v[76:79]
	v_mfma_f32_16x16x32_bf16 v[72:75], v[162:165], v[198:201], v[72:75]
	v_mfma_f32_16x16x32_bf16 v[68:71], v[150:153], v[220:223], v[68:71]
	v_mfma_f32_16x16x32_bf16 v[64:67], v[162:165], v[220:223], v[64:67]
	s_setprio 0
	s_barrier
	s_add_i32 s90, s40, vcc_hi
	s_add_i32 s63, s63, s50
	v_add_u32_e32 v158, s90, v204
	s_mov_b32 m0, s63
	ds_read_b128 v[166:169], v214 offset:16384
	ds_read_b128 v[170:173], v214 offset:17408
	ds_read_b128 v[174:177], v214 offset:18432
	ds_read_b128 v[178:181], v214 offset:19456
	ds_read_b128 v[194:197], v214 offset:20480
	ds_read_b128 v[198:201], v214 offset:21504
	ds_read_b128 v[216:219], v214 offset:22528
	ds_read_b128 v[220:223], v214 offset:23552
	global_load_lds_dwordx4 v158, s[82:83]
	s_add_i32 m0, s63, 0x2000
	s_add_i32 s63, vcc_hi, 0x80000
	v_add_u32_e32 v158, s90, v206
	s_add_i32 s90, s63, s40
	s_add_i32 s0, s0, s50
	v_add_u32_e32 v183, s90, v204
	global_load_lds_dwordx4 v158, s[82:83]
	s_mov_b32 m0, s0
	v_add_u32_e32 v158, s90, v206
	global_load_lds_dwordx4 v183, s[82:83]
	s_add_i32 m0, s0, 0x2000
	v_add_u32_e32 v159, s46, v205
	global_load_lds_dwordx4 v158, s[82:83]
	v_add_u32_e32 v158, s62, v161
	v_add_u32_e32 v182, s40, v158
	s_mov_b32 m0, s78
	v_add_u32_e32 v183, s40, v159
	global_load_lds_dwordx4 v182, s[82:83]
	s_mov_b32 m0, s79
	s_nop 0
	global_load_lds_dwordx4 v183, s[82:83]
	s_waitcnt vmcnt(8) lgkmcnt(0)
	s_barrier
; #define G_STAGE_A(bufoff, p0, p1, koff) do { \
;         __builtin_amdgcn_global_load_lds((const unsigned*)(gbase + (size_t)(unsigned)((p0) + (koff) + voffA[0])), (LAS unsigned*)(lds + (bufoff) + ldsw), 16, 0, 0); \
;         __builtin_amdgcn_global_load_lds((const unsigned*)(gbase + (size_t)(unsigned)((p1) + (koff) + voffA[1])), (LAS unsigned*)(lds + (bufoff) + ldsw + 8192), 16, 0, 0); } while (0)
; #define G_STAGE_B(bufoff, p, koff) do { \
;         __builtin_amdgcn_global_load_lds((const unsigned*)(gbase + (size_t)(unsigned)((p) + (koff) + voffB[0])), (LAS unsigned*)(lds + (bufoff) + ldsw), 16, 0, 0); \
;         __builtin_amdgcn_global_load_lds((const unsigned*)(gbase + (size_t)(unsigned)((p) + (koff) + voffB[1])), (LAS unsigned*)(lds + (bufoff) + ldsw + 8192), 16, 0, 0); } while (0)
; #define G_LDA(dst, b, h) do { _Pragma("unroll") for (int m = 0; m < 4; ++m) _Pragma("unroll") for (int k = 0; k < 2; ++k) dst[m][k] = *(const LAS bf16x8*)(lds + G_SA(b, h) + aoff + m * 2048 + k * 1024); } while (0)
; #define G_LDB(dst, b, h) do { _Pragma("unroll") for (int n = 0; n < 2; ++n) _Pragma("unroll") for (int k = 0; k < 2; ++k) dst[n][k] = *(const LAS bf16x8*)(lds + G_SB(b, h) + boff + n * 2048 + k * 1024); } while (0)
; #define G_MMA(ai, bj, At, Bt) do { __builtin_amdgcn_s_setprio(1); _Pragma("unroll") for (int m = 0; m < 4; ++m) _Pragma("unroll") for (int n = 0; n < 2; ++n) _Pragma("unroll") for (int k = 0; k < 2; ++k) \
;         acc[ai][bj][m][n] = __builtin_amdgcn_mfma_f32_16x16x32_bf16(Bt[n][k], At[m][k], acc[ai][bj][m][n], 0, 0, 0); __builtin_amdgcn_s_setprio(0); } while (0)
; template <class Epi>
; DI void gemm_phase(LAS unsigned char* lds, const Sched& S, const Epi& E, const int K) {
;     ...
;             G_LDB(B0, 0, 0); G_LDB(B1, 0, 1); G_SCHED; G_LDA(At, 0, 0); G_STAGE_A(G_SA(1, 1), cur.a2, cur.a3, k1);
;             G_WAIT_V(8); G_WAIT_L(0); G_BAR; G_MMA(0, 0, At, B0); G_MMA(0, 1, At, B1); G_BAR; G_SCHED;
;             G_LDA(At, 0, 1); G_STAGE_B(G_SB(0, 0), xb, kb2); G_STAGE_B(G_SB(0, 1), xb + hstepB, kb2); G_STAGE_A(G_SA(0, 0), x0, x1, k2);
;             G_WAIT_V(8); G_WAIT_L(0); G_BAR; G_MMA(1, 0, At, B0); G_MMA(1, 1, At, B1); G_BAR; G_SCHED;
;             G_LDB(B0, 1, 0); G_LDB(B1, 1, 1); G_SCHED; G_LDA(At, 1, 0); G_STAGE_A(G_SA(0, 1), x2, x3, k2);
;             G_WAIT_V(8); G_WAIT_L(0); G_BAR; G_MMA(0, 0, At, B0); G_MMA(0, 1, At, B1); G_BAR; G_SCHED;
	s_setprio 1
	v_mfma_f32_16x16x32_bf16 v[60:63], v[130:133], v[166:169], v[60:63]
	v_mfma_f32_16x16x32_bf16 v[56:59], v[138:141], v[166:169], v[56:59]
	v_mfma_f32_16x16x32_bf16 v[52:55], v[130:133], v[174:177], v[52:55]
	v_mfma_f32_16x16x32_bf16 v[48:51], v[138:141], v[174:177], v[48:51]
	v_mfma_f32_16x16x32_bf16 v[44:47], v[130:133], v[194:197], v[44:47]
	v_mfma_f32_16x16x32_bf16 v[40:43], v[138:141], v[194:197], v[40:43]
	v_mfma_f32_16x16x32_bf16 v[36:39], v[130:133], v[216:219], v[36:39]
	v_mfma_f32_16x16x32_bf16 v[32:35], v[138:141], v[216:219], v[32:35]
	v_mfma_f32_16x16x32_bf16 v[60:63], v[134:137], v[170:173], v[60:63]
	v_mfma_f32_16x16x32_bf16 v[56:59], v[142:145], v[170:173], v[56:59]
	v_mfma_f32_16x16x32_bf16 v[52:55], v[134:137], v[178:181], v[52:55]
	v_mfma_f32_16x16x32_bf16 v[48:51], v[142:145], v[178:181], v[48:51]
	v_mfma_f32_16x16x32_bf16 v[44:47], v[134:137], v[198:201], v[44:47]
	v_mfma_f32_16x16x32_bf16 v[40:43], v[142:145], v[198:201], v[40:43]
	v_mfma_f32_16x16x32_bf16 v[36:39], v[134:137], v[220:223], v[36:39]
	v_mfma_f32_16x16x32_bf16 v[32:35], v[142:145], v[220:223], v[32:35]
	v_mfma_f32_16x16x32_bf16 v[28:31], v[146:149], v[166:169], v[28:31]
	v_mfma_f32_16x16x32_bf16 v[24:27], v[154:157], v[166:169], v[24:27]
	v_mfma_f32_16x16x32_bf16 v[20:23], v[146:149], v[174:177], v[20:23]
	v_mfma_f32_16x16x32_bf16 v[16:19], v[154:157], v[174:177], v[16:19]
	v_mfma_f32_16x16x32_bf16 v[12:15], v[146:149], v[194:197], v[12:15]
	v_mfma_f32_16x16x32_bf16 v[8:11], v[154:157], v[194:197], v[8:11]
	v_mfma_f32_16x16x32_bf16 v[4:7], v[146:149], v[216:219], v[4:7]
	v_mfma_f32_16x16x32_bf16 v[0:3], v[154:157], v[216:219], v[0:3]
	v_mfma_f32_16x16x32_bf16 v[28:31], v[150:153], v[170:173], v[28:31]
	v_mfma_f32_16x16x32_bf16 v[24:27], v[162:165], v[170:173], v[24:27]
	v_mfma_f32_16x16x32_bf16 v[20:23], v[150:153], v[178:181], v[20:23]
	v_mfma_f32_16x16x32_bf16 v[16:19], v[162:165], v[178:181], v[16:19]
	v_mfma_f32_16x16x32_bf16 v[12:15], v[150:153], v[198:201], v[12:15]
	v_mfma_f32_16x16x32_bf16 v[8:11], v[162:165], v[198:201], v[8:11]
	v_mfma_f32_16x16x32_bf16 v[4:7], v[150:153], v[220:223], v[4:7]
	v_mfma_f32_16x16x32_bf16 v[0:3], v[162:165], v[220:223], v[0:3]
	s_setprio 0
	s_barrier
	s_add_i32 s0, 0, 0x18000
	ds_read_b128 v[130:133], v252 offset:32768
	ds_read_b128 v[134:137], v252 offset:33792
	ds_read_b128 v[138:141], v252 offset:34816
	ds_read_b128 v[142:145], v252 offset:35840
	ds_read_b128 v[146:149], v252 offset:49152
	ds_read_b128 v[150:153], v252 offset:50176
	ds_read_b128 v[154:157], v252 offset:51200
	ds_read_b128 v[162:165], v252 offset:52224
	s_add_i32 s88, s88, s40
	s_mov_b32 m0, s92
	v_add_u32_e32 v182, s88, v161
	s_add_i32 s47, s47, s40
	v_add_u32_e32 v183, s47, v205
	ds_read_b128 v[166:169], v214 offset:32768
	ds_read_b128 v[170:173], v214 offset:33792
	ds_read_b128 v[174:177], v214 offset:34816
	ds_read_b128 v[178:181], v214 offset:35840
	ds_read_b128 v[194:197], v214 offset:36864
	ds_read_b128 v[198:201], v214 offset:37888
	ds_read_b128 v[216:219], v214 offset:38912
	ds_read_b128 v[220:223], v214 offset:39936
	global_load_lds_dwordx4 v182, s[82:83]
	s_mov_b32 m0, s93
	s_add_i32 s46, 0, 0x1c000
	global_load_lds_dwordx4 v183, s[82:83]
	s_waitcnt vmcnt(8) lgkmcnt(0)
	s_barrier
	s_setprio 1
	v_mfma_f32_16x16x32_bf16 v[124:127], v[130:133], v[166:169], v[124:127]
	v_mfma_f32_16x16x32_bf16 v[120:123], v[138:141], v[166:169], v[120:123]
	v_mfma_f32_16x16x32_bf16 v[116:119], v[130:133], v[174:177], v[116:119]
	v_mfma_f32_16x16x32_bf16 v[112:115], v[138:141], v[174:177], v[112:115]
	v_mfma_f32_16x16x32_bf16 v[108:111], v[130:133], v[194:197], v[108:111]
	v_mfma_f32_16x16x32_bf16 v[104:107], v[138:141], v[194:197], v[104:107]
	v_mfma_f32_16x16x32_bf16 v[100:103], v[130:133], v[216:219], v[100:103]
	v_mfma_f32_16x16x32_bf16 v[96:99], v[138:141], v[216:219], v[96:99]
	v_mfma_f32_16x16x32_bf16 v[124:127], v[134:137], v[170:173], v[124:127]
	v_mfma_f32_16x16x32_bf16 v[120:123], v[142:145], v[170:173], v[120:123]
	v_mfma_f32_16x16x32_bf16 v[116:119], v[134:137], v[178:181], v[116:119]
	v_mfma_f32_16x16x32_bf16 v[112:115], v[142:145], v[178:181], v[112:115]
	v_mfma_f32_16x16x32_bf16 v[108:111], v[134:137], v[198:201], v[108:111]
	v_mfma_f32_16x16x32_bf16 v[104:107], v[142:145], v[198:201], v[104:107]
	v_mfma_f32_16x16x32_bf16 v[100:103], v[134:137], v[220:223], v[100:103]
	v_mfma_f32_16x16x32_bf16 v[96:99], v[142:145], v[220:223], v[96:99]
	v_mfma_f32_16x16x32_bf16 v[92:95], v[146:149], v[166:169], v[92:95]
	v_mfma_f32_16x16x32_bf16 v[88:91], v[154:157], v[166:169], v[88:91]
	v_mfma_f32_16x16x32_bf16 v[84:87], v[146:149], v[174:177], v[84:87]
	v_mfma_f32_16x16x32_bf16 v[80:83], v[154:157], v[174:177], v[80:83]
	v_mfma_f32_16x16x32_bf16 v[76:79], v[146:149], v[194:197], v[76:79]
	v_mfma_f32_16x16x32_bf16 v[72:75], v[154:157], v[194:197], v[72:75]
	v_mfma_f32_16x16x32_bf16 v[68:71], v[146:149], v[216:219], v[68:71]
	v_mfma_f32_16x16x32_bf16 v[64:67], v[154:157], v[216:219], v[64:67]
	v_mfma_f32_16x16x32_bf16 v[92:95], v[150:153], v[170:173], v[92:95]
	v_mfma_f32_16x16x32_bf16 v[88:91], v[162:165], v[170:173], v[88:91]
	v_mfma_f32_16x16x32_bf16 v[84:87], v[150:153], v[178:181], v[84:87]
	v_mfma_f32_16x16x32_bf16 v[80:83], v[162:165], v[178:181], v[80:83]
	v_mfma_f32_16x16x32_bf16 v[76:79], v[150:153], v[198:201], v[76:79]
	v_mfma_f32_16x16x32_bf16 v[72:75], v[162:165], v[198:201], v[72:75]
	v_mfma_f32_16x16x32_bf16 v[68:71], v[150:153], v[220:223], v[68:71]
	v_mfma_f32_16x16x32_bf16 v[64:67], v[162:165], v[220:223], v[64:67]
	s_setprio 0
	s_barrier
; #define G_STAGE_A(bufoff, p0, p1, koff) do { \
;         __builtin_amdgcn_global_load_lds((const unsigned*)(gbase + (size_t)(unsigned)((p0) + (koff) + voffA[0])), (LAS unsigned*)(lds + (bufoff) + ldsw), 16, 0, 0); \
;         __builtin_amdgcn_global_load_lds((const unsigned*)(gbase + (size_t)(unsigned)((p1) + (koff) + voffA[1])), (LAS unsigned*)(lds + (bufoff) + ldsw + 8192), 16, 0, 0); } while (0)
; #define G_STAGE_B(bufoff, p, koff) do { \
;         __builtin_amdgcn_global_load_lds((const unsigned*)(gbase + (size_t)(unsigned)((p) + (koff) + voffB[0])), (LAS unsigned*)(lds + (bufoff) + ldsw), 16, 0, 0); \
;         __builtin_amdgcn_global_load_lds((const unsigned*)(gbase + (size_t)(unsigned)((p) + (koff) + voffB[1])), (LAS unsigned*)(lds + (bufoff) + ldsw + 8192), 16, 0, 0); } while (0)
; #define G_LDA(dst, b, h) do { _Pragma("unroll") for (int m = 0; m < 4; ++m) _Pragma("unroll") for (int k = 0; k < 2; ++k) dst[m][k] = *(const LAS bf16x8*)(lds + G_SA(b, h) + aoff + m * 2048 + k * 1024); } while (0)
; #define G_LDB(dst, b, h) do { _Pragma("unroll") for (int n = 0; n < 2; ++n) _Pragma("unroll") for (int k = 0; k < 2; ++k) dst[n][k] = *(const LAS bf16x8*)(lds + G_SB(b, h) + boff + n * 2048 + k * 1024); } while (0)
; #define G_MMA(ai, bj, At, Bt) do { __builtin_amdgcn_s_setprio(1); _Pragma("unroll") for (int m = 0; m < 4; ++m) _Pragma("unroll") for (int n = 0; n < 2; ++n) _Pragma("unroll") for (int k = 0; k < 2; ++k) \
;         acc[ai][bj][m][n] = __builtin_amdgcn_mfma_f32_16x16x32_bf16(Bt[n][k], At[m][k], acc[ai][bj][m][n], 0, 0, 0); __builtin_amdgcn_s_setprio(0); } while (0)
; #define G_WAIT_V(n) asm volatile("s_waitcnt vmcnt(" #n ")" ::: "memory")
; #define G_WAIT_L(n) asm volatile("s_waitcnt lgkmcnt(" #n ")" ::: "memory")
; #define G_BAR __builtin_amdgcn_s_barrier()
; template <class Epi>
; DI void gemm_phase(LAS unsigned char* lds, const Sched& S, const Epi& E, const int K) {
;     ...
;             G_LDB(B0, 1, 0); G_LDB(B1, 1, 1); G_SCHED; G_LDA(At, 1, 0); G_STAGE_A(G_SA(0, 1), x2, x3, k2);
;             G_WAIT_V(8); G_WAIT_L(0); G_BAR; G_MMA(0, 0, At, B0); G_MMA(0, 1, At, B1); G_BAR; G_SCHED;
;             G_LDA(At, 1, 1); G_STAGE_B(G_SB(1, 0), xb, kb3); G_STAGE_B(G_SB(1, 1), xb + hstepB, kb3); G_STAGE_A(G_SA(1, 0), x0, x1, k3);
;             G_WAIT_V(8); G_WAIT_L(0); G_BAR; G_MMA(1, 0, At, B0); G_MMA(1, 1, At, B1); G_BAR; G_SCHED;
	s_add_i32 s40, vcc_lo, vcc_hi
	s_add_i32 s0, s0, s50
	v_add_u32_e32 v182, s40, v204
	s_mov_b32 m0, s0
	ds_read_b128 v[166:169], v214 offset:49152
	ds_read_b128 v[170:173], v214 offset:50176
	ds_read_b128 v[174:177], v214 offset:51200
	ds_read_b128 v[178:181], v214 offset:52224
	ds_read_b128 v[194:197], v214 offset:53248
	ds_read_b128 v[198:201], v214 offset:54272
	ds_read_b128 v[216:219], v214 offset:55296
	ds_read_b128 v[220:223], v214 offset:56320
	global_load_lds_dwordx4 v182, s[82:83]
	v_add_u32_e32 v182, s40, v206
	s_add_i32 m0, s0, 0x2000
	s_add_i32 s0, vcc_lo, s63
	s_add_i32 s40, s46, s50
	global_load_lds_dwordx4 v182, s[82:83]
	v_add_u32_e32 v182, s0, v204
	s_mov_b32 m0, s40
	v_add_u32_e32 v158, vcc_lo, v158
	global_load_lds_dwordx4 v182, s[82:83]
	v_add_u32_e32 v182, s0, v206
	s_add_i32 m0, s40, 0x2000
	v_add_u32_e32 v183, vcc_lo, v159
	global_load_lds_dwordx4 v182, s[82:83]
	s_mov_b32 m0, s39
	s_add_i32 s44, s44, 2
	global_load_lds_dwordx4 v158, s[82:83]
	s_mov_b32 m0, s38
	s_mov_b32 s90, s91
	global_load_lds_dwordx4 v183, s[82:83]
	s_waitcnt vmcnt(8) lgkmcnt(0)
	s_barrier
	s_setprio 1
	v_mfma_f32_16x16x32_bf16 v[60:63], v[130:133], v[166:169], v[60:63]
	v_mfma_f32_16x16x32_bf16 v[56:59], v[138:141], v[166:169], v[56:59]
	v_mfma_f32_16x16x32_bf16 v[52:55], v[130:133], v[174:177], v[52:55]
	v_mfma_f32_16x16x32_bf16 v[48:51], v[138:141], v[174:177], v[48:51]
	v_mfma_f32_16x16x32_bf16 v[44:47], v[130:133], v[194:197], v[44:47]
	v_mfma_f32_16x16x32_bf16 v[40:43], v[138:141], v[194:197], v[40:43]
	v_mfma_f32_16x16x32_bf16 v[36:39], v[130:133], v[216:219], v[36:39]
	v_mfma_f32_16x16x32_bf16 v[32:35], v[138:141], v[216:219], v[32:35]
	v_mfma_f32_16x16x32_bf16 v[60:63], v[134:137], v[170:173], v[60:63]
	v_mfma_f32_16x16x32_bf16 v[56:59], v[142:145], v[170:173], v[56:59]
	v_mfma_f32_16x16x32_bf16 v[52:55], v[134:137], v[178:181], v[52:55]
	v_mfma_f32_16x16x32_bf16 v[48:51], v[142:145], v[178:181], v[48:51]
	v_mfma_f32_16x16x32_bf16 v[44:47], v[134:137], v[198:201], v[44:47]
	v_mfma_f32_16x16x32_bf16 v[40:43], v[142:145], v[198:201], v[40:43]
	v_mfma_f32_16x16x32_bf16 v[36:39], v[134:137], v[220:223], v[36:39]
	v_mfma_f32_16x16x32_bf16 v[32:35], v[142:145], v[220:223], v[32:35]
	v_mfma_f32_16x16x32_bf16 v[28:31], v[146:149], v[166:169], v[28:31]
	v_mfma_f32_16x16x32_bf16 v[24:27], v[154:157], v[166:169], v[24:27]
	v_mfma_f32_16x16x32_bf16 v[20:23], v[146:149], v[174:177], v[20:23]
	v_mfma_f32_16x16x32_bf16 v[16:19], v[154:157], v[174:177], v[16:19]
	v_mfma_f32_16x16x32_bf16 v[12:15], v[146:149], v[194:197], v[12:15]
	v_mfma_f32_16x16x32_bf16 v[8:11], v[154:157], v[194:197], v[8:11]
	v_mfma_f32_16x16x32_bf16 v[4:7], v[146:149], v[216:219], v[4:7]
	v_mfma_f32_16x16x32_bf16 v[0:3], v[154:157], v[216:219], v[0:3]
	v_mfma_f32_16x16x32_bf16 v[28:31], v[150:153], v[170:173], v[28:31]
	v_mfma_f32_16x16x32_bf16 v[24:27], v[162:165], v[170:173], v[24:27]
	v_mfma_f32_16x16x32_bf16 v[20:23], v[150:153], v[178:181], v[20:23]
	v_mfma_f32_16x16x32_bf16 v[16:19], v[162:165], v[178:181], v[16:19]
	v_mfma_f32_16x16x32_bf16 v[12:15], v[150:153], v[198:201], v[12:15]
	v_mfma_f32_16x16x32_bf16 v[8:11], v[162:165], v[198:201], v[8:11]
	v_mfma_f32_16x16x32_bf16 v[4:7], v[150:153], v[220:223], v[4:7]
	v_mfma_f32_16x16x32_bf16 v[0:3], v[162:165], v[220:223], v[0:3]
	s_setprio 0
	s_barrier
	s_cmp_gt_u32 s44, 29
	s_cbranch_scc0 .LBB0_110
	v_readlane_b32 s44, v254, 63
	v_readlane_b32 s45, v255, 0
	s_and_b64 vcc, exec, s[44:45]
	s_cbranch_vccz .LBB0_113
	s_barrier

; #define G_STAGE_A(bufoff, p0, p1, koff) do { \
;         __builtin_amdgcn_global_load_lds((const unsigned*)(gbase + (size_t)(unsigned)((p0) + (koff) + voffA[0])), (LAS unsigned*)(lds + (bufoff) + ldsw), 16, 0, 0); \
;         __builtin_amdgcn_global_load_lds((const unsigned*)(gbase + (size_t)(unsigned)((p1) + (koff) + voffA[1])), (LAS unsigned*)(lds + (bufoff) + ldsw + 8192), 16, 0, 0); } while (0)
; #define G_STAGE_B(bufoff, p, koff) do { \
;         __builtin_amdgcn_global_load_lds((const unsigned*)(gbase + (size_t)(unsigned)((p) + (koff) + voffB[0])), (LAS unsigned*)(lds + (bufoff) + ldsw), 16, 0, 0); \
;         __builtin_amdgcn_global_load_lds((const unsigned*)(gbase + (size_t)(unsigned)((p) + (koff) + voffB[1])), (LAS unsigned*)(lds + (bufoff) + ldsw + 8192), 16, 0, 0); } while (0)
; template <class Epi>
; DI void gemm_phase(LAS unsigned char* lds, const Sched& S, const Epi& E, const int K) {
;     ...
;         for (int t = 0; t < nt; t += 2) {
;             const bool last = (t == nt - 2);
;             const unsigned k1 = (unsigned)(t + 1) * kstepA;
;             const unsigned k2 = last ? 0u : (unsigned)(t + 2) * kstepA, k3 = k2 + kstepA;
;             const unsigned kb2 = last ? 0u : (unsigned)(t + 2) * kstepB, kb3 = kb2 + kstepB;
;             const unsigned x0 = last ? n0 : cur.a0, x1 = last ? n1 : cur.a1, x2 = last ? n2 : cur.a2, x3 = last ? n3 : cur.a3;
;             const unsigned xb = last ? nB : cur.b;
;     ...
;             G_LDB(B0, 0, 0); G_LDB(B1, 0, 1); G_SCHED; G_LDA(At, 0, 0); G_STAGE_A(G_SA(1, 1), cur.a2, cur.a3, k1);
;             G_WAIT_V(8); G_WAIT_L(0); G_BAR; G_MMA(0, 0, At, B0); G_MMA(0, 1, At, B1); G_BAR; G_SCHED;
;             G_LDA(At, 0, 1); G_STAGE_B(G_SB(0, 0), xb, kb2); G_STAGE_B(G_SB(0, 1), xb + hstepB, kb2); G_STAGE_A(G_SA(0, 0), x0, x1, k2);
;             G_WAIT_V(8); G_WAIT_L(0); G_BAR; G_MMA(1, 0, At, B0); G_MMA(1, 1, At, B1); G_BAR; G_SCHED;
;             G_LDB(B0, 1, 0); G_LDB(B1, 1, 1); G_SCHED; G_LDA(At, 1, 0); G_STAGE_A(G_SA(0, 1), x2, x3, k2);
;             G_WAIT_V(8); G_WAIT_L(0); G_BAR; G_MMA(0, 0, At, B0); G_MMA(0, 1, At, B1); G_BAR; G_SCHED;
;             G_LDA(At, 1, 1); G_STAGE_B(G_SB(1, 0), xb, kb3); G_STAGE_B(G_SB(1, 1), xb + hstepB, kb3); G_STAGE_A(G_SA(1, 0), x0, x1, k3);
;             G_WAIT_V(8); G_WAIT_L(0); G_BAR; G_MMA(1, 0, At, B0); G_MMA(1, 1, At, B1); G_BAR; G_SCHED;
.LBB0_196:
	s_add_i32 s72, s71, 2
	s_add_i32 s73, s14, 0x100
	s_cmp_eq_u32 s47, s71
	s_cselect_b32 s40, 0, s73
	s_cselect_b32 s78, s67, s37
	s_cselect_b32 s79, s69, s35
	s_cselect_b32 s80, s68, s36
	s_cselect_b32 s81, s15, s27
	s_cselect_b32 s75, s70, s26
	s_add_i32 s86, 0, 0x10000
	s_add_i32 s87, 0, 0x14000
	v_add_u32_e32 v152, s86, v133
	v_add_u32_e32 v168, s87, v133
	ds_read_b128 v[140:143], v152
	ds_read_b128 v[144:147], v152 offset:1024
	ds_read_b128 v[148:151], v152 offset:2048
	ds_read_b128 v[152:155], v152 offset:3072
	ds_read_b128 v[156:159], v168
	ds_read_b128 v[160:163], v168 offset:1024
	ds_read_b128 v[164:167], v168 offset:2048
	ds_read_b128 v[168:171], v168 offset:3072
	s_or_b32 s71, s40, 0x80
	v_add_u32_e32 v184, s14, v139
	s_add_i32 m0, s25, 0xc000
	ds_read_b128 v[172:175], v137
	ds_read_b128 v[176:179], v137 offset:1024
	ds_read_b128 v[180:183], v137 offset:2048
	ds_read_b128 v[194:197], v137 offset:3072
	ds_read_b128 v[198:201], v137 offset:4096
	ds_read_b128 v[202:205], v137 offset:5120
	ds_read_b128 v[206:209], v137 offset:6144
	ds_read_b128 v[210:213], v137 offset:7168
	global_load_lds_dwordx4 v184, s[82:83]
	v_add_u32_e32 v184, s14, v138
	s_add_i32 m0, s25, 0xe000
	s_nop 0
	global_load_lds_dwordx4 v184, s[82:83]
	s_waitcnt vmcnt(8) lgkmcnt(0)
	s_barrier
	s_setprio 1
	v_mfma_f32_16x16x32_bf16 v[124:127], v[140:143], v[172:175], v[124:127]
	v_mfma_f32_16x16x32_bf16 v[120:123], v[148:151], v[172:175], v[120:123]
	v_mfma_f32_16x16x32_bf16 v[116:119], v[140:143], v[180:183], v[116:119]
	v_mfma_f32_16x16x32_bf16 v[112:115], v[148:151], v[180:183], v[112:115]
	v_mfma_f32_16x16x32_bf16 v[108:111], v[140:143], v[198:201], v[108:111]
	v_mfma_f32_16x16x32_bf16 v[104:107], v[148:151], v[198:201], v[104:107]
	v_mfma_f32_16x16x32_bf16 v[100:103], v[140:143], v[206:209], v[100:103]
	v_mfma_f32_16x16x32_bf16 v[96:99], v[148:151], v[206:209], v[96:99]
	v_mfma_f32_16x16x32_bf16 v[124:127], v[144:147], v[176:179], v[124:127]
	v_mfma_f32_16x16x32_bf16 v[120:123], v[152:155], v[176:179], v[120:123]
	v_mfma_f32_16x16x32_bf16 v[116:119], v[144:147], v[194:197], v[116:119]
	v_mfma_f32_16x16x32_bf16 v[112:115], v[152:155], v[194:197], v[112:115]
	v_mfma_f32_16x16x32_bf16 v[108:111], v[144:147], v[202:205], v[108:111]
	v_mfma_f32_16x16x32_bf16 v[104:107], v[152:155], v[202:205], v[104:107]
	v_mfma_f32_16x16x32_bf16 v[100:103], v[144:147], v[210:213], v[100:103]
	v_mfma_f32_16x16x32_bf16 v[96:99], v[152:155], v[210:213], v[96:99]
	v_mfma_f32_16x16x32_bf16 v[92:95], v[156:159], v[172:175], v[92:95]
	v_mfma_f32_16x16x32_bf16 v[88:91], v[164:167], v[172:175], v[88:91]
	v_mfma_f32_16x16x32_bf16 v[84:87], v[156:159], v[180:183], v[84:87]
	v_mfma_f32_16x16x32_bf16 v[80:83], v[164:167], v[180:183], v[80:83]
	v_mfma_f32_16x16x32_bf16 v[76:79], v[156:159], v[198:201], v[76:79]
	v_mfma_f32_16x16x32_bf16 v[72:75], v[164:167], v[198:201], v[72:75]
	v_mfma_f32_16x16x32_bf16 v[68:71], v[156:159], v[206:209], v[68:71]
	v_mfma_f32_16x16x32_bf16 v[64:67], v[164:167], v[206:209], v[64:67]
	v_mfma_f32_16x16x32_bf16 v[92:95], v[160:163], v[176:179], v[92:95]
	v_mfma_f32_16x16x32_bf16 v[88:91], v[168:171], v[176:179], v[88:91]
	v_mfma_f32_16x16x32_bf16 v[84:87], v[160:163], v[194:197], v[84:87]
	v_mfma_f32_16x16x32_bf16 v[80:83], v[168:171], v[194:197], v[80:83]
	v_mfma_f32_16x16x32_bf16 v[76:79], v[160:163], v[202:205], v[76:79]
	v_mfma_f32_16x16x32_bf16 v[72:75], v[168:171], v[202:205], v[72:75]
	v_mfma_f32_16x16x32_bf16 v[68:71], v[160:163], v[210:213], v[68:71]
	v_mfma_f32_16x16x32_bf16 v[64:67], v[168:171], v[210:213], v[64:67]
	s_setprio 0
	s_barrier
	s_add_i32 s14, s40, s75
	s_add_i32 s86, s86, s20
	v_add_u32_e32 v184, s14, v128
	s_mov_b32 m0, s86
	ds_read_b128 v[172:175], v137 offset:16384
	ds_read_b128 v[176:179], v137 offset:17408
	ds_read_b128 v[180:183], v137 offset:18432
	ds_read_b128 v[194:197], v137 offset:19456
	ds_read_b128 v[198:201], v137 offset:20480
	ds_read_b128 v[202:205], v137 offset:21504
	ds_read_b128 v[206:209], v137 offset:22528
	ds_read_b128 v[210:213], v137 offset:23552
	global_load_lds_dwordx4 v184, s[82:83]
	v_add_u32_e32 v184, s14, v130
	s_add_i32 s14, s75, s16
	s_add_i32 m0, s86, 0x2000
	s_add_i32 s86, s14, s40
	s_add_i32 s87, s87, s20
	global_load_lds_dwordx4 v184, s[82:83]
	v_add_u32_e32 v184, s86, v128
	s_mov_b32 m0, s87
	s_nop 0
	global_load_lds_dwordx4 v184, s[82:83]
	v_add_u32_e32 v184, s86, v130
	s_add_i32 m0, s87, 0x2000
	s_nop 0
	global_load_lds_dwordx4 v184, s[82:83]
	v_add_u32_e32 v184, s81, v132
	v_add_u32_e32 v214, s40, v184
	s_mov_b32 m0, s25
	s_nop 0
	global_load_lds_dwordx4 v214, s[82:83]
	v_add_u32_e32 v214, s78, v129
	v_add_u32_e32 v215, s40, v214
	s_mov_b32 m0, s38
	s_nop 0
	global_load_lds_dwordx4 v215, s[82:83]
	s_waitcnt vmcnt(8) lgkmcnt(0)
	s_barrier
; #define G_STAGE_A(bufoff, p0, p1, koff) do { \
;         __builtin_amdgcn_global_load_lds((const unsigned*)(gbase + (size_t)(unsigned)((p0) + (koff) + voffA[0])), (LAS unsigned*)(lds + (bufoff) + ldsw), 16, 0, 0); \
;         __builtin_amdgcn_global_load_lds((const unsigned*)(gbase + (size_t)(unsigned)((p1) + (koff) + voffA[1])), (LAS unsigned*)(lds + (bufoff) + ldsw + 8192), 16, 0, 0); } while (0)
; #define G_STAGE_B(bufoff, p, koff) do { \
;         __builtin_amdgcn_global_load_lds((const unsigned*)(gbase + (size_t)(unsigned)((p) + (koff) + voffB[0])), (LAS unsigned*)(lds + (bufoff) + ldsw), 16, 0, 0); \
;         __builtin_amdgcn_global_load_lds((const unsigned*)(gbase + (size_t)(unsigned)((p) + (koff) + voffB[1])), (LAS unsigned*)(lds + (bufoff) + ldsw + 8192), 16, 0, 0); } while (0)
; #define G_LDA(dst, b, h) do { _Pragma("unroll") for (int m = 0; m < 4; ++m) _Pragma("unroll") for (int k = 0; k < 2; ++k) dst[m][k] = *(const LAS bf16x8*)(lds + G_SA(b, h) + aoff + m * 2048 + k * 1024); } while (0)
; #define G_LDB(dst, b, h) do { _Pragma("unroll") for (int n = 0; n < 2; ++n) _Pragma("unroll") for (int k = 0; k < 2; ++k) dst[n][k] = *(const LAS bf16x8*)(lds + G_SB(b, h) + boff + n * 2048 + k * 1024); } while (0)
; #define G_MMA(ai, bj, At, Bt) do { __builtin_amdgcn_s_setprio(1); _Pragma("unroll") for (int m = 0; m < 4; ++m) _Pragma("unroll") for (int n = 0; n < 2; ++n) _Pragma("unroll") for (int k = 0; k < 2; ++k) \
;         acc[ai][bj][m][n] = __builtin_amdgcn_mfma_f32_16x16x32_bf16(Bt[n][k], At[m][k], acc[ai][bj][m][n], 0, 0, 0); __builtin_amdgcn_s_setprio(0); } while (0)
; template <class Epi>
; DI void gemm_phase(LAS unsigned char* lds, const Sched& S, const Epi& E, const int K) {
;     ...
;             G_LDB(B0, 0, 0); G_LDB(B1, 0, 1); G_SCHED; G_LDA(At, 0, 0); G_STAGE_A(G_SA(1, 1), cur.a2, cur.a3, k1);
;             G_WAIT_V(8); G_WAIT_L(0); G_BAR; G_MMA(0, 0, At, B0); G_MMA(0, 1, At, B1); G_BAR; G_SCHED;
;             G_LDA(At, 0, 1); G_STAGE_B(G_SB(0, 0), xb, kb2); G_STAGE_B(G_SB(0, 1), xb + hstepB, kb2); G_STAGE_A(G_SA(0, 0), x0, x1, k2);
;             G_WAIT_V(8); G_WAIT_L(0); G_BAR; G_MMA(1, 0, At, B0); G_MMA(1, 1, At, B1); G_BAR; G_SCHED;
;             G_LDB(B0, 1, 0); G_LDB(B1, 1, 1); G_SCHED; G_LDA(At, 1, 0); G_STAGE_A(G_SA(0, 1), x2, x3, k2);
;             G_WAIT_V(8); G_WAIT_L(0); G_BAR; G_MMA(0, 0, At, B0); G_MMA(0, 1, At, B1); G_BAR; G_SCHED;
	s_setprio 1
	v_mfma_f32_16x16x32_bf16 v[60:63], v[140:143], v[172:175], v[60:63]
	v_mfma_f32_16x16x32_bf16 v[56:59], v[148:151], v[172:175], v[56:59]
	v_mfma_f32_16x16x32_bf16 v[52:55], v[140:143], v[180:183], v[52:55]
	v_mfma_f32_16x16x32_bf16 v[48:51], v[148:151], v[180:183], v[48:51]
	v_mfma_f32_16x16x32_bf16 v[44:47], v[140:143], v[198:201], v[44:47]
	v_mfma_f32_16x16x32_bf16 v[40:43], v[148:151], v[198:201], v[40:43]
	v_mfma_f32_16x16x32_bf16 v[36:39], v[140:143], v[206:209], v[36:39]
	v_mfma_f32_16x16x32_bf16 v[32:35], v[148:151], v[206:209], v[32:35]
	v_mfma_f32_16x16x32_bf16 v[60:63], v[144:147], v[176:179], v[60:63]
	v_mfma_f32_16x16x32_bf16 v[56:59], v[152:155], v[176:179], v[56:59]
	v_mfma_f32_16x16x32_bf16 v[52:55], v[144:147], v[194:197], v[52:55]
	v_mfma_f32_16x16x32_bf16 v[48:51], v[152:155], v[194:197], v[48:51]
	v_mfma_f32_16x16x32_bf16 v[44:47], v[144:147], v[202:205], v[44:47]
	v_mfma_f32_16x16x32_bf16 v[40:43], v[152:155], v[202:205], v[40:43]
	v_mfma_f32_16x16x32_bf16 v[36:39], v[144:147], v[210:213], v[36:39]
	v_mfma_f32_16x16x32_bf16 v[32:35], v[152:155], v[210:213], v[32:35]
	v_mfma_f32_16x16x32_bf16 v[28:31], v[156:159], v[172:175], v[28:31]
	v_mfma_f32_16x16x32_bf16 v[24:27], v[164:167], v[172:175], v[24:27]
	v_mfma_f32_16x16x32_bf16 v[20:23], v[156:159], v[180:183], v[20:23]
	v_mfma_f32_16x16x32_bf16 v[16:19], v[164:167], v[180:183], v[16:19]
	v_mfma_f32_16x16x32_bf16 v[12:15], v[156:159], v[198:201], v[12:15]
	v_mfma_f32_16x16x32_bf16 v[8:11], v[164:167], v[198:201], v[8:11]
	v_mfma_f32_16x16x32_bf16 v[4:7], v[156:159], v[206:209], v[4:7]
	v_mfma_f32_16x16x32_bf16 v[0:3], v[164:167], v[206:209], v[0:3]
	v_mfma_f32_16x16x32_bf16 v[28:31], v[160:163], v[176:179], v[28:31]
	v_mfma_f32_16x16x32_bf16 v[24:27], v[168:171], v[176:179], v[24:27]
	v_mfma_f32_16x16x32_bf16 v[20:23], v[160:163], v[194:197], v[20:23]
	v_mfma_f32_16x16x32_bf16 v[16:19], v[168:171], v[194:197], v[16:19]
	v_mfma_f32_16x16x32_bf16 v[12:15], v[160:163], v[202:205], v[12:15]
	v_mfma_f32_16x16x32_bf16 v[8:11], v[168:171], v[202:205], v[8:11]
	v_mfma_f32_16x16x32_bf16 v[4:7], v[160:163], v[210:213], v[4:7]
	v_mfma_f32_16x16x32_bf16 v[0:3], v[168:171], v[210:213], v[0:3]
	s_setprio 0
	s_barrier
	s_add_i32 s78, 0, 0x18000
	s_add_i32 s81, 0, 0x1c000
	v_add_u32_e32 v152, s78, v133
	v_add_u32_e32 v168, s81, v133
	ds_read_b128 v[140:143], v152
	ds_read_b128 v[144:147], v152 offset:1024
	ds_read_b128 v[148:151], v152 offset:2048
	ds_read_b128 v[152:155], v152 offset:3072
	ds_read_b128 v[156:159], v168
	ds_read_b128 v[160:163], v168 offset:1024
	ds_read_b128 v[164:167], v168 offset:2048
	ds_read_b128 v[168:171], v168 offset:3072
	s_add_i32 s80, s80, s40
	s_mov_b32 m0, s39
	v_add_u32_e32 v215, s80, v132
	s_add_i32 s79, s79, s40
	ds_read_b128 v[172:175], v137 offset:32768
	ds_read_b128 v[176:179], v137 offset:33792
	ds_read_b128 v[180:183], v137 offset:34816
	ds_read_b128 v[194:197], v137 offset:35840
	ds_read_b128 v[198:201], v137 offset:36864
	ds_read_b128 v[202:205], v137 offset:37888
	ds_read_b128 v[206:209], v137 offset:38912
	ds_read_b128 v[210:213], v137 offset:39936
	global_load_lds_dwordx4 v215, s[82:83]
	v_add_u32_e32 v215, s79, v129
	s_mov_b32 m0, s41
	s_nop 0
	global_load_lds_dwordx4 v215, s[82:83]
	s_waitcnt vmcnt(8) lgkmcnt(0)
	s_barrier
	s_setprio 1
	v_mfma_f32_16x16x32_bf16 v[124:127], v[140:143], v[172:175], v[124:127]
	v_mfma_f32_16x16x32_bf16 v[120:123], v[148:151], v[172:175], v[120:123]
	v_mfma_f32_16x16x32_bf16 v[116:119], v[140:143], v[180:183], v[116:119]
	v_mfma_f32_16x16x32_bf16 v[112:115], v[148:151], v[180:183], v[112:115]
	v_mfma_f32_16x16x32_bf16 v[108:111], v[140:143], v[198:201], v[108:111]
	v_mfma_f32_16x16x32_bf16 v[104:107], v[148:151], v[198:201], v[104:107]
	v_mfma_f32_16x16x32_bf16 v[100:103], v[140:143], v[206:209], v[100:103]
	v_mfma_f32_16x16x32_bf16 v[96:99], v[148:151], v[206:209], v[96:99]
	v_mfma_f32_16x16x32_bf16 v[124:127], v[144:147], v[176:179], v[124:127]
	v_mfma_f32_16x16x32_bf16 v[120:123], v[152:155], v[176:179], v[120:123]
	v_mfma_f32_16x16x32_bf16 v[116:119], v[144:147], v[194:197], v[116:119]
	v_mfma_f32_16x16x32_bf16 v[112:115], v[152:155], v[194:197], v[112:115]
	v_mfma_f32_16x16x32_bf16 v[108:111], v[144:147], v[202:205], v[108:111]
	v_mfma_f32_16x16x32_bf16 v[104:107], v[152:155], v[202:205], v[104:107]
	v_mfma_f32_16x16x32_bf16 v[100:103], v[144:147], v[210:213], v[100:103]
	v_mfma_f32_16x16x32_bf16 v[96:99], v[152:155], v[210:213], v[96:99]
	v_mfma_f32_16x16x32_bf16 v[92:95], v[156:159], v[172:175], v[92:95]
	v_mfma_f32_16x16x32_bf16 v[88:91], v[164:167], v[172:175], v[88:91]
	v_mfma_f32_16x16x32_bf16 v[84:87], v[156:159], v[180:183], v[84:87]
	v_mfma_f32_16x16x32_bf16 v[80:83], v[164:167], v[180:183], v[80:83]
	v_mfma_f32_16x16x32_bf16 v[76:79], v[156:159], v[198:201], v[76:79]
	v_mfma_f32_16x16x32_bf16 v[72:75], v[164:167], v[198:201], v[72:75]
	v_mfma_f32_16x16x32_bf16 v[68:71], v[156:159], v[206:209], v[68:71]
	v_mfma_f32_16x16x32_bf16 v[64:67], v[164:167], v[206:209], v[64:67]
	v_mfma_f32_16x16x32_bf16 v[92:95], v[160:163], v[176:179], v[92:95]
	v_mfma_f32_16x16x32_bf16 v[88:91], v[168:171], v[176:179], v[88:91]
	v_mfma_f32_16x16x32_bf16 v[84:87], v[160:163], v[194:197], v[84:87]
	v_mfma_f32_16x16x32_bf16 v[80:83], v[168:171], v[194:197], v[80:83]
	v_mfma_f32_16x16x32_bf16 v[76:79], v[160:163], v[202:205], v[76:79]
	v_mfma_f32_16x16x32_bf16 v[72:75], v[168:171], v[202:205], v[72:75]
	v_mfma_f32_16x16x32_bf16 v[68:71], v[160:163], v[210:213], v[68:71]
	v_mfma_f32_16x16x32_bf16 v[64:67], v[168:171], v[210:213], v[64:67]
	s_setprio 0
	s_barrier
; #define G_STAGE_A(bufoff, p0, p1, koff) do { \
;         __builtin_amdgcn_global_load_lds((const unsigned*)(gbase + (size_t)(unsigned)((p0) + (koff) + voffA[0])), (LAS unsigned*)(lds + (bufoff) + ldsw), 16, 0, 0); \
;         __builtin_amdgcn_global_load_lds((const unsigned*)(gbase + (size_t)(unsigned)((p1) + (koff) + voffA[1])), (LAS unsigned*)(lds + (bufoff) + ldsw + 8192), 16, 0, 0); } while (0)
; #define G_STAGE_B(bufoff, p, koff) do { \
;         __builtin_amdgcn_global_load_lds((const unsigned*)(gbase + (size_t)(unsigned)((p) + (koff) + voffB[0])), (LAS unsigned*)(lds + (bufoff) + ldsw), 16, 0, 0); \
;         __builtin_amdgcn_global_load_lds((const unsigned*)(gbase + (size_t)(unsigned)((p) + (koff) + voffB[1])), (LAS unsigned*)(lds + (bufoff) + ldsw + 8192), 16, 0, 0); } while (0)
; #define G_LDA(dst, b, h) do { _Pragma("unroll") for (int m = 0; m < 4; ++m) _Pragma("unroll") for (int k = 0; k < 2; ++k) dst[m][k] = *(const LAS bf16x8*)(lds + G_SA(b, h) + aoff + m * 2048 + k * 1024); } while (0)
; #define G_LDB(dst, b, h) do { _Pragma("unroll") for (int n = 0; n < 2; ++n) _Pragma("unroll") for (int k = 0; k < 2; ++k) dst[n][k] = *(const LAS bf16x8*)(lds + G_SB(b, h) + boff + n * 2048 + k * 1024); } while (0)
; #define G_MMA(ai, bj, At, Bt) do { __builtin_amdgcn_s_setprio(1); _Pragma("unroll") for (int m = 0; m < 4; ++m) _Pragma("unroll") for (int n = 0; n < 2; ++n) _Pragma("unroll") for (int k = 0; k < 2; ++k) \
;         acc[ai][bj][m][n] = __builtin_amdgcn_mfma_f32_16x16x32_bf16(Bt[n][k], At[m][k], acc[ai][bj][m][n], 0, 0, 0); __builtin_amdgcn_s_setprio(0); } while (0)
; #define G_WAIT_V(n) asm volatile("s_waitcnt vmcnt(" #n ")" ::: "memory")
; #define G_WAIT_L(n) asm volatile("s_waitcnt lgkmcnt(" #n ")" ::: "memory")
; #define G_BAR __builtin_amdgcn_s_barrier()
; template <class Epi>
; DI void gemm_phase(LAS unsigned char* lds, const Sched& S, const Epi& E, const int K) {
;     ...
;             G_LDB(B0, 1, 0); G_LDB(B1, 1, 1); G_SCHED; G_LDA(At, 1, 0); G_STAGE_A(G_SA(0, 1), x2, x3, k2);
;             G_WAIT_V(8); G_WAIT_L(0); G_BAR; G_MMA(0, 0, At, B0); G_MMA(0, 1, At, B1); G_BAR; G_SCHED;
;             G_LDA(At, 1, 1); G_STAGE_B(G_SB(1, 0), xb, kb3); G_STAGE_B(G_SB(1, 1), xb + hstepB, kb3); G_STAGE_A(G_SA(1, 0), x0, x1, k3);
;             G_WAIT_V(8); G_WAIT_L(0); G_BAR; G_MMA(1, 0, At, B0); G_MMA(1, 1, At, B1); G_BAR; G_SCHED;
	s_add_i32 s40, s71, s75
	s_add_i32 s75, s78, s20
	v_add_u32_e32 v215, s40, v128
	s_mov_b32 m0, s75
	ds_read_b128 v[172:175], v137 offset:49152
	ds_read_b128 v[176:179], v137 offset:50176
	ds_read_b128 v[180:183], v137 offset:51200
	ds_read_b128 v[194:197], v137 offset:52224
	ds_read_b128 v[198:201], v137 offset:53248
	ds_read_b128 v[202:205], v137 offset:54272
	ds_read_b128 v[206:209], v137 offset:55296
	ds_read_b128 v[210:213], v137 offset:56320
	global_load_lds_dwordx4 v215, s[82:83]
	v_add_u32_e32 v215, s40, v130
	s_add_i32 m0, s75, 0x2000
	s_add_i32 s14, s71, s14
	s_add_i32 s40, s81, s20
	global_load_lds_dwordx4 v215, s[82:83]
	v_add_u32_e32 v215, s14, v128
	s_mov_b32 m0, s40
	v_add_u32_e32 v184, s71, v184
	global_load_lds_dwordx4 v215, s[82:83]
	v_add_u32_e32 v215, s14, v130
	s_add_i32 m0, s40, 0x2000
	s_nop 0
	global_load_lds_dwordx4 v215, s[82:83]
	s_mov_b32 m0, s45
	s_nop 0
	global_load_lds_dwordx4 v184, s[82:83]
	v_add_u32_e32 v184, s71, v214
	s_mov_b32 m0, s46
	s_nop 0
	global_load_lds_dwordx4 v184, s[82:83]
	s_waitcnt vmcnt(8) lgkmcnt(0)
	s_barrier
	s_setprio 1
	v_mfma_f32_16x16x32_bf16 v[60:63], v[140:143], v[172:175], v[60:63]
	v_mfma_f32_16x16x32_bf16 v[56:59], v[148:151], v[172:175], v[56:59]
	v_mfma_f32_16x16x32_bf16 v[52:55], v[140:143], v[180:183], v[52:55]
	v_mfma_f32_16x16x32_bf16 v[48:51], v[148:151], v[180:183], v[48:51]
	v_mfma_f32_16x16x32_bf16 v[44:47], v[140:143], v[198:201], v[44:47]
	v_mfma_f32_16x16x32_bf16 v[40:43], v[148:151], v[198:201], v[40:43]
	v_mfma_f32_16x16x32_bf16 v[36:39], v[140:143], v[206:209], v[36:39]
	v_mfma_f32_16x16x32_bf16 v[32:35], v[148:151], v[206:209], v[32:35]
	v_mfma_f32_16x16x32_bf16 v[60:63], v[144:147], v[176:179], v[60:63]
	v_mfma_f32_16x16x32_bf16 v[56:59], v[152:155], v[176:179], v[56:59]
	v_mfma_f32_16x16x32_bf16 v[52:55], v[144:147], v[194:197], v[52:55]
	v_mfma_f32_16x16x32_bf16 v[48:51], v[152:155], v[194:197], v[48:51]
	v_mfma_f32_16x16x32_bf16 v[44:47], v[144:147], v[202:205], v[44:47]
	v_mfma_f32_16x16x32_bf16 v[40:43], v[152:155], v[202:205], v[40:43]
	v_mfma_f32_16x16x32_bf16 v[36:39], v[144:147], v[210:213], v[36:39]
	v_mfma_f32_16x16x32_bf16 v[32:35], v[152:155], v[210:213], v[32:35]
	v_mfma_f32_16x16x32_bf16 v[28:31], v[156:159], v[172:175], v[28:31]
	v_mfma_f32_16x16x32_bf16 v[24:27], v[164:167], v[172:175], v[24:27]
	v_mfma_f32_16x16x32_bf16 v[20:23], v[156:159], v[180:183], v[20:23]
	v_mfma_f32_16x16x32_bf16 v[16:19], v[164:167], v[180:183], v[16:19]
	v_mfma_f32_16x16x32_bf16 v[12:15], v[156:159], v[198:201], v[12:15]
	v_mfma_f32_16x16x32_bf16 v[8:11], v[164:167], v[198:201], v[8:11]
	v_mfma_f32_16x16x32_bf16 v[4:7], v[156:159], v[206:209], v[4:7]
	v_mfma_f32_16x16x32_bf16 v[0:3], v[164:167], v[206:209], v[0:3]
	v_mfma_f32_16x16x32_bf16 v[28:31], v[160:163], v[176:179], v[28:31]
	v_mfma_f32_16x16x32_bf16 v[24:27], v[168:171], v[176:179], v[24:27]
	v_mfma_f32_16x16x32_bf16 v[20:23], v[160:163], v[194:197], v[20:23]
	v_mfma_f32_16x16x32_bf16 v[16:19], v[168:171], v[194:197], v[16:19]
	v_mfma_f32_16x16x32_bf16 v[12:15], v[160:163], v[202:205], v[12:15]
	v_mfma_f32_16x16x32_bf16 v[8:11], v[168:171], v[202:205], v[8:11]
	v_mfma_f32_16x16x32_bf16 v[4:7], v[160:163], v[210:213], v[4:7]
	v_mfma_f32_16x16x32_bf16 v[0:3], v[168:171], v[210:213], v[0:3]
	s_setprio 0
	s_barrier
	s_cmp_ge_u32 s72, s44
	s_mov_b32 s14, s73
	s_mov_b32 s71, s72
	s_cbranch_scc0 .LBB0_196
	s_and_b64 vcc, exec, s[12:13]
	s_mov_b32 s71, 0xf800000
	s_cbranch_vccz .LBB0_199
	s_barrier

; #define G_STAGE_A(bufoff, p0, p1, koff) do { \
;         __builtin_amdgcn_global_load_lds((const unsigned*)(gbase + (size_t)(unsigned)((p0) + (koff) + voffA[0])), (LAS unsigned*)(lds + (bufoff) + ldsw), 16, 0, 0); \
;         __builtin_amdgcn_global_load_lds((const unsigned*)(gbase + (size_t)(unsigned)((p1) + (koff) + voffA[1])), (LAS unsigned*)(lds + (bufoff) + ldsw + 8192), 16, 0, 0); } while (0)
; #define G_STAGE_B(bufoff, p, koff) do { \
;         __builtin_amdgcn_global_load_lds((const unsigned*)(gbase + (size_t)(unsigned)((p) + (koff) + voffB[0])), (LAS unsigned*)(lds + (bufoff) + ldsw), 16, 0, 0); \
;         __builtin_amdgcn_global_load_lds((const unsigned*)(gbase + (size_t)(unsigned)((p) + (koff) + voffB[1])), (LAS unsigned*)(lds + (bufoff) + ldsw + 8192), 16, 0, 0); } while (0)
; template <class Epi>
; DI void gemm_phase(LAS unsigned char* lds, const Sched& S, const Epi& E, const int K) {
;     ...
;         for (int t = 0; t < nt; t += 2) {
;             const bool last = (t == nt - 2);
;             const unsigned k1 = (unsigned)(t + 1) * kstepA;
;             const unsigned k2 = last ? 0u : (unsigned)(t + 2) * kstepA, k3 = k2 + kstepA;
;             const unsigned kb2 = last ? 0u : (unsigned)(t + 2) * kstepB, kb3 = kb2 + kstepB;
;             const unsigned x0 = last ? n0 : cur.a0, x1 = last ? n1 : cur.a1, x2 = last ? n2 : cur.a2, x3 = last ? n3 : cur.a3;
;             const unsigned xb = last ? nB : cur.b;
;     ...
;             G_LDB(B0, 0, 0); G_LDB(B1, 0, 1); G_SCHED; G_LDA(At, 0, 0); G_STAGE_A(G_SA(1, 1), cur.a2, cur.a3, k1);
;             G_WAIT_V(8); G_WAIT_L(0); G_BAR; G_MMA(0, 0, At, B0); G_MMA(0, 1, At, B1); G_BAR; G_SCHED;
;             G_LDA(At, 0, 1); G_STAGE_B(G_SB(0, 0), xb, kb2); G_STAGE_B(G_SB(0, 1), xb + hstepB, kb2); G_STAGE_A(G_SA(0, 0), x0, x1, k2);
;             G_WAIT_V(8); G_WAIT_L(0); G_BAR; G_MMA(1, 0, At, B0); G_MMA(1, 1, At, B1); G_BAR; G_SCHED;
;             G_LDB(B0, 1, 0); G_LDB(B1, 1, 1); G_SCHED; G_LDA(At, 1, 0); G_STAGE_A(G_SA(0, 1), x2, x3, k2);
;             G_WAIT_V(8); G_WAIT_L(0); G_BAR; G_MMA(0, 0, At, B0); G_MMA(0, 1, At, B1); G_BAR; G_SCHED;
;             G_LDA(At, 1, 1); G_STAGE_B(G_SB(1, 0), xb, kb3); G_STAGE_B(G_SB(1, 1), xb + hstepB, kb3); G_STAGE_A(G_SA(1, 0), x0, x1, k3);
;             G_WAIT_V(8); G_WAIT_L(0); G_BAR; G_MMA(1, 0, At, B0); G_MMA(1, 1, At, B1); G_BAR; G_SCHED;
.LBB0_217:
	s_add_i32 s71, s70, 2
	s_add_i32 s72, s14, 0x100
	s_cmp_eq_u32 s46, s70
	s_cselect_b32 s40, 0, s72
	s_cselect_b32 s75, s15, s38
	s_cselect_b32 s78, s68, s36
	s_cselect_b32 s79, s67, s37
	s_cselect_b32 s80, s13, s35
	s_cselect_b32 s73, s69, s27
	s_add_i32 s81, 0, 0x10000
	s_add_i32 s86, 0, 0x14000
	v_add_u32_e32 v152, s81, v133
	v_add_u32_e32 v168, s86, v133
	ds_read_b128 v[140:143], v152
	ds_read_b128 v[144:147], v152 offset:1024
	ds_read_b128 v[148:151], v152 offset:2048
	ds_read_b128 v[152:155], v152 offset:3072
	ds_read_b128 v[156:159], v168
	ds_read_b128 v[160:163], v168 offset:1024
	ds_read_b128 v[164:167], v168 offset:2048
	ds_read_b128 v[168:171], v168 offset:3072
	s_or_b32 s70, s40, 0x80
	v_add_u32_e32 v184, s14, v139
	s_add_i32 m0, s26, 0xc000
	ds_read_b128 v[172:175], v137
	ds_read_b128 v[176:179], v137 offset:1024
	ds_read_b128 v[180:183], v137 offset:2048
	ds_read_b128 v[194:197], v137 offset:3072
	ds_read_b128 v[198:201], v137 offset:4096
	ds_read_b128 v[202:205], v137 offset:5120
	ds_read_b128 v[206:209], v137 offset:6144
	ds_read_b128 v[210:213], v137 offset:7168
	global_load_lds_dwordx4 v184, s[82:83]
	v_add_u32_e32 v184, s14, v138
	s_add_i32 m0, s26, 0xe000
	s_nop 0
	global_load_lds_dwordx4 v184, s[82:83]
	s_waitcnt vmcnt(8) lgkmcnt(0)
	s_barrier
	s_setprio 1
	v_mfma_f32_16x16x32_bf16 v[124:127], v[140:143], v[172:175], v[124:127]
	v_mfma_f32_16x16x32_bf16 v[120:123], v[148:151], v[172:175], v[120:123]
	v_mfma_f32_16x16x32_bf16 v[116:119], v[140:143], v[180:183], v[116:119]
	v_mfma_f32_16x16x32_bf16 v[112:115], v[148:151], v[180:183], v[112:115]
	v_mfma_f32_16x16x32_bf16 v[108:111], v[140:143], v[198:201], v[108:111]
	v_mfma_f32_16x16x32_bf16 v[104:107], v[148:151], v[198:201], v[104:107]
	v_mfma_f32_16x16x32_bf16 v[100:103], v[140:143], v[206:209], v[100:103]
	v_mfma_f32_16x16x32_bf16 v[96:99], v[148:151], v[206:209], v[96:99]
	v_mfma_f32_16x16x32_bf16 v[124:127], v[144:147], v[176:179], v[124:127]
	v_mfma_f32_16x16x32_bf16 v[120:123], v[152:155], v[176:179], v[120:123]
	v_mfma_f32_16x16x32_bf16 v[116:119], v[144:147], v[194:197], v[116:119]
	v_mfma_f32_16x16x32_bf16 v[112:115], v[152:155], v[194:197], v[112:115]
	v_mfma_f32_16x16x32_bf16 v[108:111], v[144:147], v[202:205], v[108:111]
	v_mfma_f32_16x16x32_bf16 v[104:107], v[152:155], v[202:205], v[104:107]
	v_mfma_f32_16x16x32_bf16 v[100:103], v[144:147], v[210:213], v[100:103]
	v_mfma_f32_16x16x32_bf16 v[96:99], v[152:155], v[210:213], v[96:99]
	v_mfma_f32_16x16x32_bf16 v[92:95], v[156:159], v[172:175], v[92:95]
	v_mfma_f32_16x16x32_bf16 v[88:91], v[164:167], v[172:175], v[88:91]
	v_mfma_f32_16x16x32_bf16 v[84:87], v[156:159], v[180:183], v[84:87]
	v_mfma_f32_16x16x32_bf16 v[80:83], v[164:167], v[180:183], v[80:83]
	v_mfma_f32_16x16x32_bf16 v[76:79], v[156:159], v[198:201], v[76:79]
	v_mfma_f32_16x16x32_bf16 v[72:75], v[164:167], v[198:201], v[72:75]
	v_mfma_f32_16x16x32_bf16 v[68:71], v[156:159], v[206:209], v[68:71]
	v_mfma_f32_16x16x32_bf16 v[64:67], v[164:167], v[206:209], v[64:67]
	v_mfma_f32_16x16x32_bf16 v[92:95], v[160:163], v[176:179], v[92:95]
	v_mfma_f32_16x16x32_bf16 v[88:91], v[168:171], v[176:179], v[88:91]
	v_mfma_f32_16x16x32_bf16 v[84:87], v[160:163], v[194:197], v[84:87]
	v_mfma_f32_16x16x32_bf16 v[80:83], v[168:171], v[194:197], v[80:83]
	v_mfma_f32_16x16x32_bf16 v[76:79], v[160:163], v[202:205], v[76:79]
	v_mfma_f32_16x16x32_bf16 v[72:75], v[168:171], v[202:205], v[72:75]
	v_mfma_f32_16x16x32_bf16 v[68:71], v[160:163], v[210:213], v[68:71]
	v_mfma_f32_16x16x32_bf16 v[64:67], v[168:171], v[210:213], v[64:67]
	s_setprio 0
	s_barrier
	s_add_i32 s14, s40, s73
	s_add_i32 s81, s81, s21
	v_add_u32_e32 v184, s14, v128
	s_mov_b32 m0, s81
	ds_read_b128 v[172:175], v137 offset:16384
	ds_read_b128 v[176:179], v137 offset:17408
	ds_read_b128 v[180:183], v137 offset:18432
	ds_read_b128 v[194:197], v137 offset:19456
	ds_read_b128 v[198:201], v137 offset:20480
	ds_read_b128 v[202:205], v137 offset:21504
	ds_read_b128 v[206:209], v137 offset:22528
	ds_read_b128 v[210:213], v137 offset:23552
	global_load_lds_dwordx4 v184, s[82:83]
	v_add_u32_e32 v184, s14, v130
	s_add_i32 s14, s73, s16
	s_add_i32 m0, s81, 0x2000
	s_add_i32 s81, s14, s40
	s_add_i32 s86, s86, s21
	global_load_lds_dwordx4 v184, s[82:83]
	v_add_u32_e32 v184, s81, v128
	s_mov_b32 m0, s86
	s_nop 0
	global_load_lds_dwordx4 v184, s[82:83]
	v_add_u32_e32 v184, s81, v130
	s_add_i32 m0, s86, 0x2000
	s_nop 0
	global_load_lds_dwordx4 v184, s[82:83]
	v_add_u32_e32 v184, s80, v132
	v_add_u32_e32 v214, s40, v184
	s_mov_b32 m0, s26
	s_nop 0
	global_load_lds_dwordx4 v214, s[82:83]
	v_add_u32_e32 v214, s75, v129
	v_add_u32_e32 v215, s40, v214
	s_mov_b32 m0, s39
	s_nop 0
	global_load_lds_dwordx4 v215, s[82:83]
	s_waitcnt vmcnt(8) lgkmcnt(0)
	s_barrier
; #define G_STAGE_A(bufoff, p0, p1, koff) do { \
;         __builtin_amdgcn_global_load_lds((const unsigned*)(gbase + (size_t)(unsigned)((p0) + (koff) + voffA[0])), (LAS unsigned*)(lds + (bufoff) + ldsw), 16, 0, 0); \
;         __builtin_amdgcn_global_load_lds((const unsigned*)(gbase + (size_t)(unsigned)((p1) + (koff) + voffA[1])), (LAS unsigned*)(lds + (bufoff) + ldsw + 8192), 16, 0, 0); } while (0)
; #define G_STAGE_B(bufoff, p, koff) do { \
;         __builtin_amdgcn_global_load_lds((const unsigned*)(gbase + (size_t)(unsigned)((p) + (koff) + voffB[0])), (LAS unsigned*)(lds + (bufoff) + ldsw), 16, 0, 0); \
;         __builtin_amdgcn_global_load_lds((const unsigned*)(gbase + (size_t)(unsigned)((p) + (koff) + voffB[1])), (LAS unsigned*)(lds + (bufoff) + ldsw + 8192), 16, 0, 0); } while (0)
; #define G_LDA(dst, b, h) do { _Pragma("unroll") for (int m = 0; m < 4; ++m) _Pragma("unroll") for (int k = 0; k < 2; ++k) dst[m][k] = *(const LAS bf16x8*)(lds + G_SA(b, h) + aoff + m * 2048 + k * 1024); } while (0)
; #define G_LDB(dst, b, h) do { _Pragma("unroll") for (int n = 0; n < 2; ++n) _Pragma("unroll") for (int k = 0; k < 2; ++k) dst[n][k] = *(const LAS bf16x8*)(lds + G_SB(b, h) + boff + n * 2048 + k * 1024); } while (0)
; #define G_MMA(ai, bj, At, Bt) do { __builtin_amdgcn_s_setprio(1); _Pragma("unroll") for (int m = 0; m < 4; ++m) _Pragma("unroll") for (int n = 0; n < 2; ++n) _Pragma("unroll") for (int k = 0; k < 2; ++k) \
;         acc[ai][bj][m][n] = __builtin_amdgcn_mfma_f32_16x16x32_bf16(Bt[n][k], At[m][k], acc[ai][bj][m][n], 0, 0, 0); __builtin_amdgcn_s_setprio(0); } while (0)
; template <class Epi>
; DI void gemm_phase(LAS unsigned char* lds, const Sched& S, const Epi& E, const int K) {
;     ...
;             G_LDB(B0, 0, 0); G_LDB(B1, 0, 1); G_SCHED; G_LDA(At, 0, 0); G_STAGE_A(G_SA(1, 1), cur.a2, cur.a3, k1);
;             G_WAIT_V(8); G_WAIT_L(0); G_BAR; G_MMA(0, 0, At, B0); G_MMA(0, 1, At, B1); G_BAR; G_SCHED;
;             G_LDA(At, 0, 1); G_STAGE_B(G_SB(0, 0), xb, kb2); G_STAGE_B(G_SB(0, 1), xb + hstepB, kb2); G_STAGE_A(G_SA(0, 0), x0, x1, k2);
;             G_WAIT_V(8); G_WAIT_L(0); G_BAR; G_MMA(1, 0, At, B0); G_MMA(1, 1, At, B1); G_BAR; G_SCHED;
;             G_LDB(B0, 1, 0); G_LDB(B1, 1, 1); G_SCHED; G_LDA(At, 1, 0); G_STAGE_A(G_SA(0, 1), x2, x3, k2);
;             G_WAIT_V(8); G_WAIT_L(0); G_BAR; G_MMA(0, 0, At, B0); G_MMA(0, 1, At, B1); G_BAR; G_SCHED;
	s_setprio 1
	v_mfma_f32_16x16x32_bf16 v[60:63], v[140:143], v[172:175], v[60:63]
	v_mfma_f32_16x16x32_bf16 v[56:59], v[148:151], v[172:175], v[56:59]
	v_mfma_f32_16x16x32_bf16 v[52:55], v[140:143], v[180:183], v[52:55]
	v_mfma_f32_16x16x32_bf16 v[48:51], v[148:151], v[180:183], v[48:51]
	v_mfma_f32_16x16x32_bf16 v[44:47], v[140:143], v[198:201], v[44:47]
	v_mfma_f32_16x16x32_bf16 v[40:43], v[148:151], v[198:201], v[40:43]
	v_mfma_f32_16x16x32_bf16 v[36:39], v[140:143], v[206:209], v[36:39]
	v_mfma_f32_16x16x32_bf16 v[32:35], v[148:151], v[206:209], v[32:35]
	v_mfma_f32_16x16x32_bf16 v[60:63], v[144:147], v[176:179], v[60:63]
	v_mfma_f32_16x16x32_bf16 v[56:59], v[152:155], v[176:179], v[56:59]
	v_mfma_f32_16x16x32_bf16 v[52:55], v[144:147], v[194:197], v[52:55]
	v_mfma_f32_16x16x32_bf16 v[48:51], v[152:155], v[194:197], v[48:51]
	v_mfma_f32_16x16x32_bf16 v[44:47], v[144:147], v[202:205], v[44:47]
	v_mfma_f32_16x16x32_bf16 v[40:43], v[152:155], v[202:205], v[40:43]
	v_mfma_f32_16x16x32_bf16 v[36:39], v[144:147], v[210:213], v[36:39]
	v_mfma_f32_16x16x32_bf16 v[32:35], v[152:155], v[210:213], v[32:35]
	v_mfma_f32_16x16x32_bf16 v[28:31], v[156:159], v[172:175], v[28:31]
	v_mfma_f32_16x16x32_bf16 v[24:27], v[164:167], v[172:175], v[24:27]
	v_mfma_f32_16x16x32_bf16 v[20:23], v[156:159], v[180:183], v[20:23]
	v_mfma_f32_16x16x32_bf16 v[16:19], v[164:167], v[180:183], v[16:19]
	v_mfma_f32_16x16x32_bf16 v[12:15], v[156:159], v[198:201], v[12:15]
	v_mfma_f32_16x16x32_bf16 v[8:11], v[164:167], v[198:201], v[8:11]
	v_mfma_f32_16x16x32_bf16 v[4:7], v[156:159], v[206:209], v[4:7]
	v_mfma_f32_16x16x32_bf16 v[0:3], v[164:167], v[206:209], v[0:3]
	v_mfma_f32_16x16x32_bf16 v[28:31], v[160:163], v[176:179], v[28:31]
	v_mfma_f32_16x16x32_bf16 v[24:27], v[168:171], v[176:179], v[24:27]
	v_mfma_f32_16x16x32_bf16 v[20:23], v[160:163], v[194:197], v[20:23]
	v_mfma_f32_16x16x32_bf16 v[16:19], v[168:171], v[194:197], v[16:19]
	v_mfma_f32_16x16x32_bf16 v[12:15], v[160:163], v[202:205], v[12:15]
	v_mfma_f32_16x16x32_bf16 v[8:11], v[168:171], v[202:205], v[8:11]
	v_mfma_f32_16x16x32_bf16 v[4:7], v[160:163], v[210:213], v[4:7]
	v_mfma_f32_16x16x32_bf16 v[0:3], v[168:171], v[210:213], v[0:3]
	s_setprio 0
	s_barrier
	s_add_i32 s75, 0, 0x18000
	s_add_i32 s80, 0, 0x1c000
	v_add_u32_e32 v152, s75, v133
	v_add_u32_e32 v168, s80, v133
	ds_read_b128 v[140:143], v152
	ds_read_b128 v[144:147], v152 offset:1024
	ds_read_b128 v[148:151], v152 offset:2048
	ds_read_b128 v[152:155], v152 offset:3072
	ds_read_b128 v[156:159], v168
	ds_read_b128 v[160:163], v168 offset:1024
	ds_read_b128 v[164:167], v168 offset:2048
	ds_read_b128 v[168:171], v168 offset:3072
	s_add_i32 s79, s79, s40
	s_mov_b32 m0, s41
	v_add_u32_e32 v215, s79, v132
	s_add_i32 s78, s78, s40
	ds_read_b128 v[172:175], v137 offset:32768
	ds_read_b128 v[176:179], v137 offset:33792
	ds_read_b128 v[180:183], v137 offset:34816
	ds_read_b128 v[194:197], v137 offset:35840
	ds_read_b128 v[198:201], v137 offset:36864
	ds_read_b128 v[202:205], v137 offset:37888
	ds_read_b128 v[206:209], v137 offset:38912
	ds_read_b128 v[210:213], v137 offset:39936
	global_load_lds_dwordx4 v215, s[82:83]
	v_add_u32_e32 v215, s78, v129
	s_mov_b32 m0, s44
	s_nop 0
	global_load_lds_dwordx4 v215, s[82:83]
	s_waitcnt vmcnt(8) lgkmcnt(0)
	s_barrier
	s_setprio 1
	v_mfma_f32_16x16x32_bf16 v[124:127], v[140:143], v[172:175], v[124:127]
	v_mfma_f32_16x16x32_bf16 v[120:123], v[148:151], v[172:175], v[120:123]
	v_mfma_f32_16x16x32_bf16 v[116:119], v[140:143], v[180:183], v[116:119]
	v_mfma_f32_16x16x32_bf16 v[112:115], v[148:151], v[180:183], v[112:115]
	v_mfma_f32_16x16x32_bf16 v[108:111], v[140:143], v[198:201], v[108:111]
	v_mfma_f32_16x16x32_bf16 v[104:107], v[148:151], v[198:201], v[104:107]
	v_mfma_f32_16x16x32_bf16 v[100:103], v[140:143], v[206:209], v[100:103]
	v_mfma_f32_16x16x32_bf16 v[96:99], v[148:151], v[206:209], v[96:99]
	v_mfma_f32_16x16x32_bf16 v[124:127], v[144:147], v[176:179], v[124:127]
	v_mfma_f32_16x16x32_bf16 v[120:123], v[152:155], v[176:179], v[120:123]
	v_mfma_f32_16x16x32_bf16 v[116:119], v[144:147], v[194:197], v[116:119]
	v_mfma_f32_16x16x32_bf16 v[112:115], v[152:155], v[194:197], v[112:115]
	v_mfma_f32_16x16x32_bf16 v[108:111], v[144:147], v[202:205], v[108:111]
	v_mfma_f32_16x16x32_bf16 v[104:107], v[152:155], v[202:205], v[104:107]
	v_mfma_f32_16x16x32_bf16 v[100:103], v[144:147], v[210:213], v[100:103]
	v_mfma_f32_16x16x32_bf16 v[96:99], v[152:155], v[210:213], v[96:99]
	v_mfma_f32_16x16x32_bf16 v[92:95], v[156:159], v[172:175], v[92:95]
	v_mfma_f32_16x16x32_bf16 v[88:91], v[164:167], v[172:175], v[88:91]
	v_mfma_f32_16x16x32_bf16 v[84:87], v[156:159], v[180:183], v[84:87]
	v_mfma_f32_16x16x32_bf16 v[80:83], v[164:167], v[180:183], v[80:83]
	v_mfma_f32_16x16x32_bf16 v[76:79], v[156:159], v[198:201], v[76:79]
	v_mfma_f32_16x16x32_bf16 v[72:75], v[164:167], v[198:201], v[72:75]
	v_mfma_f32_16x16x32_bf16 v[68:71], v[156:159], v[206:209], v[68:71]
	v_mfma_f32_16x16x32_bf16 v[64:67], v[164:167], v[206:209], v[64:67]
	v_mfma_f32_16x16x32_bf16 v[92:95], v[160:163], v[176:179], v[92:95]
	v_mfma_f32_16x16x32_bf16 v[88:91], v[168:171], v[176:179], v[88:91]
	v_mfma_f32_16x16x32_bf16 v[84:87], v[160:163], v[194:197], v[84:87]
	v_mfma_f32_16x16x32_bf16 v[80:83], v[168:171], v[194:197], v[80:83]
	v_mfma_f32_16x16x32_bf16 v[76:79], v[160:163], v[202:205], v[76:79]
	v_mfma_f32_16x16x32_bf16 v[72:75], v[168:171], v[202:205], v[72:75]
	v_mfma_f32_16x16x32_bf16 v[68:71], v[160:163], v[210:213], v[68:71]
	v_mfma_f32_16x16x32_bf16 v[64:67], v[168:171], v[210:213], v[64:67]
	s_setprio 0
	s_barrier
; #define G_STAGE_A(bufoff, p0, p1, koff) do { \
;         __builtin_amdgcn_global_load_lds((const unsigned*)(gbase + (size_t)(unsigned)((p0) + (koff) + voffA[0])), (LAS unsigned*)(lds + (bufoff) + ldsw), 16, 0, 0); \
;         __builtin_amdgcn_global_load_lds((const unsigned*)(gbase + (size_t)(unsigned)((p1) + (koff) + voffA[1])), (LAS unsigned*)(lds + (bufoff) + ldsw + 8192), 16, 0, 0); } while (0)
; #define G_STAGE_B(bufoff, p, koff) do { \
;         __builtin_amdgcn_global_load_lds((const unsigned*)(gbase + (size_t)(unsigned)((p) + (koff) + voffB[0])), (LAS unsigned*)(lds + (bufoff) + ldsw), 16, 0, 0); \
;         __builtin_amdgcn_global_load_lds((const unsigned*)(gbase + (size_t)(unsigned)((p) + (koff) + voffB[1])), (LAS unsigned*)(lds + (bufoff) + ldsw + 8192), 16, 0, 0); } while (0)
; #define G_LDA(dst, b, h) do { _Pragma("unroll") for (int m = 0; m < 4; ++m) _Pragma("unroll") for (int k = 0; k < 2; ++k) dst[m][k] = *(const LAS bf16x8*)(lds + G_SA(b, h) + aoff + m * 2048 + k * 1024); } while (0)
; #define G_LDB(dst, b, h) do { _Pragma("unroll") for (int n = 0; n < 2; ++n) _Pragma("unroll") for (int k = 0; k < 2; ++k) dst[n][k] = *(const LAS bf16x8*)(lds + G_SB(b, h) + boff + n * 2048 + k * 1024); } while (0)
; #define G_MMA(ai, bj, At, Bt) do { __builtin_amdgcn_s_setprio(1); _Pragma("unroll") for (int m = 0; m < 4; ++m) _Pragma("unroll") for (int n = 0; n < 2; ++n) _Pragma("unroll") for (int k = 0; k < 2; ++k) \
;         acc[ai][bj][m][n] = __builtin_amdgcn_mfma_f32_16x16x32_bf16(Bt[n][k], At[m][k], acc[ai][bj][m][n], 0, 0, 0); __builtin_amdgcn_s_setprio(0); } while (0)
; #define G_WAIT_V(n) asm volatile("s_waitcnt vmcnt(" #n ")" ::: "memory")
; #define G_WAIT_L(n) asm volatile("s_waitcnt lgkmcnt(" #n ")" ::: "memory")
; #define G_BAR __builtin_amdgcn_s_barrier()
; template <class Epi>
; DI void gemm_phase(LAS unsigned char* lds, const Sched& S, const Epi& E, const int K) {
;     ...
;             G_LDB(B0, 1, 0); G_LDB(B1, 1, 1); G_SCHED; G_LDA(At, 1, 0); G_STAGE_A(G_SA(0, 1), x2, x3, k2);
;             G_WAIT_V(8); G_WAIT_L(0); G_BAR; G_MMA(0, 0, At, B0); G_MMA(0, 1, At, B1); G_BAR; G_SCHED;
;             G_LDA(At, 1, 1); G_STAGE_B(G_SB(1, 0), xb, kb3); G_STAGE_B(G_SB(1, 1), xb + hstepB, kb3); G_STAGE_A(G_SA(1, 0), x0, x1, k3);
;             G_WAIT_V(8); G_WAIT_L(0); G_BAR; G_MMA(1, 0, At, B0); G_MMA(1, 1, At, B1); G_BAR; G_SCHED;
	s_add_i32 s40, s70, s73
	s_add_i32 s73, s75, s21
	v_add_u32_e32 v215, s40, v128
	s_mov_b32 m0, s73
	ds_read_b128 v[172:175], v137 offset:49152
	ds_read_b128 v[176:179], v137 offset:50176
	ds_read_b128 v[180:183], v137 offset:51200
	ds_read_b128 v[194:197], v137 offset:52224
	ds_read_b128 v[198:201], v137 offset:53248
	ds_read_b128 v[202:205], v137 offset:54272
	ds_read_b128 v[206:209], v137 offset:55296
	ds_read_b128 v[210:213], v137 offset:56320
	global_load_lds_dwordx4 v215, s[82:83]
	v_add_u32_e32 v215, s40, v130
	s_add_i32 m0, s73, 0x2000
	s_add_i32 s14, s70, s14
	s_add_i32 s40, s80, s21
	global_load_lds_dwordx4 v215, s[82:83]
	v_add_u32_e32 v215, s14, v128
	s_mov_b32 m0, s40
	v_add_u32_e32 v184, s70, v184
	global_load_lds_dwordx4 v215, s[82:83]
	v_add_u32_e32 v215, s14, v130
	s_add_i32 m0, s40, 0x2000
	s_nop 0
	global_load_lds_dwordx4 v215, s[82:83]
	s_mov_b32 m0, s18
	s_nop 0
	global_load_lds_dwordx4 v184, s[82:83]
	v_add_u32_e32 v184, s70, v214
	s_mov_b32 m0, s45
	s_nop 0
	global_load_lds_dwordx4 v184, s[82:83]
	s_waitcnt vmcnt(8) lgkmcnt(0)
	s_barrier
	s_setprio 1
	v_mfma_f32_16x16x32_bf16 v[60:63], v[140:143], v[172:175], v[60:63]
	v_mfma_f32_16x16x32_bf16 v[56:59], v[148:151], v[172:175], v[56:59]
	v_mfma_f32_16x16x32_bf16 v[52:55], v[140:143], v[180:183], v[52:55]
	v_mfma_f32_16x16x32_bf16 v[48:51], v[148:151], v[180:183], v[48:51]
	v_mfma_f32_16x16x32_bf16 v[44:47], v[140:143], v[198:201], v[44:47]
	v_mfma_f32_16x16x32_bf16 v[40:43], v[148:151], v[198:201], v[40:43]
	v_mfma_f32_16x16x32_bf16 v[36:39], v[140:143], v[206:209], v[36:39]
	v_mfma_f32_16x16x32_bf16 v[32:35], v[148:151], v[206:209], v[32:35]
	v_mfma_f32_16x16x32_bf16 v[60:63], v[144:147], v[176:179], v[60:63]
	v_mfma_f32_16x16x32_bf16 v[56:59], v[152:155], v[176:179], v[56:59]
	v_mfma_f32_16x16x32_bf16 v[52:55], v[144:147], v[194:197], v[52:55]
	v_mfma_f32_16x16x32_bf16 v[48:51], v[152:155], v[194:197], v[48:51]
	v_mfma_f32_16x16x32_bf16 v[44:47], v[144:147], v[202:205], v[44:47]
	v_mfma_f32_16x16x32_bf16 v[40:43], v[152:155], v[202:205], v[40:43]
	v_mfma_f32_16x16x32_bf16 v[36:39], v[144:147], v[210:213], v[36:39]
	v_mfma_f32_16x16x32_bf16 v[32:35], v[152:155], v[210:213], v[32:35]
	v_mfma_f32_16x16x32_bf16 v[28:31], v[156:159], v[172:175], v[28:31]
	v_mfma_f32_16x16x32_bf16 v[24:27], v[164:167], v[172:175], v[24:27]
	v_mfma_f32_16x16x32_bf16 v[20:23], v[156:159], v[180:183], v[20:23]
	v_mfma_f32_16x16x32_bf16 v[16:19], v[164:167], v[180:183], v[16:19]
	v_mfma_f32_16x16x32_bf16 v[12:15], v[156:159], v[198:201], v[12:15]
	v_mfma_f32_16x16x32_bf16 v[8:11], v[164:167], v[198:201], v[8:11]
	v_mfma_f32_16x16x32_bf16 v[4:7], v[156:159], v[206:209], v[4:7]
	v_mfma_f32_16x16x32_bf16 v[0:3], v[164:167], v[206:209], v[0:3]
	v_mfma_f32_16x16x32_bf16 v[28:31], v[160:163], v[176:179], v[28:31]
	v_mfma_f32_16x16x32_bf16 v[24:27], v[168:171], v[176:179], v[24:27]
	v_mfma_f32_16x16x32_bf16 v[20:23], v[160:163], v[194:197], v[20:23]
	v_mfma_f32_16x16x32_bf16 v[16:19], v[168:171], v[194:197], v[16:19]
	v_mfma_f32_16x16x32_bf16 v[12:15], v[160:163], v[202:205], v[12:15]
	v_mfma_f32_16x16x32_bf16 v[8:11], v[168:171], v[202:205], v[8:11]
	v_mfma_f32_16x16x32_bf16 v[4:7], v[160:163], v[210:213], v[4:7]
	v_mfma_f32_16x16x32_bf16 v[0:3], v[168:171], v[210:213], v[0:3]
	s_setprio 0
	s_barrier
	s_cmp_ge_u32 s71, s17
	s_mov_b32 s14, s72
	s_mov_b32 s70, s71
	s_cbranch_scc0 .LBB0_217
	s_and_b64 vcc, exec, s[10:11]
	s_movk_i32 s70, 0x1000
	s_cbranch_vccz .LBB0_220
	s_barrier

; #define G_STAGE_A(bufoff, p0, p1, koff) do { \
;         __builtin_amdgcn_global_load_lds((const unsigned*)(gbase + (size_t)(unsigned)((p0) + (koff) + voffA[0])), (LAS unsigned*)(lds + (bufoff) + ldsw), 16, 0, 0); \
;         __builtin_amdgcn_global_load_lds((const unsigned*)(gbase + (size_t)(unsigned)((p1) + (koff) + voffA[1])), (LAS unsigned*)(lds + (bufoff) + ldsw + 8192), 16, 0, 0); } while (0)
; #define G_STAGE_B(bufoff, p, koff) do { \
;         __builtin_amdgcn_global_load_lds((const unsigned*)(gbase + (size_t)(unsigned)((p) + (koff) + voffB[0])), (LAS unsigned*)(lds + (bufoff) + ldsw), 16, 0, 0); \
;         __builtin_amdgcn_global_load_lds((const unsigned*)(gbase + (size_t)(unsigned)((p) + (koff) + voffB[1])), (LAS unsigned*)(lds + (bufoff) + ldsw + 8192), 16, 0, 0); } while (0)
; #define G_LDA(dst, b, h) do { _Pragma("unroll") for (int m = 0; m < 4; ++m) _Pragma("unroll") for (int k = 0; k < 2; ++k) dst[m][k] = *(const LAS bf16x8*)(lds + G_SA(b, h) + aoff + m * 2048 + k * 1024); } while (0)
; #define G_LDB(dst, b, h) do { _Pragma("unroll") for (int n = 0; n < 2; ++n) _Pragma("unroll") for (int k = 0; k < 2; ++k) dst[n][k] = *(const LAS bf16x8*)(lds + G_SB(b, h) + boff + n * 2048 + k * 1024); } while (0)
; #define G_WAIT_V(n) asm volatile("s_waitcnt vmcnt(" #n ")" ::: "memory")
; #define G_BAR __builtin_amdgcn_s_barrier()
; template <class Epi>
; DI void gemm_phase(LAS unsigned char* lds, const Sched& S, const Epi& E, const int K) {
;     ...
;             G_LDB(B0, 0, 0); G_LDB(B1, 0, 1); G_SCHED; G_LDA(At, 0, 0); G_STAGE_A(G_SA(1, 1), cur.a2, cur.a3, k1);
;             G_WAIT_V(8); G_WAIT_L(0); G_BAR; G_MMA(0, 0, At, B0); G_MMA(0, 1, At, B1); G_BAR; G_SCHED;
;             G_LDA(At, 0, 1); G_STAGE_B(G_SB(0, 0), xb, kb2); G_STAGE_B(G_SB(0, 1), xb + hstepB, kb2); G_STAGE_A(G_SA(0, 0), x0, x1, k2);
;             G_WAIT_V(8); G_WAIT_L(0); G_BAR; G_MMA(1, 0, At, B0); G_MMA(1, 1, At, B1); G_BAR; G_SCHED;
;             G_LDB(B0, 1, 0); G_LDB(B1, 1, 1); G_SCHED; G_LDA(At, 1, 0); G_STAGE_A(G_SA(0, 1), x2, x3, k2);
;             G_WAIT_V(8); G_WAIT_L(0); G_BAR; G_MMA(0, 0, At, B0); G_MMA(0, 1, At, B1); G_BAR; G_SCHED;
;             G_LDA(At, 1, 1); G_STAGE_B(G_SB(1, 0), xb, kb3); G_STAGE_B(G_SB(1, 1), xb + hstepB, kb3); G_STAGE_A(G_SA(1, 0), x0, x1, k3);
;             G_WAIT_V(8); G_WAIT_L(0); G_BAR; G_MMA(1, 0, At, B0); G_MMA(1, 1, At, B1); G_BAR; G_SCHED;
.LBB0_240:
	s_add_i32 s14, s15, 0x8000
	v_add_u32_e32 v151, s14, v80
	v_add_u32_e32 v152, s14, v81
	s_add_i32 s14, s15, 0x80
	v_add_u32_e32 v153, s14, v80
	v_add_u32_e32 v154, s14, v81
	s_add_i32 s14, s15, 0x8080
	v_add_u32_e32 v85, s15, v80
	v_add_u32_e32 v150, s15, v81
	v_add_u32_e32 v155, s14, v80
	v_add_u32_e32 v156, s14, v81
	s_add_i32 s14, 0, 0x10000
	s_add_i32 s15, 0, 0x14000
	v_add_u32_e32 v98, s14, v83
	v_add_u32_e32 v114, s15, v83
	ds_read_b128 v[86:89], v98
	ds_read_b128 v[90:93], v98 offset:1024
	ds_read_b128 v[94:97], v98 offset:2048
	ds_read_b128 v[98:101], v98 offset:3072
	ds_read_b128 v[102:105], v114
	ds_read_b128 v[106:109], v114 offset:1024
	ds_read_b128 v[110:113], v114 offset:2048
	ds_read_b128 v[114:117], v114 offset:3072
	s_add_i32 m0, s17, 0xc000
	s_waitcnt vmcnt(0)
	ds_read_b128 v[118:121], v84
	ds_read_b128 v[122:125], v84 offset:1024
	ds_read_b128 v[126:129], v84 offset:2048
	ds_read_b128 v[130:133], v84 offset:3072
	ds_read_b128 v[134:137], v84 offset:4096
	ds_read_b128 v[138:141], v84 offset:5120
	ds_read_b128 v[142:145], v84 offset:6144
	ds_read_b128 v[146:149], v84 offset:7168
	global_load_lds_dwordx4 v[76:77], off
	s_add_i32 m0, s17, 0xe000
	s_nop 0
	global_load_lds_dwordx4 v[78:79], off
	s_waitcnt vmcnt(8) lgkmcnt(0)
	s_barrier
	s_setprio 1
	v_mfma_f32_16x16x32_bf16 v[60:63], v[86:89], v[118:121], v[60:63]
	v_mfma_f32_16x16x32_bf16 v[56:59], v[94:97], v[118:121], v[56:59]
	v_mfma_f32_16x16x32_bf16 v[52:55], v[86:89], v[126:129], v[52:55]
	v_mfma_f32_16x16x32_bf16 v[48:51], v[94:97], v[126:129], v[48:51]
	v_mfma_f32_16x16x32_bf16 v[44:47], v[86:89], v[134:137], v[44:47]
	v_mfma_f32_16x16x32_bf16 v[40:43], v[94:97], v[134:137], v[40:43]
	v_mfma_f32_16x16x32_bf16 v[36:39], v[86:89], v[142:145], v[36:39]
	v_mfma_f32_16x16x32_bf16 v[32:35], v[94:97], v[142:145], v[32:35]
	v_mfma_f32_16x16x32_bf16 v[60:63], v[90:93], v[122:125], v[60:63]
	v_mfma_f32_16x16x32_bf16 v[56:59], v[98:101], v[122:125], v[56:59]
	v_mfma_f32_16x16x32_bf16 v[52:55], v[90:93], v[130:133], v[52:55]
	v_mfma_f32_16x16x32_bf16 v[48:51], v[98:101], v[130:133], v[48:51]
	v_mfma_f32_16x16x32_bf16 v[44:47], v[90:93], v[138:141], v[44:47]
	v_mfma_f32_16x16x32_bf16 v[40:43], v[98:101], v[138:141], v[40:43]
	v_mfma_f32_16x16x32_bf16 v[36:39], v[90:93], v[146:149], v[36:39]
	v_mfma_f32_16x16x32_bf16 v[32:35], v[98:101], v[146:149], v[32:35]
	v_mfma_f32_16x16x32_bf16 v[28:31], v[102:105], v[118:121], v[28:31]
	v_mfma_f32_16x16x32_bf16 v[24:27], v[110:113], v[118:121], v[24:27]
	v_mfma_f32_16x16x32_bf16 v[20:23], v[102:105], v[126:129], v[20:23]
	v_mfma_f32_16x16x32_bf16 v[16:19], v[110:113], v[126:129], v[16:19]
	v_mfma_f32_16x16x32_bf16 v[12:15], v[102:105], v[134:137], v[12:15]
	v_mfma_f32_16x16x32_bf16 v[8:11], v[110:113], v[134:137], v[8:11]
	v_mfma_f32_16x16x32_bf16 v[4:7], v[102:105], v[142:145], v[4:7]
	v_mfma_f32_16x16x32_bf16 v[0:3], v[110:113], v[142:145], v[0:3]
	v_mfma_f32_16x16x32_bf16 v[28:31], v[106:109], v[122:125], v[28:31]
	v_mfma_f32_16x16x32_bf16 v[24:27], v[114:117], v[122:125], v[24:27]
	v_mfma_f32_16x16x32_bf16 v[20:23], v[106:109], v[130:133], v[20:23]
	v_mfma_f32_16x16x32_bf16 v[16:19], v[114:117], v[130:133], v[16:19]
	v_mfma_f32_16x16x32_bf16 v[12:15], v[106:109], v[138:141], v[12:15]
	v_mfma_f32_16x16x32_bf16 v[8:11], v[114:117], v[138:141], v[8:11]
	v_mfma_f32_16x16x32_bf16 v[4:7], v[106:109], v[146:149], v[4:7]
	v_mfma_f32_16x16x32_bf16 v[0:3], v[114:117], v[146:149], v[0:3]
	s_setprio 0
	s_barrier
	s_add_i32 s14, s14, s16
	s_mov_b32 m0, s14
	s_nop 0
	global_load_lds_dwordx4 v85, s[82:83]
	s_add_i32 m0, s14, 0x2000
	s_add_i32 s14, s15, s16
	global_load_lds_dwordx4 v150, s[82:83]
	s_mov_b32 m0, s14
	s_nop 0
	global_load_lds_dwordx4 v151, s[82:83]
	s_add_i32 m0, s14, 0x2000
	s_nop 0
	global_load_lds_dwordx4 v152, s[82:83]
	s_mov_b32 m0, s17
	s_nop 0
	global_load_lds_dwordx4 v[64:65], off
	s_mov_b32 m0, s18
	s_nop 0
	global_load_lds_dwordx4 v[66:67], off
	s_waitcnt vmcnt(8) lgkmcnt(0)
	s_barrier
	s_setprio 1
	s_setprio 0
	s_setprio 1
	s_setprio 0
	s_barrier
	s_add_i32 s14, 0, 0x18000
	v_add_u32_e32 v85, s14, v83
	s_add_i32 s15, 0, 0x1c000
	ds_read_b128 v[86:89], v85
	ds_read_b128 v[90:93], v85 offset:1024
	ds_read_b128 v[94:97], v85 offset:2048
	ds_read_b128 v[98:101], v85 offset:3072
	v_add_u32_e32 v85, s15, v83
	ds_read_b128 v[102:105], v85
	ds_read_b128 v[106:109], v85 offset:1024
	ds_read_b128 v[110:113], v85 offset:2048
	ds_read_b128 v[114:117], v85 offset:3072
	s_mov_b32 m0, s19
	ds_read_b128 v[118:121], v84 offset:32768
	ds_read_b128 v[122:125], v84 offset:33792
	ds_read_b128 v[126:129], v84 offset:34816
	ds_read_b128 v[130:133], v84 offset:35840
	ds_read_b128 v[134:137], v84 offset:36864
	ds_read_b128 v[138:141], v84 offset:37888
	ds_read_b128 v[142:145], v84 offset:38912
	ds_read_b128 v[146:149], v84 offset:39936
	global_load_lds_dwordx4 v[68:69], off
	s_mov_b32 m0, s20
	s_nop 0
	global_load_lds_dwordx4 v[70:71], off
	s_waitcnt vmcnt(8) lgkmcnt(0)
	s_barrier
; #define G_STAGE_A(bufoff, p0, p1, koff) do { \
;         __builtin_amdgcn_global_load_lds((const unsigned*)(gbase + (size_t)(unsigned)((p0) + (koff) + voffA[0])), (LAS unsigned*)(lds + (bufoff) + ldsw), 16, 0, 0); \
;         __builtin_amdgcn_global_load_lds((const unsigned*)(gbase + (size_t)(unsigned)((p1) + (koff) + voffA[1])), (LAS unsigned*)(lds + (bufoff) + ldsw + 8192), 16, 0, 0); } while (0)
; #define G_STAGE_B(bufoff, p, koff) do { \
;         __builtin_amdgcn_global_load_lds((const unsigned*)(gbase + (size_t)(unsigned)((p) + (koff) + voffB[0])), (LAS unsigned*)(lds + (bufoff) + ldsw), 16, 0, 0); \
;         __builtin_amdgcn_global_load_lds((const unsigned*)(gbase + (size_t)(unsigned)((p) + (koff) + voffB[1])), (LAS unsigned*)(lds + (bufoff) + ldsw + 8192), 16, 0, 0); } while (0)
; #define G_LDA(dst, b, h) do { _Pragma("unroll") for (int m = 0; m < 4; ++m) _Pragma("unroll") for (int k = 0; k < 2; ++k) dst[m][k] = *(const LAS bf16x8*)(lds + G_SA(b, h) + aoff + m * 2048 + k * 1024); } while (0)
; #define G_LDB(dst, b, h) do { _Pragma("unroll") for (int n = 0; n < 2; ++n) _Pragma("unroll") for (int k = 0; k < 2; ++k) dst[n][k] = *(const LAS bf16x8*)(lds + G_SB(b, h) + boff + n * 2048 + k * 1024); } while (0)
; #define G_WAIT_V(n) asm volatile("s_waitcnt vmcnt(" #n ")" ::: "memory")
; #define G_BAR __builtin_amdgcn_s_barrier()
; template <class Epi>
; DI void gemm_phase(LAS unsigned char* lds, const Sched& S, const Epi& E, const int K) {
;     ...
;             G_LDB(B0, 1, 0); G_LDB(B1, 1, 1); G_SCHED; G_LDA(At, 1, 0); G_STAGE_A(G_SA(0, 1), x2, x3, k2);
;             G_WAIT_V(8); G_WAIT_L(0); G_BAR; G_MMA(0, 0, At, B0); G_MMA(0, 1, At, B1); G_BAR; G_SCHED;
;             G_LDA(At, 1, 1); G_STAGE_B(G_SB(1, 0), xb, kb3); G_STAGE_B(G_SB(1, 1), xb + hstepB, kb3); G_STAGE_A(G_SA(1, 0), x0, x1, k3);
;             G_WAIT_V(8); G_WAIT_L(0); G_BAR; G_MMA(1, 0, At, B0); G_MMA(1, 1, At, B1); G_BAR; G_SCHED;
;     ...
;         if (wr == 0) G_BAR;
;     ...
;         E(acc, cur, wr, wc, fr, fq);
;     DI void operator()(const f32x4 (&acc)[2][2][4][2], const Unit& u, int wr, int wc, int fr, int fq) const {
;         if (wr != 0) return;
;         const int b = u.z >> 6, k1 = u.z & 63;
; #pragma unroll
;         for (int m = 0; m < 4; ++m) { const int k2 = 16 * m + fr; bf16_t* rowp = MIXCAT + (size_t)(b * 4096 + k1 + 64 * k2) * DM + 1024 + u.pn * 256 + wc * 32 + 8 * fq;
	s_setprio 1
	v_mfma_f32_16x16x32_bf16 v[60:63], v[86:89], v[118:121], v[60:63]
	v_mfma_f32_16x16x32_bf16 v[56:59], v[94:97], v[118:121], v[56:59]
	v_mfma_f32_16x16x32_bf16 v[52:55], v[86:89], v[126:129], v[52:55]
	v_mfma_f32_16x16x32_bf16 v[48:51], v[94:97], v[126:129], v[48:51]
	v_mfma_f32_16x16x32_bf16 v[44:47], v[86:89], v[134:137], v[44:47]
	v_mfma_f32_16x16x32_bf16 v[40:43], v[94:97], v[134:137], v[40:43]
	v_mfma_f32_16x16x32_bf16 v[36:39], v[86:89], v[142:145], v[36:39]
	v_mfma_f32_16x16x32_bf16 v[32:35], v[94:97], v[142:145], v[32:35]
	v_mfma_f32_16x16x32_bf16 v[60:63], v[90:93], v[122:125], v[60:63]
	v_mfma_f32_16x16x32_bf16 v[56:59], v[98:101], v[122:125], v[56:59]
	v_mfma_f32_16x16x32_bf16 v[52:55], v[90:93], v[130:133], v[52:55]
	v_mfma_f32_16x16x32_bf16 v[48:51], v[98:101], v[130:133], v[48:51]
	v_mfma_f32_16x16x32_bf16 v[44:47], v[90:93], v[138:141], v[44:47]
	v_mfma_f32_16x16x32_bf16 v[40:43], v[98:101], v[138:141], v[40:43]
	v_mfma_f32_16x16x32_bf16 v[36:39], v[90:93], v[146:149], v[36:39]
	v_mfma_f32_16x16x32_bf16 v[32:35], v[98:101], v[146:149], v[32:35]
	v_mfma_f32_16x16x32_bf16 v[28:31], v[102:105], v[118:121], v[28:31]
	v_mfma_f32_16x16x32_bf16 v[24:27], v[110:113], v[118:121], v[24:27]
	v_mfma_f32_16x16x32_bf16 v[20:23], v[102:105], v[126:129], v[20:23]
	v_mfma_f32_16x16x32_bf16 v[16:19], v[110:113], v[126:129], v[16:19]
	v_mfma_f32_16x16x32_bf16 v[12:15], v[102:105], v[134:137], v[12:15]
	v_mfma_f32_16x16x32_bf16 v[8:11], v[110:113], v[134:137], v[8:11]
	v_mfma_f32_16x16x32_bf16 v[4:7], v[102:105], v[142:145], v[4:7]
	v_mfma_f32_16x16x32_bf16 v[0:3], v[110:113], v[142:145], v[0:3]
	v_mfma_f32_16x16x32_bf16 v[28:31], v[106:109], v[122:125], v[28:31]
	v_mfma_f32_16x16x32_bf16 v[24:27], v[114:117], v[122:125], v[24:27]
	v_mfma_f32_16x16x32_bf16 v[20:23], v[106:109], v[130:133], v[20:23]
	v_mfma_f32_16x16x32_bf16 v[16:19], v[114:117], v[130:133], v[16:19]
	v_mfma_f32_16x16x32_bf16 v[12:15], v[106:109], v[138:141], v[12:15]
	v_mfma_f32_16x16x32_bf16 v[8:11], v[114:117], v[138:141], v[8:11]
	v_mfma_f32_16x16x32_bf16 v[4:7], v[106:109], v[146:149], v[4:7]
	v_mfma_f32_16x16x32_bf16 v[0:3], v[114:117], v[146:149], v[0:3]
	s_setprio 0
	s_barrier
	s_add_i32 s14, s14, s16
	s_mov_b32 m0, s14
	s_nop 0
	global_load_lds_dwordx4 v153, s[82:83]
	s_add_i32 m0, s14, 0x2000
	s_add_i32 s14, s15, s16
	global_load_lds_dwordx4 v154, s[82:83]
	s_mov_b32 m0, s14
	s_nop 0
	global_load_lds_dwordx4 v155, s[82:83]
	s_add_i32 m0, s14, 0x2000
	s_nop 0
	global_load_lds_dwordx4 v156, s[82:83]
	s_mov_b32 m0, s21
	s_nop 0
	global_load_lds_dwordx4 v[72:73], off
	s_mov_b32 m0, s24
	s_nop 0
	global_load_lds_dwordx4 v[74:75], off
	s_waitcnt vmcnt(8) lgkmcnt(0)
	s_barrier
	s_setprio 1
	s_setprio 0
	s_setprio 1
	s_setprio 0
	s_barrier
	s_andn2_b64 vcc, exec, s[12:13]
	s_cbranch_vccnz .LBB0_242
	s_lshl_b32 s15, s25, 6
	s_and_b32 s14, s25, 63
	s_and_b32 s15, s15, 0xfffff000
	s_or_b32 s14, s14, s15
	v_or_b32_e32 v90, s14, v82
	s_lshl_b32 s14, s26, 8
	v_ashrrev_i32_e32 v91, 31, v90
	v_readlane_b32 s44, v254, 30
	s_ashr_i32 s15, s14, 31
	v_lshlrev_b64 v[86:87], 12, v[90:91]
	v_readlane_b32 s45, v254, 31
	s_lshl_b64 s[14:15], s[14:15], 1
	s_mov_b32 s40, 0x3c800000
	v_lshl_add_u64 v[86:87], s[44:45], 0, v[86:87]
	v_lshl_add_u64 v[86:87], v[86:87], 0, s[14:15]
	v_lshl_add_u64 v[86:87], v[86:87], 0, s[48:49]
	v_lshl_add_u64 v[92:93], v[86:87], 0, v[184:185]
	v_pk_mul_f32 v[88:89], v[62:63], s[40:41] op_sel_hi:[1,0]
	v_pk_mul_f32 v[86:87], v[60:61], s[40:41] op_sel_hi:[1,0]
	v_pk_mul_f32 v[94:95], v[58:59], s[40:41] op_sel_hi:[1,0]
	v_pk_mul_f32 v[96:97], v[56:57], s[40:41] op_sel_hi:[1,0]
	v_cvt_pk_bf16_f32 v86, v86, v87
	v_cvt_pk_bf16_f32 v87, v88, v89
	v_cvt_pk_bf16_f32 v88, v96, v97
	v_cvt_pk_bf16_f32 v89, v94, v95
	s_barrier
; DI u32x4 pack8(const f32x4& v0, const f32x4& v1) { u32x4 w; w.x = pk2(v0[0], v0[1]); w.y = pk2(v0[2], v0[3]); w.z = pk2(v1[0], v1[1]); w.w = pk2(v1[2], v1[3]); return w; }
;     DI void operator()(const f32x4 (&acc)[2][2][4][2], const Unit& u, int wr, int wc, int fr, int fq) const {
;     ...
; #pragma unroll
;         for (int m = 0; m < 4; ++m) { const int k2 = 16 * m + fr; bf16_t* rowp = MIXCAT + (size_t)(b * 4096 + k1 + 64 * k2) * DM + 1024 + u.pn * 256 + wc * 32 + 8 * fq;
; #pragma unroll
;             for (int bj = 0; bj < 2; ++bj) *(u32x4*)(rowp + bj * 128) = pack8(acc[0][bj][m][0] * 0.015625f, acc[0][bj][m][1] * 0.015625f); }
	global_store_dwordx4 v[92:93], v[86:89], off offset:2048
	v_pk_mul_f32 v[94:95], v[26:27], s[40:41] op_sel_hi:[1,0]
	v_pk_mul_f32 v[96:97], v[24:25], s[40:41] op_sel_hi:[1,0]
	v_pk_mul_f32 v[88:89], v[30:31], s[40:41] op_sel_hi:[1,0]
	v_pk_mul_f32 v[86:87], v[28:29], s[40:41] op_sel_hi:[1,0]
	s_nop 0
	v_cvt_pk_bf16_f32 v86, v86, v87
	v_cvt_pk_bf16_f32 v87, v88, v89
	v_cvt_pk_bf16_f32 v88, v96, v97
	v_cvt_pk_bf16_f32 v89, v94, v95
	global_store_dwordx4 v[92:93], v[86:89], off offset:2304
	v_pk_mul_f32 v[94:95], v[50:51], s[40:41] op_sel_hi:[1,0]
	v_pk_mul_f32 v[96:97], v[48:49], s[40:41] op_sel_hi:[1,0]
	v_or_b32_e32 v86, 0x400, v90
	v_ashrrev_i32_e32 v87, 31, v86
	v_lshlrev_b64 v[86:87], 12, v[86:87]
	v_lshl_add_u64 v[86:87], s[44:45], 0, v[86:87]
	v_lshl_add_u64 v[86:87], v[86:87], 0, s[14:15]
	v_lshl_add_u64 v[86:87], v[86:87], 0, s[48:49]
	v_lshl_add_u64 v[92:93], v[86:87], 0, v[184:185]
	v_pk_mul_f32 v[88:89], v[54:55], s[40:41] op_sel_hi:[1,0]
	v_pk_mul_f32 v[86:87], v[52:53], s[40:41] op_sel_hi:[1,0]
	s_nop 0
	v_cvt_pk_bf16_f32 v86, v86, v87
	v_cvt_pk_bf16_f32 v87, v88, v89
	v_cvt_pk_bf16_f32 v88, v96, v97
	v_cvt_pk_bf16_f32 v89, v94, v95
	global_store_dwordx4 v[92:93], v[86:89], off offset:2048
	v_pk_mul_f32 v[94:95], v[18:19], s[40:41] op_sel_hi:[1,0]
	v_pk_mul_f32 v[96:97], v[16:17], s[40:41] op_sel_hi:[1,0]
	v_pk_mul_f32 v[88:89], v[22:23], s[40:41] op_sel_hi:[1,0]
	v_pk_mul_f32 v[86:87], v[20:21], s[40:41] op_sel_hi:[1,0]
	s_nop 0
	v_cvt_pk_bf16_f32 v86, v86, v87
	v_cvt_pk_bf16_f32 v87, v88, v89
	v_cvt_pk_bf16_f32 v88, v96, v97
	v_cvt_pk_bf16_f32 v89, v94, v95
	global_store_dwordx4 v[92:93], v[86:89], off offset:2304
	v_pk_mul_f32 v[94:95], v[42:43], s[40:41] op_sel_hi:[1,0]
	v_pk_mul_f32 v[96:97], v[40:41], s[40:41] op_sel_hi:[1,0]
	v_or_b32_e32 v86, 0x800, v90
	v_ashrrev_i32_e32 v87, 31, v86
	v_lshlrev_b64 v[86:87], 12, v[86:87]
	v_lshl_add_u64 v[86:87], s[44:45], 0, v[86:87]
	v_lshl_add_u64 v[86:87], v[86:87], 0, s[14:15]
	v_lshl_add_u64 v[86:87], v[86:87], 0, s[48:49]
	v_lshl_add_u64 v[92:93], v[86:87], 0, v[184:185]
	v_pk_mul_f32 v[88:89], v[46:47], s[40:41] op_sel_hi:[1,0]
	v_pk_mul_f32 v[86:87], v[44:45], s[40:41] op_sel_hi:[1,0]
	s_nop 0
	v_cvt_pk_bf16_f32 v86, v86, v87
	v_cvt_pk_bf16_f32 v87, v88, v89
	v_cvt_pk_bf16_f32 v88, v96, v97
	v_cvt_pk_bf16_f32 v89, v94, v95
	global_store_dwordx4 v[92:93], v[86:89], off offset:2048
	v_pk_mul_f32 v[94:95], v[10:11], s[40:41] op_sel_hi:[1,0]
	v_pk_mul_f32 v[96:97], v[8:9], s[40:41] op_sel_hi:[1,0]
	v_pk_mul_f32 v[88:89], v[14:15], s[40:41] op_sel_hi:[1,0]
	v_pk_mul_f32 v[86:87], v[12:13], s[40:41] op_sel_hi:[1,0]
	s_nop 0
	v_cvt_pk_bf16_f32 v86, v86, v87
	v_cvt_pk_bf16_f32 v87, v88, v89
	v_cvt_pk_bf16_f32 v88, v96, v97
	v_cvt_pk_bf16_f32 v89, v94, v95
	global_store_dwordx4 v[92:93], v[86:89], off offset:2304
	v_pk_mul_f32 v[92:93], v[34:35], s[40:41] op_sel_hi:[1,0]
	v_pk_mul_f32 v[94:95], v[32:33], s[40:41] op_sel_hi:[1,0]
	v_or_b32_e32 v86, 0xc00, v90
	v_ashrrev_i32_e32 v87, 31, v86
	v_lshlrev_b64 v[86:87], 12, v[86:87]
	v_lshl_add_u64 v[86:87], s[44:45], 0, v[86:87]
	v_lshl_add_u64 v[86:87], v[86:87], 0, s[14:15]
	v_lshl_add_u64 v[86:87], v[86:87], 0, s[48:49]
	v_lshl_add_u64 v[90:91], v[86:87], 0, v[184:185]
	v_pk_mul_f32 v[88:89], v[38:39], s[40:41] op_sel_hi:[1,0]
	v_pk_mul_f32 v[86:87], v[36:37], s[40:41] op_sel_hi:[1,0]
	s_nop 0
	v_cvt_pk_bf16_f32 v86, v86, v87
	v_cvt_pk_bf16_f32 v87, v88, v89
	v_cvt_pk_bf16_f32 v88, v94, v95
	v_cvt_pk_bf16_f32 v89, v92, v93
	global_store_dwordx4 v[90:91], v[86:89], off offset:2048
	v_pk_mul_f32 v[92:93], v[2:3], s[40:41] op_sel_hi:[1,0]
	v_pk_mul_f32 v[94:95], v[0:1], s[40:41] op_sel_hi:[1,0]
	v_pk_mul_f32 v[88:89], v[6:7], s[40:41] op_sel_hi:[1,0]
	v_pk_mul_f32 v[86:87], v[4:5], s[40:41] op_sel_hi:[1,0]
	s_nop 0
	v_cvt_pk_bf16_f32 v86, v86, v87
	v_cvt_pk_bf16_f32 v87, v88, v89
	v_cvt_pk_bf16_f32 v88, v94, v95
	v_cvt_pk_bf16_f32 v89, v92, v93
	global_store_dwordx4 v[90:91], v[86:89], off offset:2304
	s_andn2_b64 vcc, exec, s[10:11]
	s_cbranch_vccnz .LBB0_233
	s_branch .LBB0_243

; #define G_STAGE_A(bufoff, p0, p1, koff) do { \
;         __builtin_amdgcn_global_load_lds((const unsigned*)(gbase + (size_t)(unsigned)((p0) + (koff) + voffA[0])), (LAS unsigned*)(lds + (bufoff) + ldsw), 16, 0, 0); \
;         __builtin_amdgcn_global_load_lds((const unsigned*)(gbase + (size_t)(unsigned)((p1) + (koff) + voffA[1])), (LAS unsigned*)(lds + (bufoff) + ldsw + 8192), 16, 0, 0); } while (0)
; #define G_STAGE_B(bufoff, p, koff) do { \
;         __builtin_amdgcn_global_load_lds((const unsigned*)(gbase + (size_t)(unsigned)((p) + (koff) + voffB[0])), (LAS unsigned*)(lds + (bufoff) + ldsw), 16, 0, 0); \
;         __builtin_amdgcn_global_load_lds((const unsigned*)(gbase + (size_t)(unsigned)((p) + (koff) + voffB[1])), (LAS unsigned*)(lds + (bufoff) + ldsw + 8192), 16, 0, 0); } while (0)
; #define G_LDA(dst, b, h) do { _Pragma("unroll") for (int m = 0; m < 4; ++m) _Pragma("unroll") for (int k = 0; k < 2; ++k) dst[m][k] = *(const LAS bf16x8*)(lds + G_SA(b, h) + aoff + m * 2048 + k * 1024); } while (0)
; #define G_LDB(dst, b, h) do { _Pragma("unroll") for (int n = 0; n < 2; ++n) _Pragma("unroll") for (int k = 0; k < 2; ++k) dst[n][k] = *(const LAS bf16x8*)(lds + G_SB(b, h) + boff + n * 2048 + k * 1024); } while (0)
; #define G_MMA(ai, bj, At, Bt) do { __builtin_amdgcn_s_setprio(1); _Pragma("unroll") for (int m = 0; m < 4; ++m) _Pragma("unroll") for (int n = 0; n < 2; ++n) _Pragma("unroll") for (int k = 0; k < 2; ++k) \
;         acc[ai][bj][m][n] = __builtin_amdgcn_mfma_f32_16x16x32_bf16(Bt[n][k], At[m][k], acc[ai][bj][m][n], 0, 0, 0); __builtin_amdgcn_s_setprio(0); } while (0)
; template <class Epi>
; DI void gemm_phase(LAS unsigned char* lds, const Sched& S, const Epi& E, const int K) {
;     ...
;             G_LDB(B0, 0, 0); G_LDB(B1, 0, 1); G_SCHED; G_LDA(At, 0, 0); G_STAGE_A(G_SA(1, 1), cur.a2, cur.a3, k1);
;             G_WAIT_V(8); G_WAIT_L(0); G_BAR; G_MMA(0, 0, At, B0); G_MMA(0, 1, At, B1); G_BAR; G_SCHED;
;             G_LDA(At, 0, 1); G_STAGE_B(G_SB(0, 0), xb, kb2); G_STAGE_B(G_SB(0, 1), xb + hstepB, kb2); G_STAGE_A(G_SA(0, 0), x0, x1, k2);
;             G_WAIT_V(8); G_WAIT_L(0); G_BAR; G_MMA(1, 0, At, B0); G_MMA(1, 1, At, B1); G_BAR; G_SCHED;
;             G_LDB(B0, 1, 0); G_LDB(B1, 1, 1); G_SCHED; G_LDA(At, 1, 0); G_STAGE_A(G_SA(0, 1), x2, x3, k2);
;             G_WAIT_V(8); G_WAIT_L(0); G_BAR; G_MMA(0, 0, At, B0); G_MMA(0, 1, At, B1); G_BAR; G_SCHED;
.LBB0_261:
	s_add_i32 s12, s13, 0x8000
	v_add_u32_e32 v182, s12, v170
	v_add_u32_e32 v183, s12, v171
	s_add_i32 s12, s13, 0x2000
	v_add_u32_e32 v226, s12, v170
	v_add_u32_e32 v229, s12, v171
	s_add_i32 s12, s13, 0xa000
	v_add_u32_e32 v168, s13, v170
	v_add_u32_e32 v169, s13, v171
	v_add_u32_e32 v233, s12, v170
	v_add_u32_e32 v250, s12, v171
	s_add_i32 s12, 0, 0x10000
	s_add_i32 s13, 0, 0x14000
	v_add_u32_e32 v164, s12, v173
	v_add_u32_e32 v202, s13, v173
	ds_read_b128 v[152:155], v164
	ds_read_b128 v[156:159], v164 offset:1024
	ds_read_b128 v[160:163], v164 offset:2048
	ds_read_b128 v[164:167], v164 offset:3072
	ds_read_b128 v[178:181], v202
	ds_read_b128 v[194:197], v202 offset:1024
	ds_read_b128 v[198:201], v202 offset:2048
	ds_read_b128 v[202:205], v202 offset:3072
	s_add_i32 m0, s17, 0xc000
	ds_read_b128 v[206:209], v177
	ds_read_b128 v[210:213], v177 offset:1024
	ds_read_b128 v[214:217], v177 offset:2048
	ds_read_b128 v[218:221], v177 offset:3072
	ds_read_b128 v[222:225], v177 offset:4096
	ds_read_b128 v[234:237], v177 offset:5120
	ds_read_b128 v[242:245], v177 offset:6144
	ds_read_b128 v[246:249], v177 offset:7168
	global_load_lds_dwordx4 v[148:149], off
	s_add_i32 m0, s17, 0xe000
	s_nop 0
	global_load_lds_dwordx4 v[150:151], off
	s_waitcnt vmcnt(8) lgkmcnt(0)
	s_barrier
	s_setprio 1
	v_mfma_f32_16x16x32_bf16 v[124:127], v[152:155], v[206:209], v[124:127]
	v_mfma_f32_16x16x32_bf16 v[120:123], v[160:163], v[206:209], v[120:123]
	v_mfma_f32_16x16x32_bf16 v[116:119], v[152:155], v[214:217], v[116:119]
	v_mfma_f32_16x16x32_bf16 v[112:115], v[160:163], v[214:217], v[112:115]
	v_mfma_f32_16x16x32_bf16 v[108:111], v[152:155], v[222:225], v[108:111]
	v_mfma_f32_16x16x32_bf16 v[104:107], v[160:163], v[222:225], v[104:107]
	v_mfma_f32_16x16x32_bf16 v[100:103], v[152:155], v[242:245], v[100:103]
	v_mfma_f32_16x16x32_bf16 v[96:99], v[160:163], v[242:245], v[96:99]
	v_mfma_f32_16x16x32_bf16 v[124:127], v[156:159], v[210:213], v[124:127]
	v_mfma_f32_16x16x32_bf16 v[120:123], v[164:167], v[210:213], v[120:123]
	v_mfma_f32_16x16x32_bf16 v[116:119], v[156:159], v[218:221], v[116:119]
	v_mfma_f32_16x16x32_bf16 v[112:115], v[164:167], v[218:221], v[112:115]
	v_mfma_f32_16x16x32_bf16 v[108:111], v[156:159], v[234:237], v[108:111]
	v_mfma_f32_16x16x32_bf16 v[104:107], v[164:167], v[234:237], v[104:107]
	v_mfma_f32_16x16x32_bf16 v[100:103], v[156:159], v[246:249], v[100:103]
	v_mfma_f32_16x16x32_bf16 v[96:99], v[164:167], v[246:249], v[96:99]
	v_mfma_f32_16x16x32_bf16 v[92:95], v[178:181], v[206:209], v[92:95]
	v_mfma_f32_16x16x32_bf16 v[88:91], v[198:201], v[206:209], v[88:91]
	v_mfma_f32_16x16x32_bf16 v[84:87], v[178:181], v[214:217], v[84:87]
	v_mfma_f32_16x16x32_bf16 v[80:83], v[198:201], v[214:217], v[80:83]
	v_mfma_f32_16x16x32_bf16 v[76:79], v[178:181], v[222:225], v[76:79]
	v_mfma_f32_16x16x32_bf16 v[72:75], v[198:201], v[222:225], v[72:75]
	v_mfma_f32_16x16x32_bf16 v[68:71], v[178:181], v[242:245], v[68:71]
	v_mfma_f32_16x16x32_bf16 v[64:67], v[198:201], v[242:245], v[64:67]
	v_mfma_f32_16x16x32_bf16 v[92:95], v[194:197], v[210:213], v[92:95]
	v_mfma_f32_16x16x32_bf16 v[88:91], v[202:205], v[210:213], v[88:91]
	v_mfma_f32_16x16x32_bf16 v[84:87], v[194:197], v[218:221], v[84:87]
	v_mfma_f32_16x16x32_bf16 v[80:83], v[202:205], v[218:221], v[80:83]
	v_mfma_f32_16x16x32_bf16 v[76:79], v[194:197], v[234:237], v[76:79]
	v_mfma_f32_16x16x32_bf16 v[72:75], v[202:205], v[234:237], v[72:75]
	v_mfma_f32_16x16x32_bf16 v[68:71], v[194:197], v[246:249], v[68:71]
	v_mfma_f32_16x16x32_bf16 v[64:67], v[202:205], v[246:249], v[64:67]
	s_setprio 0
	s_barrier
	s_add_i32 s12, s12, s16
	s_mov_b32 m0, s12
	ds_read_b128 v[206:209], v177 offset:16384
	ds_read_b128 v[210:213], v177 offset:17408
	ds_read_b128 v[214:217], v177 offset:18432
	ds_read_b128 v[218:221], v177 offset:19456
	ds_read_b128 v[222:225], v177 offset:20480
	ds_read_b128 v[234:237], v177 offset:21504
	ds_read_b128 v[242:245], v177 offset:22528
	ds_read_b128 v[246:249], v177 offset:23552
	global_load_lds_dwordx4 v168, s[82:83]
	s_add_i32 m0, s12, 0x2000
	s_add_i32 s12, s13, s16
	global_load_lds_dwordx4 v169, s[82:83]
	s_mov_b32 m0, s12
	s_nop 0
	global_load_lds_dwordx4 v182, s[82:83]
	s_add_i32 m0, s12, 0x2000
	s_nop 0
	global_load_lds_dwordx4 v183, s[82:83]
	s_mov_b32 m0, s17
	s_nop 0
	global_load_lds_dwordx4 v[128:129], off
	s_mov_b32 m0, s18
	s_nop 0
	global_load_lds_dwordx4 v[130:131], off
	s_waitcnt vmcnt(8) lgkmcnt(0)
	s_barrier
	s_setprio 1
	v_mfma_f32_16x16x32_bf16 v[60:63], v[152:155], v[206:209], v[60:63]
	v_mfma_f32_16x16x32_bf16 v[56:59], v[160:163], v[206:209], v[56:59]
	v_mfma_f32_16x16x32_bf16 v[52:55], v[152:155], v[214:217], v[52:55]
	v_mfma_f32_16x16x32_bf16 v[48:51], v[160:163], v[214:217], v[48:51]
	v_mfma_f32_16x16x32_bf16 v[44:47], v[152:155], v[222:225], v[44:47]
	v_mfma_f32_16x16x32_bf16 v[40:43], v[160:163], v[222:225], v[40:43]
	v_mfma_f32_16x16x32_bf16 v[36:39], v[152:155], v[242:245], v[36:39]
	v_mfma_f32_16x16x32_bf16 v[32:35], v[160:163], v[242:245], v[32:35]
	v_mfma_f32_16x16x32_bf16 v[60:63], v[156:159], v[210:213], v[60:63]
	v_mfma_f32_16x16x32_bf16 v[56:59], v[164:167], v[210:213], v[56:59]
	v_mfma_f32_16x16x32_bf16 v[52:55], v[156:159], v[218:221], v[52:55]
	v_mfma_f32_16x16x32_bf16 v[48:51], v[164:167], v[218:221], v[48:51]
	v_mfma_f32_16x16x32_bf16 v[44:47], v[156:159], v[234:237], v[44:47]
	v_mfma_f32_16x16x32_bf16 v[40:43], v[164:167], v[234:237], v[40:43]
	v_mfma_f32_16x16x32_bf16 v[36:39], v[156:159], v[246:249], v[36:39]
	v_mfma_f32_16x16x32_bf16 v[32:35], v[164:167], v[246:249], v[32:35]
	v_mfma_f32_16x16x32_bf16 v[28:31], v[178:181], v[206:209], v[28:31]
	v_mfma_f32_16x16x32_bf16 v[24:27], v[198:201], v[206:209], v[24:27]
	v_mfma_f32_16x16x32_bf16 v[20:23], v[178:181], v[214:217], v[20:23]
	v_mfma_f32_16x16x32_bf16 v[16:19], v[198:201], v[214:217], v[16:19]
	v_mfma_f32_16x16x32_bf16 v[12:15], v[178:181], v[222:225], v[12:15]
	v_mfma_f32_16x16x32_bf16 v[8:11], v[198:201], v[222:225], v[8:11]
	v_mfma_f32_16x16x32_bf16 v[4:7], v[178:181], v[242:245], v[4:7]
	v_mfma_f32_16x16x32_bf16 v[0:3], v[198:201], v[242:245], v[0:3]
	v_mfma_f32_16x16x32_bf16 v[28:31], v[194:197], v[210:213], v[28:31]
	v_mfma_f32_16x16x32_bf16 v[24:27], v[202:205], v[210:213], v[24:27]
	v_mfma_f32_16x16x32_bf16 v[20:23], v[194:197], v[218:221], v[20:23]
	v_mfma_f32_16x16x32_bf16 v[16:19], v[202:205], v[218:221], v[16:19]
	v_mfma_f32_16x16x32_bf16 v[12:15], v[194:197], v[234:237], v[12:15]
	v_mfma_f32_16x16x32_bf16 v[8:11], v[202:205], v[234:237], v[8:11]
	v_mfma_f32_16x16x32_bf16 v[4:7], v[194:197], v[246:249], v[4:7]
	v_mfma_f32_16x16x32_bf16 v[0:3], v[202:205], v[246:249], v[0:3]
	s_setprio 0
	s_barrier
; #define G_STAGE_A(bufoff, p0, p1, koff) do { \
;         __builtin_amdgcn_global_load_lds((const unsigned*)(gbase + (size_t)(unsigned)((p0) + (koff) + voffA[0])), (LAS unsigned*)(lds + (bufoff) + ldsw), 16, 0, 0); \
;         __builtin_amdgcn_global_load_lds((const unsigned*)(gbase + (size_t)(unsigned)((p1) + (koff) + voffA[1])), (LAS unsigned*)(lds + (bufoff) + ldsw + 8192), 16, 0, 0); } while (0)
; #define G_STAGE_B(bufoff, p, koff) do { \
;         __builtin_amdgcn_global_load_lds((const unsigned*)(gbase + (size_t)(unsigned)((p) + (koff) + voffB[0])), (LAS unsigned*)(lds + (bufoff) + ldsw), 16, 0, 0); \
;         __builtin_amdgcn_global_load_lds((const unsigned*)(gbase + (size_t)(unsigned)((p) + (koff) + voffB[1])), (LAS unsigned*)(lds + (bufoff) + ldsw + 8192), 16, 0, 0); } while (0)
; #define G_LDA(dst, b, h) do { _Pragma("unroll") for (int m = 0; m < 4; ++m) _Pragma("unroll") for (int k = 0; k < 2; ++k) dst[m][k] = *(const LAS bf16x8*)(lds + G_SA(b, h) + aoff + m * 2048 + k * 1024); } while (0)
; #define G_LDB(dst, b, h) do { _Pragma("unroll") for (int n = 0; n < 2; ++n) _Pragma("unroll") for (int k = 0; k < 2; ++k) dst[n][k] = *(const LAS bf16x8*)(lds + G_SB(b, h) + boff + n * 2048 + k * 1024); } while (0)
; #define G_MMA(ai, bj, At, Bt) do { __builtin_amdgcn_s_setprio(1); _Pragma("unroll") for (int m = 0; m < 4; ++m) _Pragma("unroll") for (int n = 0; n < 2; ++n) _Pragma("unroll") for (int k = 0; k < 2; ++k) \
;         acc[ai][bj][m][n] = __builtin_amdgcn_mfma_f32_16x16x32_bf16(Bt[n][k], At[m][k], acc[ai][bj][m][n], 0, 0, 0); __builtin_amdgcn_s_setprio(0); } while (0)
; #define G_WAIT_V(n) asm volatile("s_waitcnt vmcnt(" #n ")" ::: "memory")
; #define G_WAIT_L(n) asm volatile("s_waitcnt lgkmcnt(" #n ")" ::: "memory")
; #define G_BAR __builtin_amdgcn_s_barrier()
; template <class Epi>
; DI void gemm_phase(LAS unsigned char* lds, const Sched& S, const Epi& E, const int K) {
;     ...
;             G_LDB(B0, 1, 0); G_LDB(B1, 1, 1); G_SCHED; G_LDA(At, 1, 0); G_STAGE_A(G_SA(0, 1), x2, x3, k2);
;             G_WAIT_V(8); G_WAIT_L(0); G_BAR; G_MMA(0, 0, At, B0); G_MMA(0, 1, At, B1); G_BAR; G_SCHED;
;             G_LDA(At, 1, 1); G_STAGE_B(G_SB(1, 0), xb, kb3); G_STAGE_B(G_SB(1, 1), xb + hstepB, kb3); G_STAGE_A(G_SA(1, 0), x0, x1, k3);
;             G_WAIT_V(8); G_WAIT_L(0); G_BAR; G_MMA(1, 0, At, B0); G_MMA(1, 1, At, B1); G_BAR; G_SCHED;
	s_add_i32 s12, 0, 0x18000
	s_add_i32 s13, 0, 0x1c000
	v_add_u32_e32 v164, s12, v173
	v_add_u32_e32 v168, s13, v173
	ds_read_b128 v[152:155], v164
	ds_read_b128 v[156:159], v164 offset:1024
	ds_read_b128 v[160:163], v164 offset:2048
	ds_read_b128 v[164:167], v164 offset:3072
	ds_read_b128 v[178:181], v168
	ds_read_b128 v[194:197], v168 offset:1024
	ds_read_b128 v[198:201], v168 offset:2048
	ds_read_b128 v[202:205], v168 offset:3072
	s_mov_b32 m0, s19
	ds_read_b128 v[206:209], v177 offset:32768
	ds_read_b128 v[210:213], v177 offset:33792
	ds_read_b128 v[214:217], v177 offset:34816
	ds_read_b128 v[218:221], v177 offset:35840
	ds_read_b128 v[222:225], v177 offset:36864
	ds_read_b128 v[234:237], v177 offset:37888
	ds_read_b128 v[242:245], v177 offset:38912
	ds_read_b128 v[246:249], v177 offset:39936
	global_load_lds_dwordx4 v[132:133], off
	s_mov_b32 m0, s20
	s_nop 0
	global_load_lds_dwordx4 v[134:135], off
	s_waitcnt vmcnt(8) lgkmcnt(0)
	s_barrier
	s_setprio 1
	v_mfma_f32_16x16x32_bf16 v[124:127], v[152:155], v[206:209], v[124:127]
	v_mfma_f32_16x16x32_bf16 v[120:123], v[160:163], v[206:209], v[120:123]
	v_mfma_f32_16x16x32_bf16 v[116:119], v[152:155], v[214:217], v[116:119]
	v_mfma_f32_16x16x32_bf16 v[112:115], v[160:163], v[214:217], v[112:115]
	v_mfma_f32_16x16x32_bf16 v[108:111], v[152:155], v[222:225], v[108:111]
	v_mfma_f32_16x16x32_bf16 v[104:107], v[160:163], v[222:225], v[104:107]
	v_mfma_f32_16x16x32_bf16 v[100:103], v[152:155], v[242:245], v[100:103]
	v_mfma_f32_16x16x32_bf16 v[96:99], v[160:163], v[242:245], v[96:99]
	v_mfma_f32_16x16x32_bf16 v[124:127], v[156:159], v[210:213], v[124:127]
	v_mfma_f32_16x16x32_bf16 v[120:123], v[164:167], v[210:213], v[120:123]
	v_mfma_f32_16x16x32_bf16 v[116:119], v[156:159], v[218:221], v[116:119]
	v_mfma_f32_16x16x32_bf16 v[112:115], v[164:167], v[218:221], v[112:115]
	v_mfma_f32_16x16x32_bf16 v[108:111], v[156:159], v[234:237], v[108:111]
	v_mfma_f32_16x16x32_bf16 v[104:107], v[164:167], v[234:237], v[104:107]
	v_mfma_f32_16x16x32_bf16 v[100:103], v[156:159], v[246:249], v[100:103]
	v_mfma_f32_16x16x32_bf16 v[96:99], v[164:167], v[246:249], v[96:99]
	v_mfma_f32_16x16x32_bf16 v[92:95], v[178:181], v[206:209], v[92:95]
	v_mfma_f32_16x16x32_bf16 v[88:91], v[198:201], v[206:209], v[88:91]
	v_mfma_f32_16x16x32_bf16 v[84:87], v[178:181], v[214:217], v[84:87]
	v_mfma_f32_16x16x32_bf16 v[80:83], v[198:201], v[214:217], v[80:83]
	v_mfma_f32_16x16x32_bf16 v[76:79], v[178:181], v[222:225], v[76:79]
	v_mfma_f32_16x16x32_bf16 v[72:75], v[198:201], v[222:225], v[72:75]
	v_mfma_f32_16x16x32_bf16 v[68:71], v[178:181], v[242:245], v[68:71]
	v_mfma_f32_16x16x32_bf16 v[64:67], v[198:201], v[242:245], v[64:67]
	v_mfma_f32_16x16x32_bf16 v[92:95], v[194:197], v[210:213], v[92:95]
	v_mfma_f32_16x16x32_bf16 v[88:91], v[202:205], v[210:213], v[88:91]
	v_mfma_f32_16x16x32_bf16 v[84:87], v[194:197], v[218:221], v[84:87]
	v_mfma_f32_16x16x32_bf16 v[80:83], v[202:205], v[218:221], v[80:83]
	v_mfma_f32_16x16x32_bf16 v[76:79], v[194:197], v[234:237], v[76:79]
	v_mfma_f32_16x16x32_bf16 v[72:75], v[202:205], v[234:237], v[72:75]
	v_mfma_f32_16x16x32_bf16 v[68:71], v[194:197], v[246:249], v[68:71]
	v_mfma_f32_16x16x32_bf16 v[64:67], v[202:205], v[246:249], v[64:67]
	s_setprio 0
	s_barrier
	s_add_i32 s12, s12, s16
	s_mov_b32 m0, s12
	ds_read_b128 v[206:209], v177 offset:49152
	ds_read_b128 v[210:213], v177 offset:50176
	ds_read_b128 v[214:217], v177 offset:51200
	ds_read_b128 v[218:221], v177 offset:52224
	ds_read_b128 v[222:225], v177 offset:53248
	ds_read_b128 v[234:237], v177 offset:54272
	ds_read_b128 v[242:245], v177 offset:55296
	ds_read_b128 v[246:249], v177 offset:56320
	global_load_lds_dwordx4 v226, s[82:83]
	s_add_i32 m0, s12, 0x2000
	s_add_i32 s12, s13, s16
	global_load_lds_dwordx4 v229, s[82:83]
	s_mov_b32 m0, s12
	s_nop 0
	global_load_lds_dwordx4 v233, s[82:83]
	s_add_i32 m0, s12, 0x2000
	s_nop 0
	global_load_lds_dwordx4 v250, s[82:83]
	s_mov_b32 m0, s21
	s_nop 0
	global_load_lds_dwordx4 v[136:137], off
	s_mov_b32 m0, s24
	s_nop 0
	global_load_lds_dwordx4 v[138:139], off
	s_waitcnt vmcnt(8) lgkmcnt(0)
	s_barrier
	s_setprio 1
	v_mfma_f32_16x16x32_bf16 v[60:63], v[152:155], v[206:209], v[60:63]
	v_mfma_f32_16x16x32_bf16 v[56:59], v[160:163], v[206:209], v[56:59]
	v_mfma_f32_16x16x32_bf16 v[52:55], v[152:155], v[214:217], v[52:55]
	v_mfma_f32_16x16x32_bf16 v[48:51], v[160:163], v[214:217], v[48:51]
	v_mfma_f32_16x16x32_bf16 v[44:47], v[152:155], v[222:225], v[44:47]
	v_mfma_f32_16x16x32_bf16 v[40:43], v[160:163], v[222:225], v[40:43]
	v_mfma_f32_16x16x32_bf16 v[36:39], v[152:155], v[242:245], v[36:39]
	v_mfma_f32_16x16x32_bf16 v[32:35], v[160:163], v[242:245], v[32:35]
	v_mfma_f32_16x16x32_bf16 v[60:63], v[156:159], v[210:213], v[60:63]
	v_mfma_f32_16x16x32_bf16 v[56:59], v[164:167], v[210:213], v[56:59]
	v_mfma_f32_16x16x32_bf16 v[52:55], v[156:159], v[218:221], v[52:55]
	v_mfma_f32_16x16x32_bf16 v[48:51], v[164:167], v[218:221], v[48:51]
	v_mfma_f32_16x16x32_bf16 v[44:47], v[156:159], v[234:237], v[44:47]
	v_mfma_f32_16x16x32_bf16 v[40:43], v[164:167], v[234:237], v[40:43]
	v_mfma_f32_16x16x32_bf16 v[36:39], v[156:159], v[246:249], v[36:39]
	v_mfma_f32_16x16x32_bf16 v[32:35], v[164:167], v[246:249], v[32:35]
	v_mfma_f32_16x16x32_bf16 v[28:31], v[178:181], v[206:209], v[28:31]
	v_mfma_f32_16x16x32_bf16 v[24:27], v[198:201], v[206:209], v[24:27]
	v_mfma_f32_16x16x32_bf16 v[20:23], v[178:181], v[214:217], v[20:23]
	v_mfma_f32_16x16x32_bf16 v[16:19], v[198:201], v[214:217], v[16:19]
	v_mfma_f32_16x16x32_bf16 v[12:15], v[178:181], v[222:225], v[12:15]
	v_mfma_f32_16x16x32_bf16 v[8:11], v[198:201], v[222:225], v[8:11]
	v_mfma_f32_16x16x32_bf16 v[4:7], v[178:181], v[242:245], v[4:7]
	v_mfma_f32_16x16x32_bf16 v[0:3], v[198:201], v[242:245], v[0:3]
	v_mfma_f32_16x16x32_bf16 v[28:31], v[194:197], v[210:213], v[28:31]
	v_mfma_f32_16x16x32_bf16 v[24:27], v[202:205], v[210:213], v[24:27]
	v_mfma_f32_16x16x32_bf16 v[20:23], v[194:197], v[218:221], v[20:23]
	v_mfma_f32_16x16x32_bf16 v[16:19], v[202:205], v[218:221], v[16:19]
	v_mfma_f32_16x16x32_bf16 v[12:15], v[194:197], v[234:237], v[12:15]
	v_mfma_f32_16x16x32_bf16 v[8:11], v[202:205], v[234:237], v[8:11]
	v_mfma_f32_16x16x32_bf16 v[4:7], v[194:197], v[246:249], v[4:7]
	v_mfma_f32_16x16x32_bf16 v[0:3], v[202:205], v[246:249], v[0:3]
	s_setprio 0
	s_barrier
; DI u32x4 pack8(const f32x4& v0, const f32x4& v1) { u32x4 w; w.x = pk2(v0[0], v0[1]); w.y = pk2(v0[2], v0[3]); w.z = pk2(v1[0], v1[1]); w.w = pk2(v1[2], v1[3]); return w; }
;     DI void operator()(const f32x4 (&acc)[2][2][4][2], const Unit& u, int wr, int wc, int fr, int fq) const {
;         if (wr != 0) return;
; #pragma unroll
;         for (int m = 0; m < 4; ++m) {
;             const int k1 = 16 * m + fr;
; #pragma unroll
;             for (int bj = 0; bj < 2; ++bj) {
;                 const int j0 = 128 * bj + 32 * wc + 8 * fq, ge = 4 * u.pn + (j0 >> 6), nl0 = j0 & 63;
;                 const f32x4* tw = (const f32x4*)(TW + (size_t)(k1 * 64 + nl0) * 2);
;                 f32x4 yr[2], yi[2];
; #pragma unroll
;                 for (int n = 0; n < 2; ++n) {
;                     const f32x4 t0 = tw[2 * n], t1 = tw[2 * n + 1];
;                     const f32x4 c = {t0.x, t0.z, t1.x, t1.z}, s = {t0.y, t0.w, t1.y, t1.w};
;                     const f32x4 r = acc[0][bj][m][n], i = acc[1][bj][m][n];
;                     yr[n] = c * r + s * i; yi[n] = c * i - s * r;
;                 }
;                 bf16_t* dst = YP + ((((size_t)(u.z * 64 + k1)) * 1024 + ge) * 2) * 64 + nl0;
;                 *(u32x4*)dst = pack8(yr[0], yr[1]); *(u32x4*)(dst + 64) = pack8(yi[0], yi[1]);
	s_andn2_b64 vcc, exec, s[10:11]
	s_cbranch_vccnz .LBB0_263
	s_lshl_b32 s44, s26, 6
	v_or_b32_e32 v152, s44, v172
	v_ashrrev_i32_e32 v153, 31, v152
	s_barrier
	v_lshlrev_b64 v[182:183], 18, v[152:153]
	global_load_dwordx4 v[178:181], v[140:141], off offset:32
	global_load_dwordx4 v[162:165], v[140:141], off offset:48
	global_load_dwordx4 v[152:155], v[140:141], off
	global_load_dwordx4 v[156:159], v[140:141], off offset:16
	s_lshl_b32 s12, s27, 2
	s_or_b32 s14, s12, s25
	v_readlane_b32 s46, v254, 39
	s_ashr_i32 s15, s14, 31
	v_readlane_b32 s47, v254, 40
	s_lshl_b64 s[12:13], s[14:15], 8
	s_or_b32 s14, s14, 2
	s_ashr_i32 s15, s14, 31
	s_lshl_b64 s[14:15], s[14:15], 8
	s_waitcnt vmcnt(0)
	v_mov_b32_e32 v168, v153
	v_mov_b32_e32 v166, v157
	v_mov_b32_e32 v167, v159
	v_mov_b32_e32 v169, v155
	v_pk_mul_f32 v[160:161], v[62:63], v[166:167]
	v_pk_mul_f32 v[194:195], v[60:61], v[168:169]
	v_mov_b32_e32 v157, v158
	v_mov_b32_e32 v153, v154
	v_pk_mul_f32 v[154:155], v[126:127], v[166:167]
	v_pk_mul_f32 v[166:167], v[124:125], v[168:169]
	v_pk_fma_f32 v[158:159], v[126:127], v[156:157], v[160:161]
	v_pk_fma_f32 v[160:161], v[124:125], v[152:153], v[194:195]
	v_pk_fma_f32 v[154:155], v[62:63], v[156:157], v[154:155] neg_lo:[0,0,1] neg_hi:[0,0,1]
	v_pk_fma_f32 v[156:157], v[60:61], v[152:153], v[166:167] neg_lo:[0,0,1] neg_hi:[0,0,1]
	v_mov_b32_e32 v152, v163
	v_mov_b32_e32 v153, v165
	v_pk_mul_f32 v[166:167], v[58:59], v[152:153]
	v_mov_b32_e32 v194, v179
	v_mov_b32_e32 v195, v181
	v_mov_b32_e32 v163, v164
	v_pk_mul_f32 v[152:153], v[122:123], v[152:153]
	v_pk_mul_f32 v[168:169], v[56:57], v[194:195]
	v_pk_fma_f32 v[166:167], v[122:123], v[162:163], v[166:167]
	v_mov_b32_e32 v179, v180
	v_pk_mul_f32 v[164:165], v[120:121], v[194:195]
	v_pk_fma_f32 v[162:163], v[58:59], v[162:163], v[152:153] neg_lo:[0,0,1] neg_hi:[0,0,1]
	v_lshl_add_u64 v[152:153], s[46:47], 0, v[182:183]
	v_pk_fma_f32 v[168:169], v[120:121], v[178:179], v[168:169]
	v_pk_fma_f32 v[164:165], v[56:57], v[178:179], v[164:165] neg_lo:[0,0,1] neg_hi:[0,0,1]
	v_lshl_add_u64 v[178:179], v[152:153], 0, s[12:13]
	v_lshl_add_u64 v[182:183], v[178:179], 0, v[184:185]
	v_cvt_pk_bf16_f32 v178, v160, v161
	v_cvt_pk_bf16_f32 v179, v158, v159
	v_cvt_pk_bf16_f32 v180, v168, v169
	v_cvt_pk_bf16_f32 v181, v166, v167
	v_cvt_pk_bf16_f32 v156, v156, v157
	v_cvt_pk_bf16_f32 v157, v154, v155
	v_cvt_pk_bf16_f32 v158, v164, v165
	v_cvt_pk_bf16_f32 v159, v162, v163
	global_store_dwordx4 v[182:183], v[178:181], off
	global_store_dwordx4 v[182:183], v[156:159], off offset:128
	global_load_dwordx4 v[178:181], v[140:141], off offset:32
	s_nop 0
	global_load_dwordx4 v[162:165], v[140:141], off offset:48
	global_load_dwordx4 v[166:169], v[140:141], off
	global_load_dwordx4 v[154:157], v[140:141], off offset:16
	v_lshl_add_u64 v[152:153], v[152:153], 0, s[14:15]
	s_waitcnt vmcnt(1)
	v_mov_b32_e32 v194, v167
	s_waitcnt vmcnt(0)
	v_mov_b32_e32 v182, v155
	v_mov_b32_e32 v183, v157
	v_mov_b32_e32 v195, v169
	v_pk_mul_f32 v[158:159], v[30:31], v[182:183]
	v_pk_mul_f32 v[160:161], v[28:29], v[194:195]
	v_mov_b32_e32 v155, v156
	v_mov_b32_e32 v167, v168
	v_pk_mul_f32 v[156:157], v[94:95], v[182:183]
	v_pk_mul_f32 v[168:169], v[92:93], v[194:195]
	v_mov_b32_e32 v182, v163
	v_mov_b32_e32 v183, v165
	v_mov_b32_e32 v194, v179
	v_mov_b32_e32 v195, v181
	v_pk_fma_f32 v[158:159], v[94:95], v[154:155], v[158:159]
	v_pk_fma_f32 v[160:161], v[92:93], v[166:167], v[160:161]
	v_pk_fma_f32 v[154:155], v[30:31], v[154:155], v[156:157] neg_lo:[0,0,1] neg_hi:[0,0,1]
	v_pk_fma_f32 v[156:157], v[28:29], v[166:167], v[168:169] neg_lo:[0,0,1] neg_hi:[0,0,1]
	v_pk_mul_f32 v[166:167], v[26:27], v[182:183]
	v_mov_b32_e32 v163, v164
	v_mov_b32_e32 v179, v180
	v_pk_mul_f32 v[164:165], v[90:91], v[182:183]
	v_pk_mul_f32 v[180:181], v[88:89], v[194:195]
	v_pk_mul_f32 v[168:169], v[24:25], v[194:195]
	v_pk_fma_f32 v[166:167], v[90:91], v[162:163], v[166:167]
	v_pk_fma_f32 v[162:163], v[26:27], v[162:163], v[164:165] neg_lo:[0,0,1] neg_hi:[0,0,1]
	v_pk_fma_f32 v[164:165], v[24:25], v[178:179], v[180:181] neg_lo:[0,0,1] neg_hi:[0,0,1]
	v_pk_fma_f32 v[168:169], v[88:89], v[178:179], v[168:169]
	v_lshl_add_u64 v[182:183], v[152:153], 0, v[184:185]
	v_cvt_pk_bf16_f32 v152, v156, v157
	v_cvt_pk_bf16_f32 v153, v154, v155
	v_cvt_pk_bf16_f32 v154, v164, v165
	v_cvt_pk_bf16_f32 v155, v162, v163
	v_cvt_pk_bf16_f32 v178, v160, v161
	v_cvt_pk_bf16_f32 v179, v158, v159
	v_cvt_pk_bf16_f32 v180, v168, v169
	v_cvt_pk_bf16_f32 v181, v166, v167
	global_store_dwordx4 v[182:183], v[152:155], off offset:128
	global_store_dwordx4 v[182:183], v[178:181], off
	s_nop 0
	v_or_b32_e32 v152, s44, v174
	v_ashrrev_i32_e32 v153, 31, v152
	v_lshlrev_b64 v[182:183], 18, v[152:153]
	global_load_dwordx4 v[178:181], v[142:143], off offset:32
	global_load_dwordx4 v[162:165], v[142:143], off offset:48
	global_load_dwordx4 v[152:155], v[142:143], off
	global_load_dwordx4 v[156:159], v[142:143], off offset:16
	s_waitcnt vmcnt(1)
	v_mov_b32_e32 v168, v153
	s_waitcnt vmcnt(0)
; DI u32x4 pack8(const f32x4& v0, const f32x4& v1) { u32x4 w; w.x = pk2(v0[0], v0[1]); w.y = pk2(v0[2], v0[3]); w.z = pk2(v1[0], v1[1]); w.w = pk2(v1[2], v1[3]); return w; }
;     DI void operator()(const f32x4 (&acc)[2][2][4][2], const Unit& u, int wr, int wc, int fr, int fq) const {
;     ...
;         for (int m = 0; m < 4; ++m) {
;             const int k1 = 16 * m + fr;
; #pragma unroll
;             for (int bj = 0; bj < 2; ++bj) {
;                 const int j0 = 128 * bj + 32 * wc + 8 * fq, ge = 4 * u.pn + (j0 >> 6), nl0 = j0 & 63;
;                 const f32x4* tw = (const f32x4*)(TW + (size_t)(k1 * 64 + nl0) * 2);
;                 f32x4 yr[2], yi[2];
; #pragma unroll
;                 for (int n = 0; n < 2; ++n) {
;                     const f32x4 t0 = tw[2 * n], t1 = tw[2 * n + 1];
;                     const f32x4 c = {t0.x, t0.z, t1.x, t1.z}, s = {t0.y, t0.w, t1.y, t1.w};
;                     const f32x4 r = acc[0][bj][m][n], i = acc[1][bj][m][n];
;                     yr[n] = c * r + s * i; yi[n] = c * i - s * r;
;                 }
;                 bf16_t* dst = YP + ((((size_t)(u.z * 64 + k1)) * 1024 + ge) * 2) * 64 + nl0;
;                 *(u32x4*)dst = pack8(yr[0], yr[1]); *(u32x4*)(dst + 64) = pack8(yi[0], yi[1]);
	v_mov_b32_e32 v166, v157
	v_mov_b32_e32 v167, v159
	v_mov_b32_e32 v169, v155
	v_pk_mul_f32 v[160:161], v[54:55], v[166:167]
	v_pk_mul_f32 v[194:195], v[52:53], v[168:169]
	v_mov_b32_e32 v157, v158
	v_mov_b32_e32 v153, v154
	v_pk_mul_f32 v[154:155], v[118:119], v[166:167]
	v_pk_mul_f32 v[166:167], v[116:117], v[168:169]
	v_pk_fma_f32 v[158:159], v[118:119], v[156:157], v[160:161]
	v_pk_fma_f32 v[160:161], v[116:117], v[152:153], v[194:195]
	v_pk_fma_f32 v[154:155], v[54:55], v[156:157], v[154:155] neg_lo:[0,0,1] neg_hi:[0,0,1]
	v_pk_fma_f32 v[156:157], v[52:53], v[152:153], v[166:167] neg_lo:[0,0,1] neg_hi:[0,0,1]
	v_mov_b32_e32 v152, v163
	v_mov_b32_e32 v153, v165
	v_pk_mul_f32 v[166:167], v[50:51], v[152:153]
	v_mov_b32_e32 v194, v179
	v_mov_b32_e32 v195, v181
	v_mov_b32_e32 v163, v164
	v_pk_mul_f32 v[152:153], v[114:115], v[152:153]
	v_pk_mul_f32 v[168:169], v[48:49], v[194:195]
	v_pk_fma_f32 v[166:167], v[114:115], v[162:163], v[166:167]
	v_mov_b32_e32 v179, v180
	v_pk_mul_f32 v[164:165], v[112:113], v[194:195]
	v_pk_fma_f32 v[162:163], v[50:51], v[162:163], v[152:153] neg_lo:[0,0,1] neg_hi:[0,0,1]
	v_lshl_add_u64 v[152:153], s[46:47], 0, v[182:183]
	v_pk_fma_f32 v[168:169], v[112:113], v[178:179], v[168:169]
	v_pk_fma_f32 v[164:165], v[48:49], v[178:179], v[164:165] neg_lo:[0,0,1] neg_hi:[0,0,1]
	v_lshl_add_u64 v[178:179], v[152:153], 0, s[12:13]
	v_lshl_add_u64 v[182:183], v[178:179], 0, v[184:185]
	v_cvt_pk_bf16_f32 v178, v160, v161
	v_cvt_pk_bf16_f32 v179, v158, v159
	v_cvt_pk_bf16_f32 v180, v168, v169
	v_cvt_pk_bf16_f32 v181, v166, v167
	v_cvt_pk_bf16_f32 v156, v156, v157
	v_cvt_pk_bf16_f32 v157, v154, v155
	v_cvt_pk_bf16_f32 v158, v164, v165
	v_cvt_pk_bf16_f32 v159, v162, v163
	global_store_dwordx4 v[182:183], v[178:181], off
	global_store_dwordx4 v[182:183], v[156:159], off offset:128
	global_load_dwordx4 v[178:181], v[142:143], off offset:32
	s_nop 0
	global_load_dwordx4 v[162:165], v[142:143], off offset:48
	global_load_dwordx4 v[166:169], v[142:143], off
	global_load_dwordx4 v[154:157], v[142:143], off offset:16
	v_lshl_add_u64 v[152:153], v[152:153], 0, s[14:15]
	s_waitcnt vmcnt(1)
	v_mov_b32_e32 v194, v167
	s_waitcnt vmcnt(0)
	v_mov_b32_e32 v182, v155
	v_mov_b32_e32 v183, v157
	v_mov_b32_e32 v195, v169
	v_pk_mul_f32 v[158:159], v[22:23], v[182:183]
	v_pk_mul_f32 v[160:161], v[20:21], v[194:195]
	v_mov_b32_e32 v155, v156
	v_mov_b32_e32 v167, v168
	v_pk_mul_f32 v[156:157], v[86:87], v[182:183]
	v_pk_mul_f32 v[168:169], v[84:85], v[194:195]
	v_mov_b32_e32 v182, v163
	v_mov_b32_e32 v183, v165
	v_mov_b32_e32 v194, v179
	v_mov_b32_e32 v195, v181
	v_pk_fma_f32 v[158:159], v[86:87], v[154:155], v[158:159]
	v_pk_fma_f32 v[160:161], v[84:85], v[166:167], v[160:161]
	v_pk_fma_f32 v[154:155], v[22:23], v[154:155], v[156:157] neg_lo:[0,0,1] neg_hi:[0,0,1]
	v_pk_fma_f32 v[156:157], v[20:21], v[166:167], v[168:169] neg_lo:[0,0,1] neg_hi:[0,0,1]
	v_pk_mul_f32 v[166:167], v[18:19], v[182:183]
	v_mov_b32_e32 v163, v164
	v_mov_b32_e32 v179, v180
	v_pk_mul_f32 v[164:165], v[82:83], v[182:183]
	v_pk_mul_f32 v[180:181], v[80:81], v[194:195]
	v_pk_mul_f32 v[168:169], v[16:17], v[194:195]
	v_pk_fma_f32 v[166:167], v[82:83], v[162:163], v[166:167]
	v_pk_fma_f32 v[162:163], v[18:19], v[162:163], v[164:165] neg_lo:[0,0,1] neg_hi:[0,0,1]
	v_pk_fma_f32 v[164:165], v[16:17], v[178:179], v[180:181] neg_lo:[0,0,1] neg_hi:[0,0,1]
	v_pk_fma_f32 v[168:169], v[80:81], v[178:179], v[168:169]
	v_lshl_add_u64 v[182:183], v[152:153], 0, v[184:185]
	v_cvt_pk_bf16_f32 v152, v156, v157
	v_cvt_pk_bf16_f32 v153, v154, v155
	v_cvt_pk_bf16_f32 v154, v164, v165
	v_cvt_pk_bf16_f32 v155, v162, v163
	v_cvt_pk_bf16_f32 v178, v160, v161
	v_cvt_pk_bf16_f32 v179, v158, v159
	v_cvt_pk_bf16_f32 v180, v168, v169
	v_cvt_pk_bf16_f32 v181, v166, v167
	global_store_dwordx4 v[182:183], v[152:155], off offset:128
	global_store_dwordx4 v[182:183], v[178:181], off
	s_nop 0
	v_or_b32_e32 v152, s44, v175
	v_ashrrev_i32_e32 v153, 31, v152
	v_lshlrev_b64 v[182:183], 18, v[152:153]
	global_load_dwordx4 v[178:181], v[144:145], off offset:32
	global_load_dwordx4 v[162:165], v[144:145], off offset:48
	global_load_dwordx4 v[152:155], v[144:145], off
	global_load_dwordx4 v[156:159], v[144:145], off offset:16
	s_waitcnt vmcnt(1)
	v_mov_b32_e32 v168, v153
	s_waitcnt vmcnt(0)
	v_mov_b32_e32 v166, v157
	v_mov_b32_e32 v167, v159
	v_mov_b32_e32 v169, v155
	v_pk_mul_f32 v[160:161], v[46:47], v[166:167]
	v_pk_mul_f32 v[194:195], v[44:45], v[168:169]
	v_mov_b32_e32 v157, v158
	v_mov_b32_e32 v153, v154
	v_pk_mul_f32 v[154:155], v[110:111], v[166:167]
	v_pk_mul_f32 v[166:167], v[108:109], v[168:169]
	v_pk_fma_f32 v[158:159], v[110:111], v[156:157], v[160:161]
	v_pk_fma_f32 v[160:161], v[108:109], v[152:153], v[194:195]
	v_pk_fma_f32 v[154:155], v[46:47], v[156:157], v[154:155] neg_lo:[0,0,1] neg_hi:[0,0,1]
	v_pk_fma_f32 v[156:157], v[44:45], v[152:153], v[166:167] neg_lo:[0,0,1] neg_hi:[0,0,1]
	v_mov_b32_e32 v152, v163
	v_mov_b32_e32 v153, v165
	v_pk_mul_f32 v[166:167], v[42:43], v[152:153]
	v_mov_b32_e32 v194, v179
	v_mov_b32_e32 v195, v181
	v_mov_b32_e32 v163, v164
	v_pk_mul_f32 v[152:153], v[106:107], v[152:153]
	v_pk_mul_f32 v[168:169], v[40:41], v[194:195]
	v_pk_fma_f32 v[166:167], v[106:107], v[162:163], v[166:167]
	v_mov_b32_e32 v179, v180
	v_pk_mul_f32 v[164:165], v[104:105], v[194:195]
	v_pk_fma_f32 v[162:163], v[42:43], v[162:163], v[152:153] neg_lo:[0,0,1] neg_hi:[0,0,1]
	v_lshl_add_u64 v[152:153], s[46:47], 0, v[182:183]
	v_pk_fma_f32 v[168:169], v[104:105], v[178:179], v[168:169]
	v_pk_fma_f32 v[164:165], v[40:41], v[178:179], v[164:165] neg_lo:[0,0,1] neg_hi:[0,0,1]
	v_lshl_add_u64 v[178:179], v[152:153], 0, s[12:13]
	v_lshl_add_u64 v[182:183], v[178:179], 0, v[184:185]
	v_cvt_pk_bf16_f32 v178, v160, v161
	v_cvt_pk_bf16_f32 v179, v158, v159
	v_cvt_pk_bf16_f32 v180, v168, v169
	v_cvt_pk_bf16_f32 v181, v166, v167
	v_cvt_pk_bf16_f32 v156, v156, v157
	v_cvt_pk_bf16_f32 v157, v154, v155
	v_cvt_pk_bf16_f32 v158, v164, v165
	v_cvt_pk_bf16_f32 v159, v162, v163
	global_store_dwordx4 v[182:183], v[178:181], off
	global_store_dwordx4 v[182:183], v[156:159], off offset:128
	global_load_dwordx4 v[178:181], v[144:145], off offset:32
	s_nop 0
	global_load_dwordx4 v[162:165], v[144:145], off offset:48
	global_load_dwordx4 v[166:169], v[144:145], off
	global_load_dwordx4 v[154:157], v[144:145], off offset:16
	v_lshl_add_u64 v[152:153], v[152:153], 0, s[14:15]
	s_waitcnt vmcnt(1)
; DI u32x4 pack8(const f32x4& v0, const f32x4& v1) { u32x4 w; w.x = pk2(v0[0], v0[1]); w.y = pk2(v0[2], v0[3]); w.z = pk2(v1[0], v1[1]); w.w = pk2(v1[2], v1[3]); return w; }
;     DI void operator()(const f32x4 (&acc)[2][2][4][2], const Unit& u, int wr, int wc, int fr, int fq) const {
;     ...
;         for (int m = 0; m < 4; ++m) {
;             const int k1 = 16 * m + fr;
; #pragma unroll
;             for (int bj = 0; bj < 2; ++bj) {
;                 const int j0 = 128 * bj + 32 * wc + 8 * fq, ge = 4 * u.pn + (j0 >> 6), nl0 = j0 & 63;
;                 const f32x4* tw = (const f32x4*)(TW + (size_t)(k1 * 64 + nl0) * 2);
;                 f32x4 yr[2], yi[2];
; #pragma unroll
;                 for (int n = 0; n < 2; ++n) {
;                     const f32x4 t0 = tw[2 * n], t1 = tw[2 * n + 1];
;                     const f32x4 c = {t0.x, t0.z, t1.x, t1.z}, s = {t0.y, t0.w, t1.y, t1.w};
;                     const f32x4 r = acc[0][bj][m][n], i = acc[1][bj][m][n];
;                     yr[n] = c * r + s * i; yi[n] = c * i - s * r;
;                 }
;                 bf16_t* dst = YP + ((((size_t)(u.z * 64 + k1)) * 1024 + ge) * 2) * 64 + nl0;
;                 *(u32x4*)dst = pack8(yr[0], yr[1]); *(u32x4*)(dst + 64) = pack8(yi[0], yi[1]);
	v_mov_b32_e32 v194, v167
	s_waitcnt vmcnt(0)
	v_mov_b32_e32 v182, v155
	v_mov_b32_e32 v183, v157
	v_mov_b32_e32 v195, v169
	v_pk_mul_f32 v[158:159], v[14:15], v[182:183]
	v_pk_mul_f32 v[160:161], v[12:13], v[194:195]
	v_mov_b32_e32 v155, v156
	v_mov_b32_e32 v167, v168
	v_pk_mul_f32 v[156:157], v[78:79], v[182:183]
	v_pk_mul_f32 v[168:169], v[76:77], v[194:195]
	v_mov_b32_e32 v182, v163
	v_mov_b32_e32 v183, v165
	v_mov_b32_e32 v194, v179
	v_mov_b32_e32 v195, v181
	v_pk_fma_f32 v[158:159], v[78:79], v[154:155], v[158:159]
	v_pk_fma_f32 v[160:161], v[76:77], v[166:167], v[160:161]
	v_pk_fma_f32 v[154:155], v[14:15], v[154:155], v[156:157] neg_lo:[0,0,1] neg_hi:[0,0,1]
	v_pk_fma_f32 v[156:157], v[12:13], v[166:167], v[168:169] neg_lo:[0,0,1] neg_hi:[0,0,1]
	v_pk_mul_f32 v[166:167], v[10:11], v[182:183]
	v_mov_b32_e32 v163, v164
	v_mov_b32_e32 v179, v180
	v_pk_mul_f32 v[164:165], v[74:75], v[182:183]
	v_pk_mul_f32 v[180:181], v[72:73], v[194:195]
	v_pk_mul_f32 v[168:169], v[8:9], v[194:195]
	v_pk_fma_f32 v[166:167], v[74:75], v[162:163], v[166:167]
	v_pk_fma_f32 v[162:163], v[10:11], v[162:163], v[164:165] neg_lo:[0,0,1] neg_hi:[0,0,1]
	v_pk_fma_f32 v[164:165], v[8:9], v[178:179], v[180:181] neg_lo:[0,0,1] neg_hi:[0,0,1]
	v_pk_fma_f32 v[168:169], v[72:73], v[178:179], v[168:169]
	v_lshl_add_u64 v[182:183], v[152:153], 0, v[184:185]
	v_cvt_pk_bf16_f32 v152, v156, v157
	v_cvt_pk_bf16_f32 v153, v154, v155
	v_cvt_pk_bf16_f32 v154, v164, v165
	v_cvt_pk_bf16_f32 v155, v162, v163
	v_cvt_pk_bf16_f32 v178, v160, v161
	v_cvt_pk_bf16_f32 v179, v158, v159
	v_cvt_pk_bf16_f32 v180, v168, v169
	v_cvt_pk_bf16_f32 v181, v166, v167
	global_store_dwordx4 v[182:183], v[152:155], off offset:128
	global_store_dwordx4 v[182:183], v[178:181], off
	s_nop 0
	v_or_b32_e32 v152, s44, v176
	v_ashrrev_i32_e32 v153, 31, v152
	v_lshlrev_b64 v[182:183], 18, v[152:153]
	global_load_dwordx4 v[178:181], v[146:147], off offset:32
	global_load_dwordx4 v[162:165], v[146:147], off offset:48
	global_load_dwordx4 v[152:155], v[146:147], off
	global_load_dwordx4 v[156:159], v[146:147], off offset:16
	s_waitcnt vmcnt(1)
	v_mov_b32_e32 v168, v153
	s_waitcnt vmcnt(0)
	v_mov_b32_e32 v166, v157
	v_mov_b32_e32 v167, v159
	v_mov_b32_e32 v169, v155
	v_pk_mul_f32 v[160:161], v[38:39], v[166:167]
	v_pk_mul_f32 v[194:195], v[36:37], v[168:169]
	v_mov_b32_e32 v157, v158
	v_mov_b32_e32 v153, v154
	v_pk_mul_f32 v[154:155], v[102:103], v[166:167]
	v_pk_mul_f32 v[166:167], v[100:101], v[168:169]
	v_pk_fma_f32 v[158:159], v[102:103], v[156:157], v[160:161]
	v_pk_fma_f32 v[160:161], v[100:101], v[152:153], v[194:195]
	v_pk_fma_f32 v[154:155], v[38:39], v[156:157], v[154:155] neg_lo:[0,0,1] neg_hi:[0,0,1]
	v_pk_fma_f32 v[156:157], v[36:37], v[152:153], v[166:167] neg_lo:[0,0,1] neg_hi:[0,0,1]
	v_mov_b32_e32 v152, v163
	v_mov_b32_e32 v153, v165
	v_pk_mul_f32 v[166:167], v[34:35], v[152:153]
	v_mov_b32_e32 v194, v179
	v_mov_b32_e32 v195, v181
	v_mov_b32_e32 v163, v164
	v_pk_mul_f32 v[152:153], v[98:99], v[152:153]
	v_pk_mul_f32 v[168:169], v[32:33], v[194:195]
	v_pk_fma_f32 v[166:167], v[98:99], v[162:163], v[166:167]
	v_mov_b32_e32 v179, v180
	v_pk_mul_f32 v[164:165], v[96:97], v[194:195]
	v_pk_fma_f32 v[162:163], v[34:35], v[162:163], v[152:153] neg_lo:[0,0,1] neg_hi:[0,0,1]
	v_lshl_add_u64 v[152:153], s[46:47], 0, v[182:183]
	v_pk_fma_f32 v[168:169], v[96:97], v[178:179], v[168:169]
	v_pk_fma_f32 v[164:165], v[32:33], v[178:179], v[164:165] neg_lo:[0,0,1] neg_hi:[0,0,1]
	v_lshl_add_u64 v[178:179], v[152:153], 0, s[12:13]
	v_lshl_add_u64 v[182:183], v[178:179], 0, v[184:185]
	v_cvt_pk_bf16_f32 v178, v160, v161
	v_cvt_pk_bf16_f32 v179, v158, v159
	v_cvt_pk_bf16_f32 v180, v168, v169
	v_cvt_pk_bf16_f32 v181, v166, v167
	v_cvt_pk_bf16_f32 v156, v156, v157
	v_cvt_pk_bf16_f32 v157, v154, v155
	v_cvt_pk_bf16_f32 v158, v164, v165
	v_cvt_pk_bf16_f32 v159, v162, v163
	global_store_dwordx4 v[182:183], v[178:181], off
	global_store_dwordx4 v[182:183], v[156:159], off offset:128
	global_load_dwordx4 v[178:181], v[146:147], off offset:32
	s_nop 0
	global_load_dwordx4 v[162:165], v[146:147], off offset:48
	global_load_dwordx4 v[166:169], v[146:147], off
	global_load_dwordx4 v[154:157], v[146:147], off offset:16
	v_lshl_add_u64 v[152:153], v[152:153], 0, s[14:15]
	s_waitcnt vmcnt(1)
	v_mov_b32_e32 v194, v167
	s_waitcnt vmcnt(0)
	v_mov_b32_e32 v182, v155
	v_mov_b32_e32 v183, v157
	v_mov_b32_e32 v195, v169
	v_pk_mul_f32 v[158:159], v[6:7], v[182:183]
	v_pk_mul_f32 v[160:161], v[4:5], v[194:195]
	v_mov_b32_e32 v155, v156
	v_mov_b32_e32 v167, v168
	v_pk_mul_f32 v[156:157], v[70:71], v[182:183]
	v_pk_mul_f32 v[168:169], v[68:69], v[194:195]
	v_mov_b32_e32 v182, v163
	v_mov_b32_e32 v183, v165
	v_mov_b32_e32 v194, v179
	v_mov_b32_e32 v195, v181
	v_pk_fma_f32 v[158:159], v[70:71], v[154:155], v[158:159]
	v_pk_fma_f32 v[160:161], v[68:69], v[166:167], v[160:161]
	v_pk_fma_f32 v[154:155], v[6:7], v[154:155], v[156:157] neg_lo:[0,0,1] neg_hi:[0,0,1]
	v_pk_fma_f32 v[156:157], v[4:5], v[166:167], v[168:169] neg_lo:[0,0,1] neg_hi:[0,0,1]
	v_pk_mul_f32 v[166:167], v[2:3], v[182:183]
	v_pk_mul_f32 v[168:169], v[0:1], v[194:195]
	v_mov_b32_e32 v163, v164
	v_mov_b32_e32 v179, v180
	v_pk_mul_f32 v[164:165], v[66:67], v[182:183]
	v_pk_mul_f32 v[180:181], v[64:65], v[194:195]
	v_pk_fma_f32 v[166:167], v[66:67], v[162:163], v[166:167]
	v_pk_fma_f32 v[168:169], v[64:65], v[178:179], v[168:169]
	v_pk_fma_f32 v[162:163], v[2:3], v[162:163], v[164:165] neg_lo:[0,0,1] neg_hi:[0,0,1]
	v_pk_fma_f32 v[164:165], v[0:1], v[178:179], v[180:181] neg_lo:[0,0,1] neg_hi:[0,0,1]
	v_lshl_add_u64 v[182:183], v[152:153], 0, v[184:185]
	v_cvt_pk_bf16_f32 v178, v160, v161
	v_cvt_pk_bf16_f32 v179, v158, v159
	v_cvt_pk_bf16_f32 v180, v168, v169
	v_cvt_pk_bf16_f32 v181, v166, v167
	v_cvt_pk_bf16_f32 v152, v156, v157
	v_cvt_pk_bf16_f32 v153, v154, v155
	v_cvt_pk_bf16_f32 v154, v164, v165
	v_cvt_pk_bf16_f32 v155, v162, v163
	global_store_dwordx4 v[182:183], v[178:181], off
	global_store_dwordx4 v[182:183], v[152:155], off offset:128
	s_andn2_b64 vcc, exec, s[8:9]
	s_cbranch_vccnz .LBB0_254
	s_branch .LBB0_264

; #define G_STAGE_A(bufoff, p0, p1, koff) do { \
;         __builtin_amdgcn_global_load_lds((const unsigned*)(gbase + (size_t)(unsigned)((p0) + (koff) + voffA[0])), (LAS unsigned*)(lds + (bufoff) + ldsw), 16, 0, 0); \
;         __builtin_amdgcn_global_load_lds((const unsigned*)(gbase + (size_t)(unsigned)((p1) + (koff) + voffA[1])), (LAS unsigned*)(lds + (bufoff) + ldsw + 8192), 16, 0, 0); } while (0)
; #define G_STAGE_B(bufoff, p, koff) do { \
;         __builtin_amdgcn_global_load_lds((const unsigned*)(gbase + (size_t)(unsigned)((p) + (koff) + voffB[0])), (LAS unsigned*)(lds + (bufoff) + ldsw), 16, 0, 0); \
;         __builtin_amdgcn_global_load_lds((const unsigned*)(gbase + (size_t)(unsigned)((p) + (koff) + voffB[1])), (LAS unsigned*)(lds + (bufoff) + ldsw + 8192), 16, 0, 0); } while (0)
; #define G_LDA(dst, b, h) do { _Pragma("unroll") for (int m = 0; m < 4; ++m) _Pragma("unroll") for (int k = 0; k < 2; ++k) dst[m][k] = *(const LAS bf16x8*)(lds + G_SA(b, h) + aoff + m * 2048 + k * 1024); } while (0)
; #define G_LDB(dst, b, h) do { _Pragma("unroll") for (int n = 0; n < 2; ++n) _Pragma("unroll") for (int k = 0; k < 2; ++k) dst[n][k] = *(const LAS bf16x8*)(lds + G_SB(b, h) + boff + n * 2048 + k * 1024); } while (0)
; #define G_WAIT_V(n) asm volatile("s_waitcnt vmcnt(" #n ")" ::: "memory")
; #define G_WAIT_L(n) asm volatile("s_waitcnt lgkmcnt(" #n ")" ::: "memory")
; template <class Epi>
; DI void gemm_phase(LAS unsigned char* lds, const Sched& S, const Epi& E, const int K) {
;     ...
;             const unsigned k1 = (unsigned)(t + 1) * kstepA;
;             const unsigned k2 = last ? 0u : (unsigned)(t + 2) * kstepA, k3 = k2 + kstepA;
;             const unsigned kb2 = last ? 0u : (unsigned)(t + 2) * kstepB, kb3 = kb2 + kstepB;
;             const unsigned x0 = last ? n0 : cur.a0, x1 = last ? n1 : cur.a1, x2 = last ? n2 : cur.a2, x3 = last ? n3 : cur.a3;
;             const unsigned xb = last ? nB : cur.b;
;     ...
;             G_LDB(B0, 0, 0); G_LDB(B1, 0, 1); G_SCHED; G_LDA(At, 0, 0); G_STAGE_A(G_SA(1, 1), cur.a2, cur.a3, k1);
;             G_WAIT_V(8); G_WAIT_L(0); G_BAR; G_MMA(0, 0, At, B0); G_MMA(0, 1, At, B1); G_BAR; G_SCHED;
;             G_LDA(At, 0, 1); G_STAGE_B(G_SB(0, 0), xb, kb2); G_STAGE_B(G_SB(0, 1), xb + hstepB, kb2); G_STAGE_A(G_SA(0, 0), x0, x1, k2);
;             G_WAIT_V(8); G_WAIT_L(0); G_BAR; G_MMA(1, 0, At, B0); G_MMA(1, 1, At, B1); G_BAR; G_SCHED;
.LBB0_281:
	s_add_u32 s14, s12, 0x100
	s_addc_u32 s15, s13, 0
	s_cmp_eq_u32 s44, 4
	s_cselect_b32 s40, 0, s14
	s_cselect_b32 s46, s41, s35
	s_add_i32 s47, 0, 0x10000
	v_add_u32_e32 v132, s47, v136
	s_add_i32 s48, 0, 0x14000
	ds_read_b128 v[144:147], v132
	ds_read_b128 v[148:151], v132 offset:1024
	ds_read_b128 v[152:155], v132 offset:2048
	ds_read_b128 v[156:159], v132 offset:3072
	v_add_u32_e32 v132, s48, v136
	ds_read_b128 v[160:163], v132
	ds_read_b128 v[164:167], v132 offset:1024
	ds_read_b128 v[168:171], v132 offset:2048
	ds_read_b128 v[172:175], v132 offset:3072
	s_or_b32 s45, s40, 0x80
	v_lshl_add_u64 v[132:133], v[130:131], 0, s[12:13]
	s_add_i32 m0, s17, 0xc000
	ds_read_b128 v[176:179], v143
	ds_read_b128 v[180:183], v143 offset:1024
	ds_read_b128 v[194:197], v143 offset:2048
	ds_read_b128 v[198:201], v143 offset:3072
	ds_read_b128 v[202:205], v143 offset:4096
	ds_read_b128 v[206:209], v143 offset:5120
	ds_read_b128 v[210:213], v143 offset:6144
	ds_read_b128 v[214:217], v143 offset:7168
	global_load_lds_dwordx4 v[132:133], off
	v_lshl_add_u64 v[132:133], v[128:129], 0, s[12:13]
	s_add_i32 m0, s17, 0xe000
	s_nop 0
	global_load_lds_dwordx4 v[132:133], off
	s_waitcnt vmcnt(8) lgkmcnt(0)
	s_barrier
	s_setprio 1
	v_mfma_f32_16x16x32_bf16 v[124:127], v[144:147], v[176:179], v[124:127]
	v_mfma_f32_16x16x32_bf16 v[120:123], v[152:155], v[176:179], v[120:123]
	v_mfma_f32_16x16x32_bf16 v[116:119], v[144:147], v[194:197], v[116:119]
	v_mfma_f32_16x16x32_bf16 v[112:115], v[152:155], v[194:197], v[112:115]
	v_mfma_f32_16x16x32_bf16 v[108:111], v[144:147], v[202:205], v[108:111]
	v_mfma_f32_16x16x32_bf16 v[104:107], v[152:155], v[202:205], v[104:107]
	v_mfma_f32_16x16x32_bf16 v[100:103], v[144:147], v[210:213], v[100:103]
	v_mfma_f32_16x16x32_bf16 v[96:99], v[152:155], v[210:213], v[96:99]
	v_mfma_f32_16x16x32_bf16 v[124:127], v[148:151], v[180:183], v[124:127]
	v_mfma_f32_16x16x32_bf16 v[120:123], v[156:159], v[180:183], v[120:123]
	v_mfma_f32_16x16x32_bf16 v[116:119], v[148:151], v[198:201], v[116:119]
	v_mfma_f32_16x16x32_bf16 v[112:115], v[156:159], v[198:201], v[112:115]
	v_mfma_f32_16x16x32_bf16 v[108:111], v[148:151], v[206:209], v[108:111]
	v_mfma_f32_16x16x32_bf16 v[104:107], v[156:159], v[206:209], v[104:107]
	v_mfma_f32_16x16x32_bf16 v[100:103], v[148:151], v[214:217], v[100:103]
	v_mfma_f32_16x16x32_bf16 v[96:99], v[156:159], v[214:217], v[96:99]
	v_mfma_f32_16x16x32_bf16 v[92:95], v[160:163], v[176:179], v[92:95]
	v_mfma_f32_16x16x32_bf16 v[88:91], v[168:171], v[176:179], v[88:91]
	v_mfma_f32_16x16x32_bf16 v[84:87], v[160:163], v[194:197], v[84:87]
	v_mfma_f32_16x16x32_bf16 v[80:83], v[168:171], v[194:197], v[80:83]
	v_mfma_f32_16x16x32_bf16 v[76:79], v[160:163], v[202:205], v[76:79]
	v_mfma_f32_16x16x32_bf16 v[72:75], v[168:171], v[202:205], v[72:75]
	v_mfma_f32_16x16x32_bf16 v[68:71], v[160:163], v[210:213], v[68:71]
	v_mfma_f32_16x16x32_bf16 v[64:67], v[168:171], v[210:213], v[64:67]
	v_mfma_f32_16x16x32_bf16 v[92:95], v[164:167], v[180:183], v[92:95]
	v_mfma_f32_16x16x32_bf16 v[88:91], v[172:175], v[180:183], v[88:91]
	v_mfma_f32_16x16x32_bf16 v[84:87], v[164:167], v[198:201], v[84:87]
	v_mfma_f32_16x16x32_bf16 v[80:83], v[172:175], v[198:201], v[80:83]
	v_mfma_f32_16x16x32_bf16 v[76:79], v[164:167], v[206:209], v[76:79]
	v_mfma_f32_16x16x32_bf16 v[72:75], v[172:175], v[206:209], v[72:75]
	v_mfma_f32_16x16x32_bf16 v[68:71], v[164:167], v[214:217], v[68:71]
	v_mfma_f32_16x16x32_bf16 v[64:67], v[172:175], v[214:217], v[64:67]
	s_setprio 0
	s_barrier
	s_add_i32 s12, s40, s46
	s_add_i32 s13, s47, s16
	v_add_u32_e32 v132, s12, v134
	s_mov_b32 m0, s13
	ds_read_b128 v[176:179], v143 offset:16384
	ds_read_b128 v[180:183], v143 offset:17408
	ds_read_b128 v[194:197], v143 offset:18432
	ds_read_b128 v[198:201], v143 offset:19456
	ds_read_b128 v[202:205], v143 offset:20480
	ds_read_b128 v[206:209], v143 offset:21504
	ds_read_b128 v[210:213], v143 offset:22528
	ds_read_b128 v[214:217], v143 offset:23552
	global_load_lds_dwordx4 v132, s[82:83]
	v_add_u32_e32 v132, s12, v135
	s_add_i32 s12, s46, 0x20000
	s_add_i32 m0, s13, 0x2000
	s_add_i32 s13, s12, s40
	s_add_i32 s47, s48, s16
	global_load_lds_dwordx4 v132, s[82:83]
	v_add_u32_e32 v132, s13, v134
	s_mov_b32 m0, s47
	s_nop 0
	global_load_lds_dwordx4 v132, s[82:83]
	v_add_u32_e32 v132, s13, v135
	s_add_i32 m0, s47, 0x2000
	s_nop 0
	global_load_lds_dwordx4 v132, s[82:83]
	v_add_u32_e32 v132, s40, v141
	s_mov_b32 m0, s17
	s_nop 0
	global_load_lds_dwordx4 v132, s[82:83]
	v_add_u32_e32 v132, s40, v142
	s_mov_b32 m0, s18
	s_nop 0
	global_load_lds_dwordx4 v132, s[82:83]
	s_waitcnt vmcnt(8) lgkmcnt(0)
	s_barrier
; #define G_STAGE_A(bufoff, p0, p1, koff) do { \
;         __builtin_amdgcn_global_load_lds((const unsigned*)(gbase + (size_t)(unsigned)((p0) + (koff) + voffA[0])), (LAS unsigned*)(lds + (bufoff) + ldsw), 16, 0, 0); \
;         __builtin_amdgcn_global_load_lds((const unsigned*)(gbase + (size_t)(unsigned)((p1) + (koff) + voffA[1])), (LAS unsigned*)(lds + (bufoff) + ldsw + 8192), 16, 0, 0); } while (0)
; #define G_LDA(dst, b, h) do { _Pragma("unroll") for (int m = 0; m < 4; ++m) _Pragma("unroll") for (int k = 0; k < 2; ++k) dst[m][k] = *(const LAS bf16x8*)(lds + G_SA(b, h) + aoff + m * 2048 + k * 1024); } while (0)
; #define G_LDB(dst, b, h) do { _Pragma("unroll") for (int n = 0; n < 2; ++n) _Pragma("unroll") for (int k = 0; k < 2; ++k) dst[n][k] = *(const LAS bf16x8*)(lds + G_SB(b, h) + boff + n * 2048 + k * 1024); } while (0)
; #define G_MMA(ai, bj, At, Bt) do { __builtin_amdgcn_s_setprio(1); _Pragma("unroll") for (int m = 0; m < 4; ++m) _Pragma("unroll") for (int n = 0; n < 2; ++n) _Pragma("unroll") for (int k = 0; k < 2; ++k) \
;         acc[ai][bj][m][n] = __builtin_amdgcn_mfma_f32_16x16x32_bf16(Bt[n][k], At[m][k], acc[ai][bj][m][n], 0, 0, 0); __builtin_amdgcn_s_setprio(0); } while (0)
; #define G_WAIT_V(n) asm volatile("s_waitcnt vmcnt(" #n ")" ::: "memory")
; #define G_WAIT_L(n) asm volatile("s_waitcnt lgkmcnt(" #n ")" ::: "memory")
; #define G_BAR __builtin_amdgcn_s_barrier()
; #define G_SCHED __builtin_amdgcn_sched_barrier(0)
; template <class Epi>
; DI void gemm_phase(LAS unsigned char* lds, const Sched& S, const Epi& E, const int K) {
;     ...
;             G_WAIT_V(8); G_WAIT_L(0); G_BAR; G_MMA(1, 0, At, B0); G_MMA(1, 1, At, B1); G_BAR; G_SCHED;
;             G_LDB(B0, 1, 0); G_LDB(B1, 1, 1); G_SCHED; G_LDA(At, 1, 0); G_STAGE_A(G_SA(0, 1), x2, x3, k2);
;             G_WAIT_V(8); G_WAIT_L(0); G_BAR; G_MMA(0, 0, At, B0); G_MMA(0, 1, At, B1); G_BAR; G_SCHED;
	s_setprio 1
	v_mfma_f32_16x16x32_bf16 v[60:63], v[144:147], v[176:179], v[60:63]
	v_mfma_f32_16x16x32_bf16 v[56:59], v[152:155], v[176:179], v[56:59]
	v_mfma_f32_16x16x32_bf16 v[52:55], v[144:147], v[194:197], v[52:55]
	v_mfma_f32_16x16x32_bf16 v[48:51], v[152:155], v[194:197], v[48:51]
	v_mfma_f32_16x16x32_bf16 v[44:47], v[144:147], v[202:205], v[44:47]
	v_mfma_f32_16x16x32_bf16 v[40:43], v[152:155], v[202:205], v[40:43]
	v_mfma_f32_16x16x32_bf16 v[36:39], v[144:147], v[210:213], v[36:39]
	v_mfma_f32_16x16x32_bf16 v[32:35], v[152:155], v[210:213], v[32:35]
	v_mfma_f32_16x16x32_bf16 v[60:63], v[148:151], v[180:183], v[60:63]
	v_mfma_f32_16x16x32_bf16 v[56:59], v[156:159], v[180:183], v[56:59]
	v_mfma_f32_16x16x32_bf16 v[52:55], v[148:151], v[198:201], v[52:55]
	v_mfma_f32_16x16x32_bf16 v[48:51], v[156:159], v[198:201], v[48:51]
	v_mfma_f32_16x16x32_bf16 v[44:47], v[148:151], v[206:209], v[44:47]
	v_mfma_f32_16x16x32_bf16 v[40:43], v[156:159], v[206:209], v[40:43]
	v_mfma_f32_16x16x32_bf16 v[36:39], v[148:151], v[214:217], v[36:39]
	v_mfma_f32_16x16x32_bf16 v[32:35], v[156:159], v[214:217], v[32:35]
	v_mfma_f32_16x16x32_bf16 v[28:31], v[160:163], v[176:179], v[28:31]
	v_mfma_f32_16x16x32_bf16 v[24:27], v[168:171], v[176:179], v[24:27]
	v_mfma_f32_16x16x32_bf16 v[20:23], v[160:163], v[194:197], v[20:23]
	v_mfma_f32_16x16x32_bf16 v[16:19], v[168:171], v[194:197], v[16:19]
	v_mfma_f32_16x16x32_bf16 v[12:15], v[160:163], v[202:205], v[12:15]
	v_mfma_f32_16x16x32_bf16 v[8:11], v[168:171], v[202:205], v[8:11]
	v_mfma_f32_16x16x32_bf16 v[4:7], v[160:163], v[210:213], v[4:7]
	v_mfma_f32_16x16x32_bf16 v[0:3], v[168:171], v[210:213], v[0:3]
	v_mfma_f32_16x16x32_bf16 v[28:31], v[164:167], v[180:183], v[28:31]
	v_mfma_f32_16x16x32_bf16 v[24:27], v[172:175], v[180:183], v[24:27]
	v_mfma_f32_16x16x32_bf16 v[20:23], v[164:167], v[198:201], v[20:23]
	v_mfma_f32_16x16x32_bf16 v[16:19], v[172:175], v[198:201], v[16:19]
	v_mfma_f32_16x16x32_bf16 v[12:15], v[164:167], v[206:209], v[12:15]
	v_mfma_f32_16x16x32_bf16 v[8:11], v[172:175], v[206:209], v[8:11]
	v_mfma_f32_16x16x32_bf16 v[4:7], v[164:167], v[214:217], v[4:7]
	v_mfma_f32_16x16x32_bf16 v[0:3], v[172:175], v[214:217], v[0:3]
	s_setprio 0
	s_barrier
	s_add_i32 s13, 0, 0x18000
	v_add_u32_e32 v132, s13, v136
	s_add_i32 s47, 0, 0x1c000
	ds_read_b128 v[144:147], v132
	ds_read_b128 v[148:151], v132 offset:1024
	ds_read_b128 v[152:155], v132 offset:2048
	ds_read_b128 v[156:159], v132 offset:3072
	v_add_u32_e32 v132, s47, v136
	ds_read_b128 v[160:163], v132
	ds_read_b128 v[164:167], v132 offset:1024
	ds_read_b128 v[168:171], v132 offset:2048
	ds_read_b128 v[172:175], v132 offset:3072
	s_mov_b32 m0, s19
	v_add_u32_e32 v132, s40, v139
	ds_read_b128 v[176:179], v143 offset:32768
	ds_read_b128 v[180:183], v143 offset:33792
	ds_read_b128 v[194:197], v143 offset:34816
	ds_read_b128 v[198:201], v143 offset:35840
	ds_read_b128 v[202:205], v143 offset:36864
	ds_read_b128 v[206:209], v143 offset:37888
	ds_read_b128 v[210:213], v143 offset:38912
	ds_read_b128 v[214:217], v143 offset:39936
	global_load_lds_dwordx4 v132, s[82:83]
	v_add_u32_e32 v132, s40, v140
	s_mov_b32 m0, s20
	s_nop 0
	global_load_lds_dwordx4 v132, s[82:83]
	s_waitcnt vmcnt(8) lgkmcnt(0)
	s_barrier
	s_setprio 1
	v_mfma_f32_16x16x32_bf16 v[124:127], v[144:147], v[176:179], v[124:127]
	v_mfma_f32_16x16x32_bf16 v[120:123], v[152:155], v[176:179], v[120:123]
	v_mfma_f32_16x16x32_bf16 v[116:119], v[144:147], v[194:197], v[116:119]
	v_mfma_f32_16x16x32_bf16 v[112:115], v[152:155], v[194:197], v[112:115]
	v_mfma_f32_16x16x32_bf16 v[108:111], v[144:147], v[202:205], v[108:111]
	v_mfma_f32_16x16x32_bf16 v[104:107], v[152:155], v[202:205], v[104:107]
	v_mfma_f32_16x16x32_bf16 v[100:103], v[144:147], v[210:213], v[100:103]
	v_mfma_f32_16x16x32_bf16 v[96:99], v[152:155], v[210:213], v[96:99]
	v_mfma_f32_16x16x32_bf16 v[124:127], v[148:151], v[180:183], v[124:127]
	v_mfma_f32_16x16x32_bf16 v[120:123], v[156:159], v[180:183], v[120:123]
	v_mfma_f32_16x16x32_bf16 v[116:119], v[148:151], v[198:201], v[116:119]
	v_mfma_f32_16x16x32_bf16 v[112:115], v[156:159], v[198:201], v[112:115]
	v_mfma_f32_16x16x32_bf16 v[108:111], v[148:151], v[206:209], v[108:111]
	v_mfma_f32_16x16x32_bf16 v[104:107], v[156:159], v[206:209], v[104:107]
	v_mfma_f32_16x16x32_bf16 v[100:103], v[148:151], v[214:217], v[100:103]
	v_mfma_f32_16x16x32_bf16 v[96:99], v[156:159], v[214:217], v[96:99]
	v_mfma_f32_16x16x32_bf16 v[92:95], v[160:163], v[176:179], v[92:95]
	v_mfma_f32_16x16x32_bf16 v[88:91], v[168:171], v[176:179], v[88:91]
	v_mfma_f32_16x16x32_bf16 v[84:87], v[160:163], v[194:197], v[84:87]
	v_mfma_f32_16x16x32_bf16 v[80:83], v[168:171], v[194:197], v[80:83]
	v_mfma_f32_16x16x32_bf16 v[76:79], v[160:163], v[202:205], v[76:79]
	v_mfma_f32_16x16x32_bf16 v[72:75], v[168:171], v[202:205], v[72:75]
	v_mfma_f32_16x16x32_bf16 v[68:71], v[160:163], v[210:213], v[68:71]
	v_mfma_f32_16x16x32_bf16 v[64:67], v[168:171], v[210:213], v[64:67]
	v_mfma_f32_16x16x32_bf16 v[92:95], v[164:167], v[180:183], v[92:95]
	v_mfma_f32_16x16x32_bf16 v[88:91], v[172:175], v[180:183], v[88:91]
	v_mfma_f32_16x16x32_bf16 v[84:87], v[164:167], v[198:201], v[84:87]
	v_mfma_f32_16x16x32_bf16 v[80:83], v[172:175], v[198:201], v[80:83]
	v_mfma_f32_16x16x32_bf16 v[76:79], v[164:167], v[206:209], v[76:79]
	v_mfma_f32_16x16x32_bf16 v[72:75], v[172:175], v[206:209], v[72:75]
	v_mfma_f32_16x16x32_bf16 v[68:71], v[164:167], v[214:217], v[68:71]
	v_mfma_f32_16x16x32_bf16 v[64:67], v[172:175], v[214:217], v[64:67]
	s_setprio 0
	s_barrier
; #define G_STAGE_A(bufoff, p0, p1, koff) do { \
;         __builtin_amdgcn_global_load_lds((const unsigned*)(gbase + (size_t)(unsigned)((p0) + (koff) + voffA[0])), (LAS unsigned*)(lds + (bufoff) + ldsw), 16, 0, 0); \
;         __builtin_amdgcn_global_load_lds((const unsigned*)(gbase + (size_t)(unsigned)((p1) + (koff) + voffA[1])), (LAS unsigned*)(lds + (bufoff) + ldsw + 8192), 16, 0, 0); } while (0)
; #define G_STAGE_B(bufoff, p, koff) do { \
;         __builtin_amdgcn_global_load_lds((const unsigned*)(gbase + (size_t)(unsigned)((p) + (koff) + voffB[0])), (LAS unsigned*)(lds + (bufoff) + ldsw), 16, 0, 0); \
;         __builtin_amdgcn_global_load_lds((const unsigned*)(gbase + (size_t)(unsigned)((p) + (koff) + voffB[1])), (LAS unsigned*)(lds + (bufoff) + ldsw + 8192), 16, 0, 0); } while (0)
; #define G_LDA(dst, b, h) do { _Pragma("unroll") for (int m = 0; m < 4; ++m) _Pragma("unroll") for (int k = 0; k < 2; ++k) dst[m][k] = *(const LAS bf16x8*)(lds + G_SA(b, h) + aoff + m * 2048 + k * 1024); } while (0)
; #define G_MMA(ai, bj, At, Bt) do { __builtin_amdgcn_s_setprio(1); _Pragma("unroll") for (int m = 0; m < 4; ++m) _Pragma("unroll") for (int n = 0; n < 2; ++n) _Pragma("unroll") for (int k = 0; k < 2; ++k) \
;         acc[ai][bj][m][n] = __builtin_amdgcn_mfma_f32_16x16x32_bf16(Bt[n][k], At[m][k], acc[ai][bj][m][n], 0, 0, 0); __builtin_amdgcn_s_setprio(0); } while (0)
; #define G_WAIT_V(n) asm volatile("s_waitcnt vmcnt(" #n ")" ::: "memory")
; #define G_WAIT_L(n) asm volatile("s_waitcnt lgkmcnt(" #n ")" ::: "memory")
; #define G_BAR __builtin_amdgcn_s_barrier()
; #define G_SCHED __builtin_amdgcn_sched_barrier(0)
; template <class Epi>
; DI void gemm_phase(LAS unsigned char* lds, const Sched& S, const Epi& E, const int K) {
;     ...
;             G_LDA(At, 1, 1); G_STAGE_B(G_SB(1, 0), xb, kb3); G_STAGE_B(G_SB(1, 1), xb + hstepB, kb3); G_STAGE_A(G_SA(1, 0), x0, x1, k3);
;             G_WAIT_V(8); G_WAIT_L(0); G_BAR; G_MMA(1, 0, At, B0); G_MMA(1, 1, At, B1); G_BAR; G_SCHED;
	s_add_i32 s40, s45, s46
	s_add_i32 s13, s13, s16
	v_add_u32_e32 v132, s40, v134
	s_mov_b32 m0, s13
	ds_read_b128 v[176:179], v143 offset:49152
	ds_read_b128 v[180:183], v143 offset:50176
	ds_read_b128 v[194:197], v143 offset:51200
	ds_read_b128 v[198:201], v143 offset:52224
	ds_read_b128 v[202:205], v143 offset:53248
	ds_read_b128 v[206:209], v143 offset:54272
	ds_read_b128 v[210:213], v143 offset:55296
	ds_read_b128 v[214:217], v143 offset:56320
	global_load_lds_dwordx4 v132, s[82:83]
	v_add_u32_e32 v132, s40, v135
	s_add_i32 m0, s13, 0x2000
	s_add_i32 s12, s45, s12
	s_add_i32 s13, s47, s16
	global_load_lds_dwordx4 v132, s[82:83]
	v_add_u32_e32 v132, s12, v134
	s_mov_b32 m0, s13
	s_nop 0
	global_load_lds_dwordx4 v132, s[82:83]
	v_add_u32_e32 v132, s12, v135
	s_add_i32 m0, s13, 0x2000
	s_nop 0
	global_load_lds_dwordx4 v132, s[82:83]
	v_add_u32_e32 v132, s45, v141
	s_mov_b32 m0, s21
	s_nop 0
	global_load_lds_dwordx4 v132, s[82:83]
	v_add_u32_e32 v132, s45, v142
	s_mov_b32 m0, s24
	s_nop 0
	global_load_lds_dwordx4 v132, s[82:83]
	s_waitcnt vmcnt(8) lgkmcnt(0)
	s_barrier
	s_setprio 1
	v_mfma_f32_16x16x32_bf16 v[60:63], v[144:147], v[176:179], v[60:63]
	v_mfma_f32_16x16x32_bf16 v[56:59], v[152:155], v[176:179], v[56:59]
	v_mfma_f32_16x16x32_bf16 v[52:55], v[144:147], v[194:197], v[52:55]
	v_mfma_f32_16x16x32_bf16 v[48:51], v[152:155], v[194:197], v[48:51]
	v_mfma_f32_16x16x32_bf16 v[44:47], v[144:147], v[202:205], v[44:47]
	v_mfma_f32_16x16x32_bf16 v[40:43], v[152:155], v[202:205], v[40:43]
	v_mfma_f32_16x16x32_bf16 v[36:39], v[144:147], v[210:213], v[36:39]
	v_mfma_f32_16x16x32_bf16 v[32:35], v[152:155], v[210:213], v[32:35]
	v_mfma_f32_16x16x32_bf16 v[60:63], v[148:151], v[180:183], v[60:63]
	v_mfma_f32_16x16x32_bf16 v[56:59], v[156:159], v[180:183], v[56:59]
	v_mfma_f32_16x16x32_bf16 v[52:55], v[148:151], v[198:201], v[52:55]
	v_mfma_f32_16x16x32_bf16 v[48:51], v[156:159], v[198:201], v[48:51]
	v_mfma_f32_16x16x32_bf16 v[44:47], v[148:151], v[206:209], v[44:47]
	v_mfma_f32_16x16x32_bf16 v[40:43], v[156:159], v[206:209], v[40:43]
	v_mfma_f32_16x16x32_bf16 v[36:39], v[148:151], v[214:217], v[36:39]
	v_mfma_f32_16x16x32_bf16 v[32:35], v[156:159], v[214:217], v[32:35]
	v_mfma_f32_16x16x32_bf16 v[28:31], v[160:163], v[176:179], v[28:31]
	v_mfma_f32_16x16x32_bf16 v[24:27], v[168:171], v[176:179], v[24:27]
	v_mfma_f32_16x16x32_bf16 v[20:23], v[160:163], v[194:197], v[20:23]
	v_mfma_f32_16x16x32_bf16 v[16:19], v[168:171], v[194:197], v[16:19]
	v_mfma_f32_16x16x32_bf16 v[12:15], v[160:163], v[202:205], v[12:15]
	v_mfma_f32_16x16x32_bf16 v[8:11], v[168:171], v[202:205], v[8:11]
	v_mfma_f32_16x16x32_bf16 v[4:7], v[160:163], v[210:213], v[4:7]
	v_mfma_f32_16x16x32_bf16 v[0:3], v[168:171], v[210:213], v[0:3]
	v_mfma_f32_16x16x32_bf16 v[28:31], v[164:167], v[180:183], v[28:31]
	v_mfma_f32_16x16x32_bf16 v[24:27], v[172:175], v[180:183], v[24:27]
	v_mfma_f32_16x16x32_bf16 v[20:23], v[164:167], v[198:201], v[20:23]
	v_mfma_f32_16x16x32_bf16 v[16:19], v[172:175], v[198:201], v[16:19]
	v_mfma_f32_16x16x32_bf16 v[12:15], v[164:167], v[206:209], v[12:15]
	v_mfma_f32_16x16x32_bf16 v[8:11], v[172:175], v[206:209], v[8:11]
	v_mfma_f32_16x16x32_bf16 v[4:7], v[164:167], v[214:217], v[4:7]
	v_mfma_f32_16x16x32_bf16 v[0:3], v[172:175], v[214:217], v[0:3]
	s_setprio 0
	s_barrier
	s_add_i32 s44, s44, 2
	s_cmp_gt_u32 s44, 5
	s_mov_b64 s[12:13], s[14:15]
	s_cbranch_scc0 .LBB0_281
	s_and_b64 vcc, exec, s[6:7]
	s_cbranch_vccz .LBB0_284
	s_barrier

; #define G_STAGE_A(bufoff, p0, p1, koff) do { \
;         __builtin_amdgcn_global_load_lds((const unsigned*)(gbase + (size_t)(unsigned)((p0) + (koff) + voffA[0])), (LAS unsigned*)(lds + (bufoff) + ldsw), 16, 0, 0); \
;         __builtin_amdgcn_global_load_lds((const unsigned*)(gbase + (size_t)(unsigned)((p1) + (koff) + voffA[1])), (LAS unsigned*)(lds + (bufoff) + ldsw + 8192), 16, 0, 0); } while (0)
; #define G_STAGE_B(bufoff, p, koff) do { \
;         __builtin_amdgcn_global_load_lds((const unsigned*)(gbase + (size_t)(unsigned)((p) + (koff) + voffB[0])), (LAS unsigned*)(lds + (bufoff) + ldsw), 16, 0, 0); \
;         __builtin_amdgcn_global_load_lds((const unsigned*)(gbase + (size_t)(unsigned)((p) + (koff) + voffB[1])), (LAS unsigned*)(lds + (bufoff) + ldsw + 8192), 16, 0, 0); } while (0)
; #define G_LDA(dst, b, h) do { _Pragma("unroll") for (int m = 0; m < 4; ++m) _Pragma("unroll") for (int k = 0; k < 2; ++k) dst[m][k] = *(const LAS bf16x8*)(lds + G_SA(b, h) + aoff + m * 2048 + k * 1024); } while (0)
; #define G_LDB(dst, b, h) do { _Pragma("unroll") for (int n = 0; n < 2; ++n) _Pragma("unroll") for (int k = 0; k < 2; ++k) dst[n][k] = *(const LAS bf16x8*)(lds + G_SB(b, h) + boff + n * 2048 + k * 1024); } while (0)
; #define G_WAIT_V(n) asm volatile("s_waitcnt vmcnt(" #n ")" ::: "memory")
; #define G_WAIT_L(n) asm volatile("s_waitcnt lgkmcnt(" #n ")" ::: "memory")
; template <class Epi>
; DI void gemm_phase(LAS unsigned char* lds, const Sched& S, const Epi& E, const int K) {
;     ...
;             const unsigned k1 = (unsigned)(t + 1) * kstepA;
;             const unsigned k2 = last ? 0u : (unsigned)(t + 2) * kstepA, k3 = k2 + kstepA;
;             const unsigned kb2 = last ? 0u : (unsigned)(t + 2) * kstepB, kb3 = kb2 + kstepB;
;             const unsigned x0 = last ? n0 : cur.a0, x1 = last ? n1 : cur.a1, x2 = last ? n2 : cur.a2, x3 = last ? n3 : cur.a3;
;             const unsigned xb = last ? nB : cur.b;
;     ...
;             G_LDB(B0, 0, 0); G_LDB(B1, 0, 1); G_SCHED; G_LDA(At, 0, 0); G_STAGE_A(G_SA(1, 1), cur.a2, cur.a3, k1);
;             G_WAIT_V(8); G_WAIT_L(0); G_BAR; G_MMA(0, 0, At, B0); G_MMA(0, 1, At, B1); G_BAR; G_SCHED;
;             G_LDA(At, 0, 1); G_STAGE_B(G_SB(0, 0), xb, kb2); G_STAGE_B(G_SB(0, 1), xb + hstepB, kb2); G_STAGE_A(G_SA(0, 0), x0, x1, k2);
;             G_WAIT_V(8); G_WAIT_L(0); G_BAR; G_MMA(1, 0, At, B0); G_MMA(1, 1, At, B1); G_BAR; G_SCHED;
.LBB0_318:
	s_add_i32 s40, s86, 0x80
	v_add_u32_e32 v222, s80, v128
	v_add_u32_e32 v224, s40, v129
	v_add_u32_e32 v225, s40, v131
	s_add_i32 s40, 0, 0x10000
	s_add_i32 s80, 0, 0x14000
	v_add_u32_e32 v154, s40, v133
	v_add_u32_e32 v170, s80, v133
	ds_read_b128 v[142:145], v154
	ds_read_b128 v[146:149], v154 offset:1024
	ds_read_b128 v[150:153], v154 offset:2048
	ds_read_b128 v[154:157], v154 offset:3072
	ds_read_b128 v[158:161], v170
	ds_read_b128 v[162:165], v170 offset:1024
	ds_read_b128 v[166:169], v170 offset:2048
	ds_read_b128 v[170:173], v170 offset:3072
	s_add_i32 s36, s86, s44
	v_add_u32_e32 v218, s36, v129
	v_add_u32_e32 v219, s36, v131
	s_addk_i32 s36, 0x80
	v_add_u32_e32 v141, s50, v134
	v_add_u32_e32 v182, s47, v139
	v_add_u32_e32 v183, s86, v129
	v_add_u32_e32 v184, s86, v131
	v_add_u32_e32 v220, s37, v128
	v_add_u32_e32 v221, s79, v130
	v_add_u32_e32 v223, s81, v130
	v_add_u32_e32 v226, s36, v129
	v_add_u32_e32 v229, s36, v131
	v_add_u32_e32 v233, s37, v134
	v_add_u32_e32 v234, s79, v139
	s_add_i32 m0, s46, 0xc000
	ds_read_b128 v[174:177], v140
	ds_read_b128 v[178:181], v140 offset:1024
	ds_read_b128 v[194:197], v140 offset:2048
	ds_read_b128 v[198:201], v140 offset:3072
	ds_read_b128 v[202:205], v140 offset:4096
	ds_read_b128 v[206:209], v140 offset:5120
	ds_read_b128 v[210:213], v140 offset:6144
	ds_read_b128 v[214:217], v140 offset:7168
	global_load_lds_dwordx4 v141, s[82:83]
	s_add_i32 m0, s46, 0xe000
	s_nop 0
	global_load_lds_dwordx4 v182, s[82:83]
	s_waitcnt vmcnt(8) lgkmcnt(0)
	s_barrier
	s_setprio 1
	v_mfma_f32_16x16x32_bf16 v[124:127], v[142:145], v[174:177], v[124:127]
	v_mfma_f32_16x16x32_bf16 v[120:123], v[150:153], v[174:177], v[120:123]
	v_mfma_f32_16x16x32_bf16 v[116:119], v[142:145], v[194:197], v[116:119]
	v_mfma_f32_16x16x32_bf16 v[112:115], v[150:153], v[194:197], v[112:115]
	v_mfma_f32_16x16x32_bf16 v[108:111], v[142:145], v[202:205], v[108:111]
	v_mfma_f32_16x16x32_bf16 v[104:107], v[150:153], v[202:205], v[104:107]
	v_mfma_f32_16x16x32_bf16 v[100:103], v[142:145], v[210:213], v[100:103]
	v_mfma_f32_16x16x32_bf16 v[96:99], v[150:153], v[210:213], v[96:99]
	v_mfma_f32_16x16x32_bf16 v[124:127], v[146:149], v[178:181], v[124:127]
	v_mfma_f32_16x16x32_bf16 v[120:123], v[154:157], v[178:181], v[120:123]
	v_mfma_f32_16x16x32_bf16 v[116:119], v[146:149], v[198:201], v[116:119]
	v_mfma_f32_16x16x32_bf16 v[112:115], v[154:157], v[198:201], v[112:115]
	v_mfma_f32_16x16x32_bf16 v[108:111], v[146:149], v[206:209], v[108:111]
	v_mfma_f32_16x16x32_bf16 v[104:107], v[154:157], v[206:209], v[104:107]
	v_mfma_f32_16x16x32_bf16 v[100:103], v[146:149], v[214:217], v[100:103]
	v_mfma_f32_16x16x32_bf16 v[96:99], v[154:157], v[214:217], v[96:99]
	v_mfma_f32_16x16x32_bf16 v[92:95], v[158:161], v[174:177], v[92:95]
	v_mfma_f32_16x16x32_bf16 v[88:91], v[166:169], v[174:177], v[88:91]
	v_mfma_f32_16x16x32_bf16 v[84:87], v[158:161], v[194:197], v[84:87]
	v_mfma_f32_16x16x32_bf16 v[80:83], v[166:169], v[194:197], v[80:83]
	v_mfma_f32_16x16x32_bf16 v[76:79], v[158:161], v[202:205], v[76:79]
	v_mfma_f32_16x16x32_bf16 v[72:75], v[166:169], v[202:205], v[72:75]
	v_mfma_f32_16x16x32_bf16 v[68:71], v[158:161], v[210:213], v[68:71]
	v_mfma_f32_16x16x32_bf16 v[64:67], v[166:169], v[210:213], v[64:67]
	v_mfma_f32_16x16x32_bf16 v[92:95], v[162:165], v[178:181], v[92:95]
	v_mfma_f32_16x16x32_bf16 v[88:91], v[170:173], v[178:181], v[88:91]
	v_mfma_f32_16x16x32_bf16 v[84:87], v[162:165], v[198:201], v[84:87]
	v_mfma_f32_16x16x32_bf16 v[80:83], v[170:173], v[198:201], v[80:83]
	v_mfma_f32_16x16x32_bf16 v[76:79], v[162:165], v[206:209], v[76:79]
	v_mfma_f32_16x16x32_bf16 v[72:75], v[170:173], v[206:209], v[72:75]
	v_mfma_f32_16x16x32_bf16 v[68:71], v[162:165], v[214:217], v[68:71]
	v_mfma_f32_16x16x32_bf16 v[64:67], v[170:173], v[214:217], v[64:67]
	s_setprio 0
	s_barrier
	s_add_i32 s36, s40, s45
	s_mov_b32 m0, s36
	ds_read_b128 v[174:177], v140 offset:16384
	ds_read_b128 v[178:181], v140 offset:17408
	ds_read_b128 v[194:197], v140 offset:18432
	ds_read_b128 v[198:201], v140 offset:19456
	ds_read_b128 v[202:205], v140 offset:20480
	ds_read_b128 v[206:209], v140 offset:21504
	ds_read_b128 v[210:213], v140 offset:22528
	ds_read_b128 v[214:217], v140 offset:23552
	global_load_lds_dwordx4 v183, s[82:83]
	s_add_i32 m0, s36, 0x2000
	s_add_i32 s36, s80, s45
	global_load_lds_dwordx4 v184, s[82:83]
	s_mov_b32 m0, s36
	s_nop 0
	global_load_lds_dwordx4 v218, s[82:83]
	s_add_i32 m0, s36, 0x2000
	s_nop 0
	global_load_lds_dwordx4 v219, s[82:83]
	s_mov_b32 m0, s46
	s_nop 0
	global_load_lds_dwordx4 v220, s[82:83]
	s_mov_b32 m0, s56
	s_nop 0
	global_load_lds_dwordx4 v221, s[82:83]
	s_waitcnt vmcnt(8) lgkmcnt(0)
	s_barrier
; #define G_STAGE_A(bufoff, p0, p1, koff) do { \
;         __builtin_amdgcn_global_load_lds((const unsigned*)(gbase + (size_t)(unsigned)((p0) + (koff) + voffA[0])), (LAS unsigned*)(lds + (bufoff) + ldsw), 16, 0, 0); \
;         __builtin_amdgcn_global_load_lds((const unsigned*)(gbase + (size_t)(unsigned)((p1) + (koff) + voffA[1])), (LAS unsigned*)(lds + (bufoff) + ldsw + 8192), 16, 0, 0); } while (0)
; #define G_LDA(dst, b, h) do { _Pragma("unroll") for (int m = 0; m < 4; ++m) _Pragma("unroll") for (int k = 0; k < 2; ++k) dst[m][k] = *(const LAS bf16x8*)(lds + G_SA(b, h) + aoff + m * 2048 + k * 1024); } while (0)
; #define G_LDB(dst, b, h) do { _Pragma("unroll") for (int n = 0; n < 2; ++n) _Pragma("unroll") for (int k = 0; k < 2; ++k) dst[n][k] = *(const LAS bf16x8*)(lds + G_SB(b, h) + boff + n * 2048 + k * 1024); } while (0)
; #define G_MMA(ai, bj, At, Bt) do { __builtin_amdgcn_s_setprio(1); _Pragma("unroll") for (int m = 0; m < 4; ++m) _Pragma("unroll") for (int n = 0; n < 2; ++n) _Pragma("unroll") for (int k = 0; k < 2; ++k) \
;         acc[ai][bj][m][n] = __builtin_amdgcn_mfma_f32_16x16x32_bf16(Bt[n][k], At[m][k], acc[ai][bj][m][n], 0, 0, 0); __builtin_amdgcn_s_setprio(0); } while (0)
; #define G_WAIT_V(n) asm volatile("s_waitcnt vmcnt(" #n ")" ::: "memory")
; #define G_WAIT_L(n) asm volatile("s_waitcnt lgkmcnt(" #n ")" ::: "memory")
; #define G_BAR __builtin_amdgcn_s_barrier()
; #define G_SCHED __builtin_amdgcn_sched_barrier(0)
; template <class Epi>
; DI void gemm_phase(LAS unsigned char* lds, const Sched& S, const Epi& E, const int K) {
;     ...
;             G_WAIT_V(8); G_WAIT_L(0); G_BAR; G_MMA(1, 0, At, B0); G_MMA(1, 1, At, B1); G_BAR; G_SCHED;
;             G_LDB(B0, 1, 0); G_LDB(B1, 1, 1); G_SCHED; G_LDA(At, 1, 0); G_STAGE_A(G_SA(0, 1), x2, x3, k2);
;             G_WAIT_V(8); G_WAIT_L(0); G_BAR; G_MMA(0, 0, At, B0); G_MMA(0, 1, At, B1); G_BAR; G_SCHED;
	s_setprio 1
	v_mfma_f32_16x16x32_bf16 v[60:63], v[142:145], v[174:177], v[60:63]
	v_mfma_f32_16x16x32_bf16 v[56:59], v[150:153], v[174:177], v[56:59]
	v_mfma_f32_16x16x32_bf16 v[52:55], v[142:145], v[194:197], v[52:55]
	v_mfma_f32_16x16x32_bf16 v[48:51], v[150:153], v[194:197], v[48:51]
	v_mfma_f32_16x16x32_bf16 v[44:47], v[142:145], v[202:205], v[44:47]
	v_mfma_f32_16x16x32_bf16 v[40:43], v[150:153], v[202:205], v[40:43]
	v_mfma_f32_16x16x32_bf16 v[36:39], v[142:145], v[210:213], v[36:39]
	v_mfma_f32_16x16x32_bf16 v[32:35], v[150:153], v[210:213], v[32:35]
	v_mfma_f32_16x16x32_bf16 v[60:63], v[146:149], v[178:181], v[60:63]
	v_mfma_f32_16x16x32_bf16 v[56:59], v[154:157], v[178:181], v[56:59]
	v_mfma_f32_16x16x32_bf16 v[52:55], v[146:149], v[198:201], v[52:55]
	v_mfma_f32_16x16x32_bf16 v[48:51], v[154:157], v[198:201], v[48:51]
	v_mfma_f32_16x16x32_bf16 v[44:47], v[146:149], v[206:209], v[44:47]
	v_mfma_f32_16x16x32_bf16 v[40:43], v[154:157], v[206:209], v[40:43]
	v_mfma_f32_16x16x32_bf16 v[36:39], v[146:149], v[214:217], v[36:39]
	v_mfma_f32_16x16x32_bf16 v[32:35], v[154:157], v[214:217], v[32:35]
	v_mfma_f32_16x16x32_bf16 v[28:31], v[158:161], v[174:177], v[28:31]
	v_mfma_f32_16x16x32_bf16 v[24:27], v[166:169], v[174:177], v[24:27]
	v_mfma_f32_16x16x32_bf16 v[20:23], v[158:161], v[194:197], v[20:23]
	v_mfma_f32_16x16x32_bf16 v[16:19], v[166:169], v[194:197], v[16:19]
	v_mfma_f32_16x16x32_bf16 v[12:15], v[158:161], v[202:205], v[12:15]
	v_mfma_f32_16x16x32_bf16 v[8:11], v[166:169], v[202:205], v[8:11]
	v_mfma_f32_16x16x32_bf16 v[4:7], v[158:161], v[210:213], v[4:7]
	v_mfma_f32_16x16x32_bf16 v[0:3], v[166:169], v[210:213], v[0:3]
	v_mfma_f32_16x16x32_bf16 v[28:31], v[162:165], v[178:181], v[28:31]
	v_mfma_f32_16x16x32_bf16 v[24:27], v[170:173], v[178:181], v[24:27]
	v_mfma_f32_16x16x32_bf16 v[20:23], v[162:165], v[198:201], v[20:23]
	v_mfma_f32_16x16x32_bf16 v[16:19], v[170:173], v[198:201], v[16:19]
	v_mfma_f32_16x16x32_bf16 v[12:15], v[162:165], v[206:209], v[12:15]
	v_mfma_f32_16x16x32_bf16 v[8:11], v[170:173], v[206:209], v[8:11]
	v_mfma_f32_16x16x32_bf16 v[4:7], v[162:165], v[214:217], v[4:7]
	v_mfma_f32_16x16x32_bf16 v[0:3], v[170:173], v[214:217], v[0:3]
	s_setprio 0
	s_barrier
	s_add_i32 s36, 0, 0x18000
	v_add_u32_e32 v141, s36, v133
	s_add_i32 s37, 0, 0x1c000
	ds_read_b128 v[142:145], v141
	ds_read_b128 v[146:149], v141 offset:1024
	ds_read_b128 v[150:153], v141 offset:2048
	ds_read_b128 v[154:157], v141 offset:3072
	v_add_u32_e32 v141, s37, v133
	ds_read_b128 v[158:161], v141
	ds_read_b128 v[162:165], v141 offset:1024
	ds_read_b128 v[166:169], v141 offset:2048
	ds_read_b128 v[170:173], v141 offset:3072
	s_mov_b32 m0, s57
	ds_read_b128 v[174:177], v140 offset:32768
	ds_read_b128 v[178:181], v140 offset:33792
	ds_read_b128 v[194:197], v140 offset:34816
	ds_read_b128 v[198:201], v140 offset:35840
	ds_read_b128 v[202:205], v140 offset:36864
	ds_read_b128 v[206:209], v140 offset:37888
	ds_read_b128 v[210:213], v140 offset:38912
	ds_read_b128 v[214:217], v140 offset:39936
	global_load_lds_dwordx4 v222, s[82:83]
	s_mov_b32 m0, s58
	s_nop 0
	global_load_lds_dwordx4 v223, s[82:83]
	s_waitcnt vmcnt(8) lgkmcnt(0)
	s_barrier
; #define G_STAGE_A(bufoff, p0, p1, koff) do { \
;         __builtin_amdgcn_global_load_lds((const unsigned*)(gbase + (size_t)(unsigned)((p0) + (koff) + voffA[0])), (LAS unsigned*)(lds + (bufoff) + ldsw), 16, 0, 0); \
;         __builtin_amdgcn_global_load_lds((const unsigned*)(gbase + (size_t)(unsigned)((p1) + (koff) + voffA[1])), (LAS unsigned*)(lds + (bufoff) + ldsw + 8192), 16, 0, 0); } while (0)
; #define G_STAGE_B(bufoff, p, koff) do { \
;         __builtin_amdgcn_global_load_lds((const unsigned*)(gbase + (size_t)(unsigned)((p) + (koff) + voffB[0])), (LAS unsigned*)(lds + (bufoff) + ldsw), 16, 0, 0); \
;         __builtin_amdgcn_global_load_lds((const unsigned*)(gbase + (size_t)(unsigned)((p) + (koff) + voffB[1])), (LAS unsigned*)(lds + (bufoff) + ldsw + 8192), 16, 0, 0); } while (0)
; #define G_LDA(dst, b, h) do { _Pragma("unroll") for (int m = 0; m < 4; ++m) _Pragma("unroll") for (int k = 0; k < 2; ++k) dst[m][k] = *(const LAS bf16x8*)(lds + G_SA(b, h) + aoff + m * 2048 + k * 1024); } while (0)
; #define G_MMA(ai, bj, At, Bt) do { __builtin_amdgcn_s_setprio(1); _Pragma("unroll") for (int m = 0; m < 4; ++m) _Pragma("unroll") for (int n = 0; n < 2; ++n) _Pragma("unroll") for (int k = 0; k < 2; ++k) \
;         acc[ai][bj][m][n] = __builtin_amdgcn_mfma_f32_16x16x32_bf16(Bt[n][k], At[m][k], acc[ai][bj][m][n], 0, 0, 0); __builtin_amdgcn_s_setprio(0); } while (0)
; #define G_WAIT_V(n) asm volatile("s_waitcnt vmcnt(" #n ")" ::: "memory")
; #define G_WAIT_L(n) asm volatile("s_waitcnt lgkmcnt(" #n ")" ::: "memory")
; #define G_BAR __builtin_amdgcn_s_barrier()
; #define G_SCHED __builtin_amdgcn_sched_barrier(0)
; template <class Epi>
; DI void gemm_phase(LAS unsigned char* lds, const Sched& S, const Epi& E, const int K) {
;     ...
;             G_WAIT_V(8); G_WAIT_L(0); G_BAR; G_MMA(0, 0, At, B0); G_MMA(0, 1, At, B1); G_BAR; G_SCHED;
;             G_LDA(At, 1, 1); G_STAGE_B(G_SB(1, 0), xb, kb3); G_STAGE_B(G_SB(1, 1), xb + hstepB, kb3); G_STAGE_A(G_SA(1, 0), x0, x1, k3);
;             G_WAIT_V(8); G_WAIT_L(0); G_BAR; G_MMA(1, 0, At, B0); G_MMA(1, 1, At, B1); G_BAR; G_SCHED;
	s_setprio 1
	v_mfma_f32_16x16x32_bf16 v[124:127], v[142:145], v[174:177], v[124:127]
	v_mfma_f32_16x16x32_bf16 v[120:123], v[150:153], v[174:177], v[120:123]
	v_mfma_f32_16x16x32_bf16 v[116:119], v[142:145], v[194:197], v[116:119]
	v_mfma_f32_16x16x32_bf16 v[112:115], v[150:153], v[194:197], v[112:115]
	v_mfma_f32_16x16x32_bf16 v[108:111], v[142:145], v[202:205], v[108:111]
	v_mfma_f32_16x16x32_bf16 v[104:107], v[150:153], v[202:205], v[104:107]
	v_mfma_f32_16x16x32_bf16 v[100:103], v[142:145], v[210:213], v[100:103]
	v_mfma_f32_16x16x32_bf16 v[96:99], v[150:153], v[210:213], v[96:99]
	v_mfma_f32_16x16x32_bf16 v[124:127], v[146:149], v[178:181], v[124:127]
	v_mfma_f32_16x16x32_bf16 v[120:123], v[154:157], v[178:181], v[120:123]
	v_mfma_f32_16x16x32_bf16 v[116:119], v[146:149], v[198:201], v[116:119]
	v_mfma_f32_16x16x32_bf16 v[112:115], v[154:157], v[198:201], v[112:115]
	v_mfma_f32_16x16x32_bf16 v[108:111], v[146:149], v[206:209], v[108:111]
	v_mfma_f32_16x16x32_bf16 v[104:107], v[154:157], v[206:209], v[104:107]
	v_mfma_f32_16x16x32_bf16 v[100:103], v[146:149], v[214:217], v[100:103]
	v_mfma_f32_16x16x32_bf16 v[96:99], v[154:157], v[214:217], v[96:99]
	v_mfma_f32_16x16x32_bf16 v[92:95], v[158:161], v[174:177], v[92:95]
	v_mfma_f32_16x16x32_bf16 v[88:91], v[166:169], v[174:177], v[88:91]
	v_mfma_f32_16x16x32_bf16 v[84:87], v[158:161], v[194:197], v[84:87]
	v_mfma_f32_16x16x32_bf16 v[80:83], v[166:169], v[194:197], v[80:83]
	v_mfma_f32_16x16x32_bf16 v[76:79], v[158:161], v[202:205], v[76:79]
	v_mfma_f32_16x16x32_bf16 v[72:75], v[166:169], v[202:205], v[72:75]
	v_mfma_f32_16x16x32_bf16 v[68:71], v[158:161], v[210:213], v[68:71]
	v_mfma_f32_16x16x32_bf16 v[64:67], v[166:169], v[210:213], v[64:67]
	v_mfma_f32_16x16x32_bf16 v[92:95], v[162:165], v[178:181], v[92:95]
	v_mfma_f32_16x16x32_bf16 v[88:91], v[170:173], v[178:181], v[88:91]
	v_mfma_f32_16x16x32_bf16 v[84:87], v[162:165], v[198:201], v[84:87]
	v_mfma_f32_16x16x32_bf16 v[80:83], v[170:173], v[198:201], v[80:83]
	v_mfma_f32_16x16x32_bf16 v[76:79], v[162:165], v[206:209], v[76:79]
	v_mfma_f32_16x16x32_bf16 v[72:75], v[170:173], v[206:209], v[72:75]
	v_mfma_f32_16x16x32_bf16 v[68:71], v[162:165], v[214:217], v[68:71]
	v_mfma_f32_16x16x32_bf16 v[64:67], v[170:173], v[214:217], v[64:67]
	s_setprio 0
	s_barrier
	s_add_i32 s36, s36, s45
	s_mov_b32 m0, s36
	ds_read_b128 v[174:177], v140 offset:49152
	ds_read_b128 v[178:181], v140 offset:50176
	ds_read_b128 v[194:197], v140 offset:51200
	ds_read_b128 v[198:201], v140 offset:52224
	ds_read_b128 v[202:205], v140 offset:53248
	ds_read_b128 v[206:209], v140 offset:54272
	ds_read_b128 v[210:213], v140 offset:55296
	ds_read_b128 v[214:217], v140 offset:56320
	global_load_lds_dwordx4 v224, s[82:83]
	s_add_i32 m0, s36, 0x2000
	s_add_i32 s36, s37, s45
	global_load_lds_dwordx4 v225, s[82:83]
	s_mov_b32 m0, s36
	s_nop 0
	global_load_lds_dwordx4 v226, s[82:83]
	s_add_i32 m0, s36, 0x2000
	s_nop 0
	global_load_lds_dwordx4 v229, s[82:83]
	s_mov_b32 m0, s59
	s_nop 0
	global_load_lds_dwordx4 v233, s[82:83]
	s_mov_b32 m0, s60
	s_nop 0
	global_load_lds_dwordx4 v234, s[82:83]
	s_waitcnt vmcnt(8) lgkmcnt(0)
	s_barrier
	s_setprio 1
	v_mfma_f32_16x16x32_bf16 v[60:63], v[142:145], v[174:177], v[60:63]
	v_mfma_f32_16x16x32_bf16 v[56:59], v[150:153], v[174:177], v[56:59]
	v_mfma_f32_16x16x32_bf16 v[52:55], v[142:145], v[194:197], v[52:55]
	v_mfma_f32_16x16x32_bf16 v[48:51], v[150:153], v[194:197], v[48:51]
	v_mfma_f32_16x16x32_bf16 v[44:47], v[142:145], v[202:205], v[44:47]
	v_mfma_f32_16x16x32_bf16 v[40:43], v[150:153], v[202:205], v[40:43]
	v_mfma_f32_16x16x32_bf16 v[36:39], v[142:145], v[210:213], v[36:39]
	v_mfma_f32_16x16x32_bf16 v[32:35], v[150:153], v[210:213], v[32:35]
	v_mfma_f32_16x16x32_bf16 v[60:63], v[146:149], v[178:181], v[60:63]
	v_mfma_f32_16x16x32_bf16 v[56:59], v[154:157], v[178:181], v[56:59]
	v_mfma_f32_16x16x32_bf16 v[52:55], v[146:149], v[198:201], v[52:55]
	v_mfma_f32_16x16x32_bf16 v[48:51], v[154:157], v[198:201], v[48:51]
	v_mfma_f32_16x16x32_bf16 v[44:47], v[146:149], v[206:209], v[44:47]
	v_mfma_f32_16x16x32_bf16 v[40:43], v[154:157], v[206:209], v[40:43]
	v_mfma_f32_16x16x32_bf16 v[36:39], v[146:149], v[214:217], v[36:39]
	v_mfma_f32_16x16x32_bf16 v[32:35], v[154:157], v[214:217], v[32:35]
	v_mfma_f32_16x16x32_bf16 v[28:31], v[158:161], v[174:177], v[28:31]
	v_mfma_f32_16x16x32_bf16 v[24:27], v[166:169], v[174:177], v[24:27]
	v_mfma_f32_16x16x32_bf16 v[20:23], v[158:161], v[194:197], v[20:23]
	v_mfma_f32_16x16x32_bf16 v[16:19], v[166:169], v[194:197], v[16:19]
	v_mfma_f32_16x16x32_bf16 v[12:15], v[158:161], v[202:205], v[12:15]
	v_mfma_f32_16x16x32_bf16 v[8:11], v[166:169], v[202:205], v[8:11]
	v_mfma_f32_16x16x32_bf16 v[4:7], v[158:161], v[210:213], v[4:7]
	v_mfma_f32_16x16x32_bf16 v[0:3], v[166:169], v[210:213], v[0:3]
	v_mfma_f32_16x16x32_bf16 v[28:31], v[162:165], v[178:181], v[28:31]
	v_mfma_f32_16x16x32_bf16 v[24:27], v[170:173], v[178:181], v[24:27]
	v_mfma_f32_16x16x32_bf16 v[20:23], v[162:165], v[198:201], v[20:23]
	v_mfma_f32_16x16x32_bf16 v[16:19], v[170:173], v[198:201], v[16:19]
	v_mfma_f32_16x16x32_bf16 v[12:15], v[162:165], v[206:209], v[12:15]
	v_mfma_f32_16x16x32_bf16 v[8:11], v[170:173], v[206:209], v[8:11]
	v_mfma_f32_16x16x32_bf16 v[4:7], v[162:165], v[214:217], v[4:7]
	v_mfma_f32_16x16x32_bf16 v[0:3], v[170:173], v[214:217], v[0:3]
	s_setprio 0
	s_barrier
	s_andn2_b64 vcc, exec, s[24:25]
	s_cbranch_vccnz .LBB0_320
	s_barrier

; #define G_STAGE_A(bufoff, p0, p1, koff) do { \
;         __builtin_amdgcn_global_load_lds((const unsigned*)(gbase + (size_t)(unsigned)((p0) + (koff) + voffA[0])), (LAS unsigned*)(lds + (bufoff) + ldsw), 16, 0, 0); \
;         __builtin_amdgcn_global_load_lds((const unsigned*)(gbase + (size_t)(unsigned)((p1) + (koff) + voffA[1])), (LAS unsigned*)(lds + (bufoff) + ldsw + 8192), 16, 0, 0); } while (0)
; #define G_STAGE_B(bufoff, p, koff) do { \
;         __builtin_amdgcn_global_load_lds((const unsigned*)(gbase + (size_t)(unsigned)((p) + (koff) + voffB[0])), (LAS unsigned*)(lds + (bufoff) + ldsw), 16, 0, 0); \
;         __builtin_amdgcn_global_load_lds((const unsigned*)(gbase + (size_t)(unsigned)((p) + (koff) + voffB[1])), (LAS unsigned*)(lds + (bufoff) + ldsw + 8192), 16, 0, 0); } while (0)
; #define G_LDA(dst, b, h) do { _Pragma("unroll") for (int m = 0; m < 4; ++m) _Pragma("unroll") for (int k = 0; k < 2; ++k) dst[m][k] = *(const LAS bf16x8*)(lds + G_SA(b, h) + aoff + m * 2048 + k * 1024); } while (0)
; #define G_LDB(dst, b, h) do { _Pragma("unroll") for (int n = 0; n < 2; ++n) _Pragma("unroll") for (int k = 0; k < 2; ++k) dst[n][k] = *(const LAS bf16x8*)(lds + G_SB(b, h) + boff + n * 2048 + k * 1024); } while (0)
; #define G_WAIT_V(n) asm volatile("s_waitcnt vmcnt(" #n ")" ::: "memory")
; #define G_WAIT_L(n) asm volatile("s_waitcnt lgkmcnt(" #n ")" ::: "memory")
; template <class Epi>
; DI void gemm_phase(LAS unsigned char* lds, const Sched& S, const Epi& E, const int K) {
;     ...
;             const unsigned k1 = (unsigned)(t + 1) * kstepA;
;             const unsigned k2 = last ? 0u : (unsigned)(t + 2) * kstepA, k3 = k2 + kstepA;
;             const unsigned kb2 = last ? 0u : (unsigned)(t + 2) * kstepB, kb3 = kb2 + kstepB;
;             const unsigned x0 = last ? n0 : cur.a0, x1 = last ? n1 : cur.a1, x2 = last ? n2 : cur.a2, x3 = last ? n3 : cur.a3;
;             const unsigned xb = last ? nB : cur.b;
;     ...
;             G_LDB(B0, 0, 0); G_LDB(B1, 0, 1); G_SCHED; G_LDA(At, 0, 0); G_STAGE_A(G_SA(1, 1), cur.a2, cur.a3, k1);
;             G_WAIT_V(8); G_WAIT_L(0); G_BAR; G_MMA(0, 0, At, B0); G_MMA(0, 1, At, B1); G_BAR; G_SCHED;
;             G_LDA(At, 0, 1); G_STAGE_B(G_SB(0, 0), xb, kb2); G_STAGE_B(G_SB(0, 1), xb + hstepB, kb2); G_STAGE_A(G_SA(0, 0), x0, x1, k2);
;             G_WAIT_V(8); G_WAIT_L(0); G_BAR; G_MMA(1, 0, At, B0); G_MMA(1, 1, At, B1); G_BAR; G_SCHED;
.LBB0_511:
	s_add_i32 s27, s26, 0x100
	s_cmp_eq_u32 s10, 28
	s_cselect_b32 s48, 0, s27
	s_cselect_b32 s72, s20, s45
	s_cselect_b32 s73, s24, s41
	s_cselect_b32 s75, s21, s44
	s_cselect_b32 s78, s11, s46
	s_cselect_b32 s37, s25, s40
	s_add_i32 s79, 0, 0x10000
	v_add_u32_e32 v130, s79, v148
	s_add_i32 s80, 0, 0x14000
	ds_read_b128 v[138:141], v130
	ds_read_b128 v[154:157], v130 offset:1024
	ds_read_b128 v[158:161], v130 offset:2048
	ds_read_b128 v[162:165], v130 offset:3072
	v_add_u32_e32 v130, s80, v148
	ds_read_b128 v[166:169], v130
	ds_read_b128 v[170:173], v130 offset:1024
	ds_read_b128 v[174:177], v130 offset:2048
	ds_read_b128 v[178:181], v130 offset:3072
	s_or_b32 s36, s48, 0x80
	v_add_u32_e32 v130, s26, v129
	s_add_i32 m0, s50, 0xc000
	ds_read_b128 v[194:197], v152
	ds_read_b128 v[198:201], v152 offset:1024
	ds_read_b128 v[202:205], v152 offset:2048
	ds_read_b128 v[206:209], v152 offset:3072
	ds_read_b128 v[210:213], v152 offset:4096
	ds_read_b128 v[214:217], v152 offset:5120
	ds_read_b128 v[218:221], v152 offset:6144
	ds_read_b128 v[222:225], v152 offset:7168
	global_load_lds_dwordx4 v130, s[82:83]
	v_add_u32_e32 v130, s26, v128
	s_add_i32 m0, s50, 0xe000
	s_nop 0
	global_load_lds_dwordx4 v130, s[82:83]
	s_waitcnt vmcnt(8) lgkmcnt(0)
	s_barrier
	s_setprio 1
	v_mfma_f32_16x16x32_bf16 v[124:127], v[138:141], v[194:197], v[124:127]
	v_mfma_f32_16x16x32_bf16 v[120:123], v[158:161], v[194:197], v[120:123]
	v_mfma_f32_16x16x32_bf16 v[116:119], v[138:141], v[202:205], v[116:119]
	v_mfma_f32_16x16x32_bf16 v[112:115], v[158:161], v[202:205], v[112:115]
	v_mfma_f32_16x16x32_bf16 v[108:111], v[138:141], v[210:213], v[108:111]
	v_mfma_f32_16x16x32_bf16 v[104:107], v[158:161], v[210:213], v[104:107]
	v_mfma_f32_16x16x32_bf16 v[100:103], v[138:141], v[218:221], v[100:103]
	v_mfma_f32_16x16x32_bf16 v[96:99], v[158:161], v[218:221], v[96:99]
	v_mfma_f32_16x16x32_bf16 v[124:127], v[154:157], v[198:201], v[124:127]
	v_mfma_f32_16x16x32_bf16 v[120:123], v[162:165], v[198:201], v[120:123]
	v_mfma_f32_16x16x32_bf16 v[116:119], v[154:157], v[206:209], v[116:119]
	v_mfma_f32_16x16x32_bf16 v[112:115], v[162:165], v[206:209], v[112:115]
	v_mfma_f32_16x16x32_bf16 v[108:111], v[154:157], v[214:217], v[108:111]
	v_mfma_f32_16x16x32_bf16 v[104:107], v[162:165], v[214:217], v[104:107]
	v_mfma_f32_16x16x32_bf16 v[100:103], v[154:157], v[222:225], v[100:103]
	v_mfma_f32_16x16x32_bf16 v[96:99], v[162:165], v[222:225], v[96:99]
	v_mfma_f32_16x16x32_bf16 v[92:95], v[166:169], v[194:197], v[92:95]
	v_mfma_f32_16x16x32_bf16 v[88:91], v[174:177], v[194:197], v[88:91]
	v_mfma_f32_16x16x32_bf16 v[84:87], v[166:169], v[202:205], v[84:87]
	v_mfma_f32_16x16x32_bf16 v[80:83], v[174:177], v[202:205], v[80:83]
	v_mfma_f32_16x16x32_bf16 v[76:79], v[166:169], v[210:213], v[76:79]
	v_mfma_f32_16x16x32_bf16 v[72:75], v[174:177], v[210:213], v[72:75]
	v_mfma_f32_16x16x32_bf16 v[68:71], v[166:169], v[218:221], v[68:71]
	v_mfma_f32_16x16x32_bf16 v[64:67], v[174:177], v[218:221], v[64:67]
	v_mfma_f32_16x16x32_bf16 v[92:95], v[170:173], v[198:201], v[92:95]
	v_mfma_f32_16x16x32_bf16 v[88:91], v[178:181], v[198:201], v[88:91]
	v_mfma_f32_16x16x32_bf16 v[84:87], v[170:173], v[206:209], v[84:87]
	v_mfma_f32_16x16x32_bf16 v[80:83], v[178:181], v[206:209], v[80:83]
	v_mfma_f32_16x16x32_bf16 v[76:79], v[170:173], v[214:217], v[76:79]
	v_mfma_f32_16x16x32_bf16 v[72:75], v[178:181], v[214:217], v[72:75]
	v_mfma_f32_16x16x32_bf16 v[68:71], v[170:173], v[222:225], v[68:71]
	v_mfma_f32_16x16x32_bf16 v[64:67], v[178:181], v[222:225], v[64:67]
	s_setprio 0
	s_barrier
	s_add_i32 s26, s48, s37
	s_add_i32 s79, s79, s47
	v_add_u32_e32 v130, s26, v144
	s_mov_b32 m0, s79
	ds_read_b128 v[194:197], v152 offset:16384
	ds_read_b128 v[198:201], v152 offset:17408
	ds_read_b128 v[202:205], v152 offset:18432
	ds_read_b128 v[206:209], v152 offset:19456
	ds_read_b128 v[210:213], v152 offset:20480
	ds_read_b128 v[214:217], v152 offset:21504
	ds_read_b128 v[218:221], v152 offset:22528
	ds_read_b128 v[222:225], v152 offset:23552
	global_load_lds_dwordx4 v130, s[82:83]
	v_add_u32_e32 v130, s26, v146
	s_add_i32 s26, s37, 0x80000
	s_add_i32 m0, s79, 0x2000
	s_add_i32 s79, s26, s48
	s_add_i32 s80, s80, s47
	global_load_lds_dwordx4 v130, s[82:83]
	v_add_u32_e32 v130, s79, v144
	s_mov_b32 m0, s80
	s_nop 0
	global_load_lds_dwordx4 v130, s[82:83]
	v_add_u32_e32 v130, s79, v146
	s_add_i32 m0, s80, 0x2000
	s_nop 0
	global_load_lds_dwordx4 v130, s[82:83]
	v_add_u32_e32 v130, s78, v133
	v_add_u32_e32 v131, s48, v130
	s_mov_b32 m0, s50
	s_nop 0
	global_load_lds_dwordx4 v131, s[82:83]
	v_add_u32_e32 v131, s72, v145
	v_add_u32_e32 v142, s48, v131
	s_mov_b32 m0, s54
	s_nop 0
	global_load_lds_dwordx4 v142, s[82:83]
	s_waitcnt vmcnt(8) lgkmcnt(0)
	s_barrier
; #define G_STAGE_A(bufoff, p0, p1, koff) do { \
;         __builtin_amdgcn_global_load_lds((const unsigned*)(gbase + (size_t)(unsigned)((p0) + (koff) + voffA[0])), (LAS unsigned*)(lds + (bufoff) + ldsw), 16, 0, 0); \
;         __builtin_amdgcn_global_load_lds((const unsigned*)(gbase + (size_t)(unsigned)((p1) + (koff) + voffA[1])), (LAS unsigned*)(lds + (bufoff) + ldsw + 8192), 16, 0, 0); } while (0)
; #define G_LDA(dst, b, h) do { _Pragma("unroll") for (int m = 0; m < 4; ++m) _Pragma("unroll") for (int k = 0; k < 2; ++k) dst[m][k] = *(const LAS bf16x8*)(lds + G_SA(b, h) + aoff + m * 2048 + k * 1024); } while (0)
; #define G_LDB(dst, b, h) do { _Pragma("unroll") for (int n = 0; n < 2; ++n) _Pragma("unroll") for (int k = 0; k < 2; ++k) dst[n][k] = *(const LAS bf16x8*)(lds + G_SB(b, h) + boff + n * 2048 + k * 1024); } while (0)
; #define G_MMA(ai, bj, At, Bt) do { __builtin_amdgcn_s_setprio(1); _Pragma("unroll") for (int m = 0; m < 4; ++m) _Pragma("unroll") for (int n = 0; n < 2; ++n) _Pragma("unroll") for (int k = 0; k < 2; ++k) \
;         acc[ai][bj][m][n] = __builtin_amdgcn_mfma_f32_16x16x32_bf16(Bt[n][k], At[m][k], acc[ai][bj][m][n], 0, 0, 0); __builtin_amdgcn_s_setprio(0); } while (0)
; #define G_WAIT_V(n) asm volatile("s_waitcnt vmcnt(" #n ")" ::: "memory")
; #define G_WAIT_L(n) asm volatile("s_waitcnt lgkmcnt(" #n ")" ::: "memory")
; #define G_BAR __builtin_amdgcn_s_barrier()
; #define G_SCHED __builtin_amdgcn_sched_barrier(0)
; template <class Epi>
; DI void gemm_phase(LAS unsigned char* lds, const Sched& S, const Epi& E, const int K) {
;     ...
;             G_WAIT_V(8); G_WAIT_L(0); G_BAR; G_MMA(1, 0, At, B0); G_MMA(1, 1, At, B1); G_BAR; G_SCHED;
;             G_LDB(B0, 1, 0); G_LDB(B1, 1, 1); G_SCHED; G_LDA(At, 1, 0); G_STAGE_A(G_SA(0, 1), x2, x3, k2);
;             G_WAIT_V(8); G_WAIT_L(0); G_BAR; G_MMA(0, 0, At, B0); G_MMA(0, 1, At, B1); G_BAR; G_SCHED;
	s_setprio 1
	v_mfma_f32_16x16x32_bf16 v[60:63], v[138:141], v[194:197], v[60:63]
	v_mfma_f32_16x16x32_bf16 v[56:59], v[158:161], v[194:197], v[56:59]
	v_mfma_f32_16x16x32_bf16 v[52:55], v[138:141], v[202:205], v[52:55]
	v_mfma_f32_16x16x32_bf16 v[48:51], v[158:161], v[202:205], v[48:51]
	v_mfma_f32_16x16x32_bf16 v[44:47], v[138:141], v[210:213], v[44:47]
	v_mfma_f32_16x16x32_bf16 v[40:43], v[158:161], v[210:213], v[40:43]
	v_mfma_f32_16x16x32_bf16 v[36:39], v[138:141], v[218:221], v[36:39]
	v_mfma_f32_16x16x32_bf16 v[32:35], v[158:161], v[218:221], v[32:35]
	v_mfma_f32_16x16x32_bf16 v[60:63], v[154:157], v[198:201], v[60:63]
	v_mfma_f32_16x16x32_bf16 v[56:59], v[162:165], v[198:201], v[56:59]
	v_mfma_f32_16x16x32_bf16 v[52:55], v[154:157], v[206:209], v[52:55]
	v_mfma_f32_16x16x32_bf16 v[48:51], v[162:165], v[206:209], v[48:51]
	v_mfma_f32_16x16x32_bf16 v[44:47], v[154:157], v[214:217], v[44:47]
	v_mfma_f32_16x16x32_bf16 v[40:43], v[162:165], v[214:217], v[40:43]
	v_mfma_f32_16x16x32_bf16 v[36:39], v[154:157], v[222:225], v[36:39]
	v_mfma_f32_16x16x32_bf16 v[32:35], v[162:165], v[222:225], v[32:35]
	v_mfma_f32_16x16x32_bf16 v[28:31], v[166:169], v[194:197], v[28:31]
	v_mfma_f32_16x16x32_bf16 v[24:27], v[174:177], v[194:197], v[24:27]
	v_mfma_f32_16x16x32_bf16 v[20:23], v[166:169], v[202:205], v[20:23]
	v_mfma_f32_16x16x32_bf16 v[16:19], v[174:177], v[202:205], v[16:19]
	v_mfma_f32_16x16x32_bf16 v[12:15], v[166:169], v[210:213], v[12:15]
	v_mfma_f32_16x16x32_bf16 v[8:11], v[174:177], v[210:213], v[8:11]
	v_mfma_f32_16x16x32_bf16 v[4:7], v[166:169], v[218:221], v[4:7]
	v_mfma_f32_16x16x32_bf16 v[0:3], v[174:177], v[218:221], v[0:3]
	v_mfma_f32_16x16x32_bf16 v[28:31], v[170:173], v[198:201], v[28:31]
	v_mfma_f32_16x16x32_bf16 v[24:27], v[178:181], v[198:201], v[24:27]
	v_mfma_f32_16x16x32_bf16 v[20:23], v[170:173], v[206:209], v[20:23]
	v_mfma_f32_16x16x32_bf16 v[16:19], v[178:181], v[206:209], v[16:19]
	v_mfma_f32_16x16x32_bf16 v[12:15], v[170:173], v[214:217], v[12:15]
	v_mfma_f32_16x16x32_bf16 v[8:11], v[178:181], v[214:217], v[8:11]
	v_mfma_f32_16x16x32_bf16 v[4:7], v[170:173], v[222:225], v[4:7]
	v_mfma_f32_16x16x32_bf16 v[0:3], v[178:181], v[222:225], v[0:3]
	s_setprio 0
	s_barrier
	s_add_i32 s72, 0, 0x18000
	v_add_u32_e32 v142, s72, v148
	s_add_i32 s78, 0, 0x1c000
	ds_read_b128 v[138:141], v142
	ds_read_b128 v[154:157], v142 offset:1024
	ds_read_b128 v[158:161], v142 offset:2048
	ds_read_b128 v[162:165], v142 offset:3072
	v_add_u32_e32 v142, s78, v148
	ds_read_b128 v[166:169], v142
	ds_read_b128 v[170:173], v142 offset:1024
	ds_read_b128 v[174:177], v142 offset:2048
	ds_read_b128 v[178:181], v142 offset:3072
	s_add_i32 s75, s75, s48
	s_mov_b32 m0, s55
	v_add_u32_e32 v142, s75, v133
	s_add_i32 s73, s73, s48
	ds_read_b128 v[194:197], v152 offset:32768
	ds_read_b128 v[198:201], v152 offset:33792
	ds_read_b128 v[202:205], v152 offset:34816
	ds_read_b128 v[206:209], v152 offset:35840
	ds_read_b128 v[210:213], v152 offset:36864
	ds_read_b128 v[214:217], v152 offset:37888
	ds_read_b128 v[218:221], v152 offset:38912
	ds_read_b128 v[222:225], v152 offset:39936
	global_load_lds_dwordx4 v142, s[82:83]
	v_add_u32_e32 v142, s73, v145
	s_mov_b32 m0, s56
	s_nop 0
	global_load_lds_dwordx4 v142, s[82:83]
	s_waitcnt vmcnt(8) lgkmcnt(0)
	s_barrier
	s_setprio 1
	v_mfma_f32_16x16x32_bf16 v[124:127], v[138:141], v[194:197], v[124:127]
	v_mfma_f32_16x16x32_bf16 v[120:123], v[158:161], v[194:197], v[120:123]
	v_mfma_f32_16x16x32_bf16 v[116:119], v[138:141], v[202:205], v[116:119]
	v_mfma_f32_16x16x32_bf16 v[112:115], v[158:161], v[202:205], v[112:115]
	v_mfma_f32_16x16x32_bf16 v[108:111], v[138:141], v[210:213], v[108:111]
	v_mfma_f32_16x16x32_bf16 v[104:107], v[158:161], v[210:213], v[104:107]
	v_mfma_f32_16x16x32_bf16 v[100:103], v[138:141], v[218:221], v[100:103]
	v_mfma_f32_16x16x32_bf16 v[96:99], v[158:161], v[218:221], v[96:99]
	v_mfma_f32_16x16x32_bf16 v[124:127], v[154:157], v[198:201], v[124:127]
	v_mfma_f32_16x16x32_bf16 v[120:123], v[162:165], v[198:201], v[120:123]
	v_mfma_f32_16x16x32_bf16 v[116:119], v[154:157], v[206:209], v[116:119]
	v_mfma_f32_16x16x32_bf16 v[112:115], v[162:165], v[206:209], v[112:115]
	v_mfma_f32_16x16x32_bf16 v[108:111], v[154:157], v[214:217], v[108:111]
	v_mfma_f32_16x16x32_bf16 v[104:107], v[162:165], v[214:217], v[104:107]
	v_mfma_f32_16x16x32_bf16 v[100:103], v[154:157], v[222:225], v[100:103]
	v_mfma_f32_16x16x32_bf16 v[96:99], v[162:165], v[222:225], v[96:99]
	v_mfma_f32_16x16x32_bf16 v[92:95], v[166:169], v[194:197], v[92:95]
	v_mfma_f32_16x16x32_bf16 v[88:91], v[174:177], v[194:197], v[88:91]
	v_mfma_f32_16x16x32_bf16 v[84:87], v[166:169], v[202:205], v[84:87]
	v_mfma_f32_16x16x32_bf16 v[80:83], v[174:177], v[202:205], v[80:83]
	v_mfma_f32_16x16x32_bf16 v[76:79], v[166:169], v[210:213], v[76:79]
	v_mfma_f32_16x16x32_bf16 v[72:75], v[174:177], v[210:213], v[72:75]
	v_mfma_f32_16x16x32_bf16 v[68:71], v[166:169], v[218:221], v[68:71]
	v_mfma_f32_16x16x32_bf16 v[64:67], v[174:177], v[218:221], v[64:67]
	v_mfma_f32_16x16x32_bf16 v[92:95], v[170:173], v[198:201], v[92:95]
	v_mfma_f32_16x16x32_bf16 v[88:91], v[178:181], v[198:201], v[88:91]
	v_mfma_f32_16x16x32_bf16 v[84:87], v[170:173], v[206:209], v[84:87]
	v_mfma_f32_16x16x32_bf16 v[80:83], v[178:181], v[206:209], v[80:83]
	v_mfma_f32_16x16x32_bf16 v[76:79], v[170:173], v[214:217], v[76:79]
	v_mfma_f32_16x16x32_bf16 v[72:75], v[178:181], v[214:217], v[72:75]
	v_mfma_f32_16x16x32_bf16 v[68:71], v[170:173], v[222:225], v[68:71]
	v_mfma_f32_16x16x32_bf16 v[64:67], v[178:181], v[222:225], v[64:67]
	s_setprio 0
	s_barrier
; #define G_STAGE_A(bufoff, p0, p1, koff) do { \
;         __builtin_amdgcn_global_load_lds((const unsigned*)(gbase + (size_t)(unsigned)((p0) + (koff) + voffA[0])), (LAS unsigned*)(lds + (bufoff) + ldsw), 16, 0, 0); \
;         __builtin_amdgcn_global_load_lds((const unsigned*)(gbase + (size_t)(unsigned)((p1) + (koff) + voffA[1])), (LAS unsigned*)(lds + (bufoff) + ldsw + 8192), 16, 0, 0); } while (0)
; #define G_STAGE_B(bufoff, p, koff) do { \
;         __builtin_amdgcn_global_load_lds((const unsigned*)(gbase + (size_t)(unsigned)((p) + (koff) + voffB[0])), (LAS unsigned*)(lds + (bufoff) + ldsw), 16, 0, 0); \
;         __builtin_amdgcn_global_load_lds((const unsigned*)(gbase + (size_t)(unsigned)((p) + (koff) + voffB[1])), (LAS unsigned*)(lds + (bufoff) + ldsw + 8192), 16, 0, 0); } while (0)
; #define G_LDA(dst, b, h) do { _Pragma("unroll") for (int m = 0; m < 4; ++m) _Pragma("unroll") for (int k = 0; k < 2; ++k) dst[m][k] = *(const LAS bf16x8*)(lds + G_SA(b, h) + aoff + m * 2048 + k * 1024); } while (0)
; #define G_MMA(ai, bj, At, Bt) do { __builtin_amdgcn_s_setprio(1); _Pragma("unroll") for (int m = 0; m < 4; ++m) _Pragma("unroll") for (int n = 0; n < 2; ++n) _Pragma("unroll") for (int k = 0; k < 2; ++k) \
;         acc[ai][bj][m][n] = __builtin_amdgcn_mfma_f32_16x16x32_bf16(Bt[n][k], At[m][k], acc[ai][bj][m][n], 0, 0, 0); __builtin_amdgcn_s_setprio(0); } while (0)
; #define G_WAIT_V(n) asm volatile("s_waitcnt vmcnt(" #n ")" ::: "memory")
; #define G_WAIT_L(n) asm volatile("s_waitcnt lgkmcnt(" #n ")" ::: "memory")
; #define G_BAR __builtin_amdgcn_s_barrier()
; #define G_SCHED __builtin_amdgcn_sched_barrier(0)
; template <class Epi>
; DI void gemm_phase(LAS unsigned char* lds, const Sched& S, const Epi& E, const int K) {
;     ...
;             G_LDA(At, 1, 1); G_STAGE_B(G_SB(1, 0), xb, kb3); G_STAGE_B(G_SB(1, 1), xb + hstepB, kb3); G_STAGE_A(G_SA(1, 0), x0, x1, k3);
;             G_WAIT_V(8); G_WAIT_L(0); G_BAR; G_MMA(1, 0, At, B0); G_MMA(1, 1, At, B1); G_BAR; G_SCHED;
	s_add_i32 s37, s36, s37
	s_add_i32 s48, s72, s47
	v_add_u32_e32 v142, s37, v144
	s_mov_b32 m0, s48
	ds_read_b128 v[194:197], v152 offset:49152
	ds_read_b128 v[198:201], v152 offset:50176
	ds_read_b128 v[202:205], v152 offset:51200
	ds_read_b128 v[206:209], v152 offset:52224
	ds_read_b128 v[210:213], v152 offset:53248
	ds_read_b128 v[214:217], v152 offset:54272
	ds_read_b128 v[218:221], v152 offset:55296
	ds_read_b128 v[222:225], v152 offset:56320
	global_load_lds_dwordx4 v142, s[82:83]
	v_add_u32_e32 v142, s37, v146
	s_add_i32 m0, s48, 0x2000
	s_add_i32 s26, s36, s26
	s_add_i32 s37, s78, s47
	global_load_lds_dwordx4 v142, s[82:83]
	v_add_u32_e32 v142, s26, v144
	s_mov_b32 m0, s37
	v_add_u32_e32 v130, s36, v130
	global_load_lds_dwordx4 v142, s[82:83]
	v_add_u32_e32 v142, s26, v146
	s_add_i32 m0, s37, 0x2000
	s_nop 0
	global_load_lds_dwordx4 v142, s[82:83]
	s_mov_b32 m0, s57
	s_nop 0
	global_load_lds_dwordx4 v130, s[82:83]
	v_add_u32_e32 v130, s36, v131
	s_mov_b32 m0, s58
	s_nop 0
	global_load_lds_dwordx4 v130, s[82:83]
	s_waitcnt vmcnt(8) lgkmcnt(0)
	s_barrier
	s_setprio 1
	v_mfma_f32_16x16x32_bf16 v[60:63], v[138:141], v[194:197], v[60:63]
	v_mfma_f32_16x16x32_bf16 v[56:59], v[158:161], v[194:197], v[56:59]
	v_mfma_f32_16x16x32_bf16 v[52:55], v[138:141], v[202:205], v[52:55]
	v_mfma_f32_16x16x32_bf16 v[48:51], v[158:161], v[202:205], v[48:51]
	v_mfma_f32_16x16x32_bf16 v[44:47], v[138:141], v[210:213], v[44:47]
	v_mfma_f32_16x16x32_bf16 v[40:43], v[158:161], v[210:213], v[40:43]
	v_mfma_f32_16x16x32_bf16 v[36:39], v[138:141], v[218:221], v[36:39]
	v_mfma_f32_16x16x32_bf16 v[32:35], v[158:161], v[218:221], v[32:35]
	v_mfma_f32_16x16x32_bf16 v[60:63], v[154:157], v[198:201], v[60:63]
	v_mfma_f32_16x16x32_bf16 v[56:59], v[162:165], v[198:201], v[56:59]
	v_mfma_f32_16x16x32_bf16 v[52:55], v[154:157], v[206:209], v[52:55]
	v_mfma_f32_16x16x32_bf16 v[48:51], v[162:165], v[206:209], v[48:51]
	v_mfma_f32_16x16x32_bf16 v[44:47], v[154:157], v[214:217], v[44:47]
	v_mfma_f32_16x16x32_bf16 v[40:43], v[162:165], v[214:217], v[40:43]
	v_mfma_f32_16x16x32_bf16 v[36:39], v[154:157], v[222:225], v[36:39]
	v_mfma_f32_16x16x32_bf16 v[32:35], v[162:165], v[222:225], v[32:35]
	v_mfma_f32_16x16x32_bf16 v[28:31], v[166:169], v[194:197], v[28:31]
	v_mfma_f32_16x16x32_bf16 v[24:27], v[174:177], v[194:197], v[24:27]
	v_mfma_f32_16x16x32_bf16 v[20:23], v[166:169], v[202:205], v[20:23]
	v_mfma_f32_16x16x32_bf16 v[16:19], v[174:177], v[202:205], v[16:19]
	v_mfma_f32_16x16x32_bf16 v[12:15], v[166:169], v[210:213], v[12:15]
	v_mfma_f32_16x16x32_bf16 v[8:11], v[174:177], v[210:213], v[8:11]
	v_mfma_f32_16x16x32_bf16 v[4:7], v[166:169], v[218:221], v[4:7]
	v_mfma_f32_16x16x32_bf16 v[0:3], v[174:177], v[218:221], v[0:3]
	v_mfma_f32_16x16x32_bf16 v[28:31], v[170:173], v[198:201], v[28:31]
	v_mfma_f32_16x16x32_bf16 v[24:27], v[178:181], v[198:201], v[24:27]
	v_mfma_f32_16x16x32_bf16 v[20:23], v[170:173], v[206:209], v[20:23]
	v_mfma_f32_16x16x32_bf16 v[16:19], v[178:181], v[206:209], v[16:19]
	v_mfma_f32_16x16x32_bf16 v[12:15], v[170:173], v[214:217], v[12:15]
	v_mfma_f32_16x16x32_bf16 v[8:11], v[178:181], v[214:217], v[8:11]
	v_mfma_f32_16x16x32_bf16 v[4:7], v[170:173], v[222:225], v[4:7]
	v_mfma_f32_16x16x32_bf16 v[0:3], v[178:181], v[222:225], v[0:3]
	s_setprio 0
	s_barrier
	s_add_i32 s10, s10, 2
	s_cmp_gt_u32 s10, 29
	s_mov_b32 s26, s27
	s_cbranch_scc0 .LBB0_511
	s_and_b64 vcc, exec, s[14:15]
	s_cbranch_vccz .LBB0_514
	s_barrier
